# load segments issue their LDS-DMA prefetch loads first and the LDS fragment reads after them (longer DMA flight time)
# speedup vs baseline: 1.0051x; 1.0020x over previous
; #define PG8_STAGE(bufoff, gbase, voff) do { _Pragma("unroll") for (int _i = 0; _i < 2; ++_i) \
;         __builtin_amdgcn_global_load_lds((const unsigned*)((const char*)(gbase) + (voff)[_i]), (PG8_LAS unsigned*)(lds + (bufoff) + ldsw + _i * 8192), 16, 0, 0); } while (0)
; #define PG8_LDA(dst, b, h) do { _Pragma("unroll") for (int m = 0; m < 4; ++m) _Pragma("unroll") for (int k = 0; k < 2; ++k) dst[m][k] = *(const PG8_LAS bf16x8*)(lds + PG8_SA(b, h) + aoff + m * 2048 + k * 1024); } while (0)
; template <class Epi, class Sched, bool ALIGN_EPI = false, bool SP2 = false>
; __device__ __forceinline__ void gemm_phase(PG8_LAS unsigned char* lds, const Gemm g, const Sched& S, const Epi& E) {
;     ...
;         const bool has_next = S.next(ui + 1, nxt);
;         const char* nA = has_next ? (const char*)g.A + (size_t)nxt.pm * tstep : cA; const char* nB = has_next ? (const char*)g.Bt + (size_t)nxt.pn * tstep : cB;
;         for (int t = 0; t < nt; t += 2) {
;             const bool last = (t == nt - 2);
;             const char* a1 = cA + (size_t)(t + 1) * kstep;
;             const char* a2 = last ? nA : cA + (size_t)(t + 2) * kstep; const char* b2 = last ? nB : cB + (size_t)(t + 2) * kstep;
;             const char* a3 = a2 + kstep; const char* b3 = b2 + kstep;
;             if (last && has_next) S.a_ready(nxt, ui + 1);
;             if constexpr (SP2) {
;             PG8_LDB(B0, 0, 0); PG8_LDB(B1, 0, 1); PG8_SCHED; PG8_LDA(At, 0, 0); PG8_STAGE(PG8_SA(1, 1), a1 + hstep, voffA);
;             PG8_WAIT_V(8); PG8_WAIT_L(0); PG8_BAR; PG8_MMA(0, 0, At, B0); PG8_MMA(0, 1, At, B1); PG8_BAR; PG8_SCHED;
;             PG8_LDA(At, 0, 1); PG8_STAGE(PG8_SB(0, 0), b2, voffB); PG8_STAGE(PG8_SB(0, 1), b2 + hstep, voffB); PG8_STAGE(PG8_SA(0, 0), a2, voffA);
;             PG8_WAIT_V(8); PG8_WAIT_L(0); PG8_BAR; PG8_MMA(1, 0, At, B0); PG8_MMA(1, 1, At, B1); PG8_BAR; PG8_SCHED;
;             PG8_LDB(B0, 1, 0); PG8_LDB(B1, 1, 1); PG8_SCHED; PG8_LDA(At, 1, 0); PG8_STAGE(PG8_SA(0, 1), a2 + hstep, voffA);
;             PG8_WAIT_V(8); PG8_WAIT_L(0); PG8_BAR; PG8_MMA(0, 0, At, B0); PG8_MMA(0, 1, At, B1); PG8_BAR; PG8_SCHED;
;             PG8_LDA(At, 1, 1); PG8_STAGE(PG8_SB(1, 0), b3, voffB); PG8_STAGE(PG8_SB(1, 1), b3 + hstep, voffB); PG8_STAGE(PG8_SA(1, 0), a3, voffA);
;             PG8_WAIT_V(8); PG8_WAIT_L(0); PG8_BAR; PG8_MMA(1, 0, At, B0); PG8_MMA(1, 1, At, B1); PG8_BAR; PG8_SCHED;
.LBB0_336:
	s_ashr_i32 s17, s16, 31
	s_lshl_b64 s[18:19], s[16:17], 19
	s_add_u32 s18, s36, s18
	s_addc_u32 s19, s37, s19
	s_and_b64 s[20:21], s[0:1], exec
	s_cselect_b32 s17, s19, s25
	s_cselect_b32 s50, s18, s24
	s_ashr_i32 s15, s14, 31
	s_lshl_b64 s[20:21], s[14:15], 19
	s_add_u32 s20, s34, s20
	s_addc_u32 s21, s35, s21
	s_and_b64 s[28:29], s[0:1], exec
	s_cselect_b32 s15, s21, s27
	s_cselect_b32 s51, s20, s26
	s_add_u32 s24, s24, 0x40080
	s_addc_u32 s25, s25, 0
	s_add_u32 s52, s26, 0x100
	s_addc_u32 s53, s27, 0
	s_mov_b32 s54, -2
	s_add_u32 s26, s24, 0xfffc0080
	s_addc_u32 s27, s25, -1
	s_cmp_eq_u32 s54, 12
	s_cselect_b32 s29, s17, s27
	s_cselect_b32 s28, s50, s26
	s_cselect_b32 s27, s15, s53
	s_cselect_b32 s26, s51, s52
	s_add_i32 m0, s23, 0xc000
	s_nop 0
	global_load_lds_dwordx4 v136, s[24:25]
	s_add_i32 m0, s23, 0xe000
	s_nop 0
	global_load_lds_dwordx4 v138, s[24:25]
	s_waitcnt vmcnt(8)
	s_waitcnt lgkmcnt(0)
	s_setprio 1
	s_barrier
	v_mfma_f32_16x16x32_bf16 v[124:127], v[152:155], v[184:187], 0
	v_mfma_f32_16x16x32_bf16 v[120:123], v[160:163], v[184:187], 0
	v_mfma_f32_16x16x32_bf16 v[108:111], v[152:155], v[192:195], 0
	v_mfma_f32_16x16x32_bf16 v[104:107], v[160:163], v[192:195], 0
	v_mfma_f32_16x16x32_bf16 v[92:95], v[152:155], v[200:203], 0
	v_mfma_f32_16x16x32_bf16 v[88:91], v[160:163], v[200:203], 0
	v_mfma_f32_16x16x32_bf16 v[76:79], v[152:155], v[208:211], 0
	v_mfma_f32_16x16x32_bf16 v[72:75], v[160:163], v[208:211], 0
	v_mfma_f32_16x16x32_bf16 v[124:127], v[156:159], v[188:191], v[124:127]
	v_mfma_f32_16x16x32_bf16 v[120:123], v[164:167], v[188:191], v[120:123]
	v_mfma_f32_16x16x32_bf16 v[108:111], v[156:159], v[196:199], v[108:111]
	v_mfma_f32_16x16x32_bf16 v[104:107], v[164:167], v[196:199], v[104:107]
	v_mfma_f32_16x16x32_bf16 v[92:95], v[156:159], v[204:207], v[92:95]
	v_mfma_f32_16x16x32_bf16 v[88:91], v[164:167], v[204:207], v[88:91]
	v_mfma_f32_16x16x32_bf16 v[76:79], v[156:159], v[212:215], v[76:79]
	v_mfma_f32_16x16x32_bf16 v[72:75], v[164:167], v[212:215], v[72:75]
	v_mfma_f32_16x16x32_bf16 v[116:119], v[168:171], v[184:187], 0
	v_mfma_f32_16x16x32_bf16 v[112:115], v[176:179], v[184:187], 0
	v_mfma_f32_16x16x32_bf16 v[100:103], v[168:171], v[192:195], 0
	v_mfma_f32_16x16x32_bf16 v[96:99], v[176:179], v[192:195], 0
	v_mfma_f32_16x16x32_bf16 v[84:87], v[168:171], v[200:203], 0
	v_mfma_f32_16x16x32_bf16 v[80:83], v[176:179], v[200:203], 0
	v_mfma_f32_16x16x32_bf16 v[68:71], v[168:171], v[208:211], 0
	v_mfma_f32_16x16x32_bf16 v[64:67], v[176:179], v[208:211], 0
	v_mfma_f32_16x16x32_bf16 v[116:119], v[172:175], v[188:191], v[116:119]
	v_mfma_f32_16x16x32_bf16 v[112:115], v[180:183], v[188:191], v[112:115]
	v_mfma_f32_16x16x32_bf16 v[100:103], v[172:175], v[196:199], v[100:103]
	v_mfma_f32_16x16x32_bf16 v[96:99], v[180:183], v[196:199], v[96:99]
	v_mfma_f32_16x16x32_bf16 v[84:87], v[172:175], v[204:207], v[84:87]
	v_mfma_f32_16x16x32_bf16 v[80:83], v[180:183], v[204:207], v[80:83]
	v_mfma_f32_16x16x32_bf16 v[68:71], v[172:175], v[212:215], v[68:71]
	v_mfma_f32_16x16x32_bf16 v[64:67], v[180:183], v[212:215], v[64:67]
	s_barrier
	s_setprio 0
	s_add_i32 s55, s44, s33
	v_lshl_add_u64 v[216:217], s[26:27], 0, v[132:133]
	s_mov_b32 m0, s55
	s_nop 0
	global_load_lds_dwordx4 v[216:217], off
	s_add_i32 m0, s55, 0x2000
	s_add_u32 s56, s26, 0x40000
	v_lshl_add_u64 v[218:219], s[26:27], 0, v[128:129]
	s_addc_u32 s57, s27, 0
	s_add_i32 s55, s45, s33
	global_load_lds_dwordx4 v[218:219], off
	s_mov_b32 m0, s55
	v_lshl_add_u64 v[222:223], s[28:29], 0, v[130:131]
	global_load_lds_dwordx4 v132, s[56:57]
	s_add_i32 m0, s55, 0x2000
	s_nop 0
	global_load_lds_dwordx4 v128, s[56:57]
	v_lshl_add_u64 v[220:221], s[28:29], 0, v[134:135]
	s_mov_b32 m0, s23
	s_nop 0
	global_load_lds_dwordx4 v[220:221], off
	s_mov_b32 m0, s39
	s_nop 0
	global_load_lds_dwordx4 v[222:223], off
	ds_read_b128 v[184:187], v150 offset:16384
	ds_read_b128 v[188:191], v150 offset:17408
	ds_read_b128 v[192:195], v150 offset:18432
	ds_read_b128 v[196:199], v150 offset:19456
	ds_read_b128 v[200:203], v150 offset:20480
	ds_read_b128 v[204:207], v150 offset:21504
	ds_read_b128 v[208:211], v150 offset:22528
	ds_read_b128 v[212:215], v150 offset:23552
	s_waitcnt vmcnt(8)
	s_waitcnt lgkmcnt(0)
	s_setprio 1
	s_barrier
	v_mfma_f32_16x16x32_bf16 v[60:63], v[152:155], v[184:187], 0
	v_mfma_f32_16x16x32_bf16 v[56:59], v[160:163], v[184:187], 0
	v_mfma_f32_16x16x32_bf16 v[44:47], v[152:155], v[192:195], 0
	v_mfma_f32_16x16x32_bf16 v[40:43], v[160:163], v[192:195], 0
	v_mfma_f32_16x16x32_bf16 v[28:31], v[152:155], v[200:203], 0
	v_mfma_f32_16x16x32_bf16 v[24:27], v[160:163], v[200:203], 0
	v_mfma_f32_16x16x32_bf16 v[12:15], v[152:155], v[208:211], 0
	v_mfma_f32_16x16x32_bf16 v[8:11], v[160:163], v[208:211], 0
	v_mfma_f32_16x16x32_bf16 v[60:63], v[156:159], v[188:191], v[60:63]
	v_mfma_f32_16x16x32_bf16 v[56:59], v[164:167], v[188:191], v[56:59]
	v_mfma_f32_16x16x32_bf16 v[44:47], v[156:159], v[196:199], v[44:47]
	v_mfma_f32_16x16x32_bf16 v[40:43], v[164:167], v[196:199], v[40:43]
	v_mfma_f32_16x16x32_bf16 v[28:31], v[156:159], v[204:207], v[28:31]
	v_mfma_f32_16x16x32_bf16 v[24:27], v[164:167], v[204:207], v[24:27]
	v_mfma_f32_16x16x32_bf16 v[12:15], v[156:159], v[212:215], v[12:15]
	v_mfma_f32_16x16x32_bf16 v[8:11], v[164:167], v[212:215], v[8:11]
	v_mfma_f32_16x16x32_bf16 v[52:55], v[168:171], v[184:187], 0
	v_mfma_f32_16x16x32_bf16 v[48:51], v[176:179], v[184:187], 0
	v_mfma_f32_16x16x32_bf16 v[36:39], v[168:171], v[192:195], 0
	v_mfma_f32_16x16x32_bf16 v[32:35], v[176:179], v[192:195], 0
	v_mfma_f32_16x16x32_bf16 v[20:23], v[168:171], v[200:203], 0
	v_mfma_f32_16x16x32_bf16 v[16:19], v[176:179], v[200:203], 0
	v_mfma_f32_16x16x32_bf16 v[4:7], v[168:171], v[208:211], 0
	v_mfma_f32_16x16x32_bf16 v[0:3], v[176:179], v[208:211], 0
	v_mfma_f32_16x16x32_bf16 v[52:55], v[172:175], v[188:191], v[52:55]
	v_mfma_f32_16x16x32_bf16 v[48:51], v[180:183], v[188:191], v[48:51]
	v_mfma_f32_16x16x32_bf16 v[36:39], v[172:175], v[196:199], v[36:39]
	v_mfma_f32_16x16x32_bf16 v[32:35], v[180:183], v[196:199], v[32:35]
	v_mfma_f32_16x16x32_bf16 v[20:23], v[172:175], v[204:207], v[20:23]
	v_mfma_f32_16x16x32_bf16 v[16:19], v[180:183], v[204:207], v[16:19]
	v_mfma_f32_16x16x32_bf16 v[4:7], v[172:175], v[212:215], v[4:7]
	v_mfma_f32_16x16x32_bf16 v[0:3], v[180:183], v[212:215], v[0:3]
	s_barrier
; #define PG8_STAGE(bufoff, gbase, voff) do { _Pragma("unroll") for (int _i = 0; _i < 2; ++_i) \
;         __builtin_amdgcn_global_load_lds((const unsigned*)((const char*)(gbase) + (voff)[_i]), (PG8_LAS unsigned*)(lds + (bufoff) + ldsw + _i * 8192), 16, 0, 0); } while (0)
; #define PG8_LDA(dst, b, h) do { _Pragma("unroll") for (int m = 0; m < 4; ++m) _Pragma("unroll") for (int k = 0; k < 2; ++k) dst[m][k] = *(const PG8_LAS bf16x8*)(lds + PG8_SA(b, h) + aoff + m * 2048 + k * 1024); } while (0)
; #define PG8_LDB(dst, b, h) do { _Pragma("unroll") for (int n = 0; n < 2; ++n) _Pragma("unroll") for (int k = 0; k < 2; ++k) dst[n][k] = *(const PG8_LAS bf16x8*)(lds + PG8_SB(b, h) + boff + n * 2048 + k * 1024); } while (0)
; #define PG8_MMA(ai, bj, At, Bt) do { __builtin_amdgcn_s_setprio(1); _Pragma("unroll") for (int m = 0; m < 4; ++m) _Pragma("unroll") for (int n = 0; n < 2; ++n) _Pragma("unroll") for (int k = 0; k < 2; ++k) \
;         acc[ai][bj][m][n] = __builtin_amdgcn_mfma_f32_16x16x32_bf16(Bt[n][k], At[m][k], acc[ai][bj][m][n], 0, 0, 0); __builtin_amdgcn_s_setprio(0); } while (0)
; #define PG8_WAIT_V(n) asm volatile("s_waitcnt vmcnt(" #n ")" ::: "memory")
; #define PG8_WAIT_L(n) asm volatile("s_waitcnt lgkmcnt(" #n ")" ::: "memory")
; #define PG8_BAR __builtin_amdgcn_s_barrier()
; #define PG8_SCHED __builtin_amdgcn_sched_barrier(0)
; template <class Epi, class Sched, bool ALIGN_EPI = false, bool SP2 = false>
; __device__ __forceinline__ void gemm_phase(PG8_LAS unsigned char* lds, const Gemm g, const Sched& S, const Epi& E) {
;     ...
;         for (int t = 0; t < nt; t += 2) {
;     ...
;             PG8_LDB(B0, 1, 0); PG8_LDB(B1, 1, 1); PG8_SCHED; PG8_LDA(At, 1, 0); PG8_STAGE(PG8_SA(0, 1), a2 + hstep, voffA);
;             PG8_WAIT_V(8); PG8_WAIT_L(0); PG8_BAR; PG8_MMA(0, 0, At, B0); PG8_MMA(0, 1, At, B1); PG8_BAR; PG8_SCHED;
;             PG8_LDA(At, 1, 1); PG8_STAGE(PG8_SB(1, 0), b3, voffB); PG8_STAGE(PG8_SB(1, 1), b3 + hstep, voffB); PG8_STAGE(PG8_SA(1, 0), a3, voffA);
;             PG8_WAIT_V(8); PG8_WAIT_L(0); PG8_BAR; PG8_MMA(1, 0, At, B0); PG8_MMA(1, 1, At, B1); PG8_BAR; PG8_SCHED;
	s_setprio 0
	s_add_i32 s55, 0, 0x18000
	v_add_u32_e32 v151, s55, v145
	s_add_i32 s56, 0, 0x1c000
	ds_read_b128 v[152:155], v151
	ds_read_b128 v[156:159], v151 offset:1024
	ds_read_b128 v[160:163], v151 offset:2048
	ds_read_b128 v[164:167], v151 offset:3072
	v_add_u32_e32 v151, s56, v145
	ds_read_b128 v[168:171], v151
	ds_read_b128 v[172:175], v151 offset:1024
	ds_read_b128 v[176:179], v151 offset:2048
	ds_read_b128 v[180:183], v151 offset:3072
	s_add_u32 s28, s28, 0x40000
	s_addc_u32 s29, s29, 0
	s_mov_b32 m0, s40
	ds_read_b128 v[184:187], v150 offset:32768
	ds_read_b128 v[188:191], v150 offset:33792
	ds_read_b128 v[192:195], v150 offset:34816
	ds_read_b128 v[196:199], v150 offset:35840
	ds_read_b128 v[200:203], v150 offset:36864
	ds_read_b128 v[204:207], v150 offset:37888
	ds_read_b128 v[208:211], v150 offset:38912
	ds_read_b128 v[212:215], v150 offset:39936
	global_load_lds_dwordx4 v134, s[28:29]
	s_mov_b32 m0, s41
	s_nop 0
	global_load_lds_dwordx4 v130, s[28:29]
	s_waitcnt vmcnt(8)
	s_waitcnt lgkmcnt(0)
	s_setprio 1
	s_barrier
	v_mfma_f32_16x16x32_bf16 v[124:127], v[152:155], v[184:187], v[124:127]
	v_mfma_f32_16x16x32_bf16 v[120:123], v[160:163], v[184:187], v[120:123]
	v_mfma_f32_16x16x32_bf16 v[108:111], v[152:155], v[192:195], v[108:111]
	v_mfma_f32_16x16x32_bf16 v[104:107], v[160:163], v[192:195], v[104:107]
	v_mfma_f32_16x16x32_bf16 v[92:95], v[152:155], v[200:203], v[92:95]
	v_mfma_f32_16x16x32_bf16 v[88:91], v[160:163], v[200:203], v[88:91]
	v_mfma_f32_16x16x32_bf16 v[76:79], v[152:155], v[208:211], v[76:79]
	v_mfma_f32_16x16x32_bf16 v[72:75], v[160:163], v[208:211], v[72:75]
	v_mfma_f32_16x16x32_bf16 v[124:127], v[156:159], v[188:191], v[124:127]
	v_mfma_f32_16x16x32_bf16 v[120:123], v[164:167], v[188:191], v[120:123]
	v_mfma_f32_16x16x32_bf16 v[108:111], v[156:159], v[196:199], v[108:111]
	v_mfma_f32_16x16x32_bf16 v[104:107], v[164:167], v[196:199], v[104:107]
	v_mfma_f32_16x16x32_bf16 v[92:95], v[156:159], v[204:207], v[92:95]
	v_mfma_f32_16x16x32_bf16 v[88:91], v[164:167], v[204:207], v[88:91]
	v_mfma_f32_16x16x32_bf16 v[76:79], v[156:159], v[212:215], v[76:79]
	v_mfma_f32_16x16x32_bf16 v[72:75], v[164:167], v[212:215], v[72:75]
	v_mfma_f32_16x16x32_bf16 v[116:119], v[168:171], v[184:187], v[116:119]
	v_mfma_f32_16x16x32_bf16 v[112:115], v[176:179], v[184:187], v[112:115]
	v_mfma_f32_16x16x32_bf16 v[100:103], v[168:171], v[192:195], v[100:103]
	v_mfma_f32_16x16x32_bf16 v[96:99], v[176:179], v[192:195], v[96:99]
	v_mfma_f32_16x16x32_bf16 v[84:87], v[168:171], v[200:203], v[84:87]
	v_mfma_f32_16x16x32_bf16 v[80:83], v[176:179], v[200:203], v[80:83]
	v_mfma_f32_16x16x32_bf16 v[68:71], v[168:171], v[208:211], v[68:71]
	v_mfma_f32_16x16x32_bf16 v[64:67], v[176:179], v[208:211], v[64:67]
	v_mfma_f32_16x16x32_bf16 v[116:119], v[172:175], v[188:191], v[116:119]
	v_mfma_f32_16x16x32_bf16 v[112:115], v[180:183], v[188:191], v[112:115]
	v_mfma_f32_16x16x32_bf16 v[100:103], v[172:175], v[196:199], v[100:103]
	v_mfma_f32_16x16x32_bf16 v[96:99], v[180:183], v[196:199], v[96:99]
	v_mfma_f32_16x16x32_bf16 v[84:87], v[172:175], v[204:207], v[84:87]
	v_mfma_f32_16x16x32_bf16 v[80:83], v[180:183], v[204:207], v[80:83]
	v_mfma_f32_16x16x32_bf16 v[68:71], v[172:175], v[212:215], v[68:71]
	v_mfma_f32_16x16x32_bf16 v[64:67], v[180:183], v[212:215], v[64:67]
	s_barrier
	s_setprio 0
	s_add_i32 s28, s55, s33
	v_lshl_add_u64 v[216:217], v[216:217], 0, s[8:9]
	s_mov_b32 m0, s28
	s_nop 0
	global_load_lds_dwordx4 v[216:217], off
	s_add_i32 m0, s28, 0x2000
	s_add_u32 s26, s26, 0x40080
	v_lshl_add_u64 v[216:217], v[218:219], 0, s[8:9]
	s_addc_u32 s27, s27, 0
	s_add_i32 s28, s56, s33
	global_load_lds_dwordx4 v[216:217], off
	s_mov_b32 m0, s28
	s_nop 0
	global_load_lds_dwordx4 v132, s[26:27]
	s_add_i32 m0, s28, 0x2000
	s_nop 0
	global_load_lds_dwordx4 v128, s[26:27]
	v_lshl_add_u64 v[216:217], v[220:221], 0, s[8:9]
	s_mov_b32 m0, s42
	s_nop 0
	global_load_lds_dwordx4 v[216:217], off
	v_lshl_add_u64 v[216:217], v[222:223], 0, s[8:9]
	s_mov_b32 m0, s43
	s_nop 0
	global_load_lds_dwordx4 v[216:217], off
	ds_read_b128 v[184:187], v150 offset:49152
	ds_read_b128 v[188:191], v150 offset:50176
	ds_read_b128 v[192:195], v150 offset:51200
	ds_read_b128 v[196:199], v150 offset:52224
	ds_read_b128 v[200:203], v150 offset:53248
	ds_read_b128 v[204:207], v150 offset:54272
	ds_read_b128 v[208:211], v150 offset:55296
	ds_read_b128 v[212:215], v150 offset:56320
	s_waitcnt vmcnt(8)
	s_waitcnt lgkmcnt(0)
	s_setprio 1
	s_barrier
	v_mfma_f32_16x16x32_bf16 v[60:63], v[152:155], v[184:187], v[60:63]
	v_mfma_f32_16x16x32_bf16 v[56:59], v[160:163], v[184:187], v[56:59]
	v_mfma_f32_16x16x32_bf16 v[44:47], v[152:155], v[192:195], v[44:47]
	v_mfma_f32_16x16x32_bf16 v[40:43], v[160:163], v[192:195], v[40:43]
	v_mfma_f32_16x16x32_bf16 v[28:31], v[152:155], v[200:203], v[28:31]
	v_mfma_f32_16x16x32_bf16 v[24:27], v[160:163], v[200:203], v[24:27]
	v_mfma_f32_16x16x32_bf16 v[12:15], v[152:155], v[208:211], v[12:15]
	v_mfma_f32_16x16x32_bf16 v[8:11], v[160:163], v[208:211], v[8:11]
	v_mfma_f32_16x16x32_bf16 v[60:63], v[156:159], v[188:191], v[60:63]
	v_mfma_f32_16x16x32_bf16 v[56:59], v[164:167], v[188:191], v[56:59]
	v_mfma_f32_16x16x32_bf16 v[44:47], v[156:159], v[196:199], v[44:47]
	v_mfma_f32_16x16x32_bf16 v[40:43], v[164:167], v[196:199], v[40:43]
	v_mfma_f32_16x16x32_bf16 v[28:31], v[156:159], v[204:207], v[28:31]
	v_mfma_f32_16x16x32_bf16 v[24:27], v[164:167], v[204:207], v[24:27]
	v_mfma_f32_16x16x32_bf16 v[12:15], v[156:159], v[212:215], v[12:15]
	v_mfma_f32_16x16x32_bf16 v[8:11], v[164:167], v[212:215], v[8:11]
	v_mfma_f32_16x16x32_bf16 v[52:55], v[168:171], v[184:187], v[52:55]
	v_mfma_f32_16x16x32_bf16 v[48:51], v[176:179], v[184:187], v[48:51]
	v_mfma_f32_16x16x32_bf16 v[36:39], v[168:171], v[192:195], v[36:39]
	v_mfma_f32_16x16x32_bf16 v[32:35], v[176:179], v[192:195], v[32:35]
	v_mfma_f32_16x16x32_bf16 v[20:23], v[168:171], v[200:203], v[20:23]
	v_mfma_f32_16x16x32_bf16 v[16:19], v[176:179], v[200:203], v[16:19]
	v_mfma_f32_16x16x32_bf16 v[4:7], v[168:171], v[208:211], v[4:7]
	v_mfma_f32_16x16x32_bf16 v[0:3], v[176:179], v[208:211], v[0:3]
	v_mfma_f32_16x16x32_bf16 v[52:55], v[172:175], v[188:191], v[52:55]
	v_mfma_f32_16x16x32_bf16 v[48:51], v[180:183], v[188:191], v[48:51]
	v_mfma_f32_16x16x32_bf16 v[36:39], v[172:175], v[196:199], v[36:39]
	v_mfma_f32_16x16x32_bf16 v[32:35], v[180:183], v[196:199], v[32:35]
	v_mfma_f32_16x16x32_bf16 v[20:23], v[172:175], v[204:207], v[20:23]
	v_mfma_f32_16x16x32_bf16 v[16:19], v[180:183], v[204:207], v[16:19]
	v_mfma_f32_16x16x32_bf16 v[4:7], v[172:175], v[212:215], v[4:7]
	v_mfma_f32_16x16x32_bf16 v[0:3], v[180:183], v[212:215], v[0:3]
	s_barrier
	s_setprio 0
	s_add_i32 s54, s54, 2
	s_add_u32 s24, s24, 0x100
	s_addc_u32 s25, s25, 0
	s_add_u32 s52, s52, 0x100
	s_addc_u32 s53, s53, 0
	s_cmp_gt_u32 s54, 13
; #define PG8_STAGE(bufoff, gbase, voff) do { _Pragma("unroll") for (int _i = 0; _i < 2; ++_i) \
;         __builtin_amdgcn_global_load_lds((const unsigned*)((const char*)(gbase) + (voff)[_i]), (PG8_LAS unsigned*)(lds + (bufoff) + ldsw + _i * 8192), 16, 0, 0); } while (0)
; #define PG8_LDA(dst, b, h) do { _Pragma("unroll") for (int m = 0; m < 4; ++m) _Pragma("unroll") for (int k = 0; k < 2; ++k) dst[m][k] = *(const PG8_LAS bf16x8*)(lds + PG8_SA(b, h) + aoff + m * 2048 + k * 1024); } while (0)
; #define PG8_LDB(dst, b, h) do { _Pragma("unroll") for (int n = 0; n < 2; ++n) _Pragma("unroll") for (int k = 0; k < 2; ++k) dst[n][k] = *(const PG8_LAS bf16x8*)(lds + PG8_SB(b, h) + boff + n * 2048 + k * 1024); } while (0)
; #define PG8_MMA(ai, bj, At, Bt) do { __builtin_amdgcn_s_setprio(1); _Pragma("unroll") for (int m = 0; m < 4; ++m) _Pragma("unroll") for (int n = 0; n < 2; ++n) _Pragma("unroll") for (int k = 0; k < 2; ++k) \
;         acc[ai][bj][m][n] = __builtin_amdgcn_mfma_f32_16x16x32_bf16(Bt[n][k], At[m][k], acc[ai][bj][m][n], 0, 0, 0); __builtin_amdgcn_s_setprio(0); } while (0)
; #define PG8_WAIT_V(n) asm volatile("s_waitcnt vmcnt(" #n ")" ::: "memory")
; #define PG8_WAIT_L(n) asm volatile("s_waitcnt lgkmcnt(" #n ")" ::: "memory")
; template <class Epi, class Sched, bool ALIGN_EPI = false, bool SP2 = false>
; __device__ __forceinline__ void gemm_phase(PG8_LAS unsigned char* lds, const Gemm g, const Sched& S, const Epi& E) {
;     ...
;             const bool last = (t == nt - 2);
;             const char* a1 = cA + (size_t)(t + 1) * kstep;
;             const char* a2 = last ? nA : cA + (size_t)(t + 2) * kstep; const char* b2 = last ? nB : cB + (size_t)(t + 2) * kstep;
;             const char* a3 = a2 + kstep; const char* b3 = b2 + kstep;
;             if (last && has_next) S.a_ready(nxt, ui + 1);
;             if constexpr (SP2) {
;             PG8_LDB(B0, 0, 0); PG8_LDB(B1, 0, 1); PG8_SCHED; PG8_LDA(At, 0, 0); PG8_STAGE(PG8_SA(1, 1), a1 + hstep, voffA);
;             PG8_WAIT_V(8); PG8_WAIT_L(0); PG8_BAR; PG8_MMA(0, 0, At, B0); PG8_MMA(0, 1, At, B1); PG8_BAR; PG8_SCHED;
;             PG8_LDA(At, 0, 1); PG8_STAGE(PG8_SB(0, 0), b2, voffB); PG8_STAGE(PG8_SB(0, 1), b2 + hstep, voffB); PG8_STAGE(PG8_SA(0, 0), a2, voffA);
;             PG8_WAIT_V(8); PG8_WAIT_L(0); PG8_BAR; PG8_MMA(1, 0, At, B0); PG8_MMA(1, 1, At, B1); PG8_BAR; PG8_SCHED;
.LBB0_337:
	s_add_u32 s26, s24, 0xfffc0080
	s_addc_u32 s27, s25, -1
	s_cmp_eq_u32 s54, 12
	s_cselect_b32 s29, s17, s27
	s_cselect_b32 s28, s50, s26
	s_cselect_b32 s27, s15, s53
	s_cselect_b32 s26, s51, s52
	s_add_i32 m0, s23, 0xc000
	s_nop 0
	global_load_lds_dwordx4 v136, s[24:25]
	s_add_i32 m0, s23, 0xe000
	s_nop 0
	global_load_lds_dwordx4 v138, s[24:25]
	ds_read_b128 v[152:155], v148
	ds_read_b128 v[156:159], v148 offset:1024
	ds_read_b128 v[160:163], v148 offset:2048
	ds_read_b128 v[164:167], v148 offset:3072
	ds_read_b128 v[168:171], v149
	ds_read_b128 v[172:175], v149 offset:1024
	ds_read_b128 v[176:179], v149 offset:2048
	ds_read_b128 v[180:183], v149 offset:3072
	ds_read_b128 v[184:187], v150
	ds_read_b128 v[188:191], v150 offset:1024
	ds_read_b128 v[192:195], v150 offset:2048
	ds_read_b128 v[196:199], v150 offset:3072
	ds_read_b128 v[200:203], v150 offset:4096
	ds_read_b128 v[204:207], v150 offset:5120
	ds_read_b128 v[208:211], v150 offset:6144
	ds_read_b128 v[212:215], v150 offset:7168
	s_waitcnt vmcnt(8)
	s_waitcnt lgkmcnt(0)
	s_setprio 1
	s_barrier
	v_mfma_f32_16x16x32_bf16 v[124:127], v[152:155], v[184:187], v[124:127]
	v_mfma_f32_16x16x32_bf16 v[120:123], v[160:163], v[184:187], v[120:123]
	v_mfma_f32_16x16x32_bf16 v[108:111], v[152:155], v[192:195], v[108:111]
	v_mfma_f32_16x16x32_bf16 v[104:107], v[160:163], v[192:195], v[104:107]
	v_mfma_f32_16x16x32_bf16 v[92:95], v[152:155], v[200:203], v[92:95]
	v_mfma_f32_16x16x32_bf16 v[88:91], v[160:163], v[200:203], v[88:91]
	v_mfma_f32_16x16x32_bf16 v[76:79], v[152:155], v[208:211], v[76:79]
	v_mfma_f32_16x16x32_bf16 v[72:75], v[160:163], v[208:211], v[72:75]
	v_mfma_f32_16x16x32_bf16 v[124:127], v[156:159], v[188:191], v[124:127]
	v_mfma_f32_16x16x32_bf16 v[120:123], v[164:167], v[188:191], v[120:123]
	v_mfma_f32_16x16x32_bf16 v[108:111], v[156:159], v[196:199], v[108:111]
	v_mfma_f32_16x16x32_bf16 v[104:107], v[164:167], v[196:199], v[104:107]
	v_mfma_f32_16x16x32_bf16 v[92:95], v[156:159], v[204:207], v[92:95]
	v_mfma_f32_16x16x32_bf16 v[88:91], v[164:167], v[204:207], v[88:91]
	v_mfma_f32_16x16x32_bf16 v[76:79], v[156:159], v[212:215], v[76:79]
	v_mfma_f32_16x16x32_bf16 v[72:75], v[164:167], v[212:215], v[72:75]
	v_mfma_f32_16x16x32_bf16 v[116:119], v[168:171], v[184:187], v[116:119]
	v_mfma_f32_16x16x32_bf16 v[112:115], v[176:179], v[184:187], v[112:115]
	v_mfma_f32_16x16x32_bf16 v[100:103], v[168:171], v[192:195], v[100:103]
	v_mfma_f32_16x16x32_bf16 v[96:99], v[176:179], v[192:195], v[96:99]
	v_mfma_f32_16x16x32_bf16 v[84:87], v[168:171], v[200:203], v[84:87]
	v_mfma_f32_16x16x32_bf16 v[80:83], v[176:179], v[200:203], v[80:83]
	v_mfma_f32_16x16x32_bf16 v[68:71], v[168:171], v[208:211], v[68:71]
	v_mfma_f32_16x16x32_bf16 v[64:67], v[176:179], v[208:211], v[64:67]
	v_mfma_f32_16x16x32_bf16 v[116:119], v[172:175], v[188:191], v[116:119]
	v_mfma_f32_16x16x32_bf16 v[112:115], v[180:183], v[188:191], v[112:115]
	v_mfma_f32_16x16x32_bf16 v[100:103], v[172:175], v[196:199], v[100:103]
	v_mfma_f32_16x16x32_bf16 v[96:99], v[180:183], v[196:199], v[96:99]
	v_mfma_f32_16x16x32_bf16 v[84:87], v[172:175], v[204:207], v[84:87]
	v_mfma_f32_16x16x32_bf16 v[80:83], v[180:183], v[204:207], v[80:83]
	v_mfma_f32_16x16x32_bf16 v[68:71], v[172:175], v[212:215], v[68:71]
	v_mfma_f32_16x16x32_bf16 v[64:67], v[180:183], v[212:215], v[64:67]
	s_barrier
	s_setprio 0
	s_add_i32 s55, s44, s33
	v_lshl_add_u64 v[216:217], s[26:27], 0, v[132:133]
	s_mov_b32 m0, s55
	s_nop 0
	global_load_lds_dwordx4 v[216:217], off
	s_add_i32 m0, s55, 0x2000
	s_add_u32 s56, s26, 0x40000
	v_lshl_add_u64 v[218:219], s[26:27], 0, v[128:129]
	s_addc_u32 s57, s27, 0
	s_add_i32 s55, s45, s33
	global_load_lds_dwordx4 v[218:219], off
	s_mov_b32 m0, s55
	v_lshl_add_u64 v[222:223], s[28:29], 0, v[130:131]
	global_load_lds_dwordx4 v132, s[56:57]
	s_add_i32 m0, s55, 0x2000
	s_nop 0
	global_load_lds_dwordx4 v128, s[56:57]
	v_lshl_add_u64 v[220:221], s[28:29], 0, v[134:135]
	s_mov_b32 m0, s23
	s_nop 0
	global_load_lds_dwordx4 v[220:221], off
	s_mov_b32 m0, s39
	s_nop 0
	global_load_lds_dwordx4 v[222:223], off
	ds_read_b128 v[184:187], v150 offset:16384
	ds_read_b128 v[188:191], v150 offset:17408
	ds_read_b128 v[192:195], v150 offset:18432
	ds_read_b128 v[196:199], v150 offset:19456
	ds_read_b128 v[200:203], v150 offset:20480
	ds_read_b128 v[204:207], v150 offset:21504
	ds_read_b128 v[208:211], v150 offset:22528
	ds_read_b128 v[212:215], v150 offset:23552
	s_waitcnt vmcnt(8)
	s_waitcnt lgkmcnt(0)
	s_setprio 1
	s_barrier
	v_mfma_f32_16x16x32_bf16 v[60:63], v[152:155], v[184:187], v[60:63]
	v_mfma_f32_16x16x32_bf16 v[56:59], v[160:163], v[184:187], v[56:59]
	v_mfma_f32_16x16x32_bf16 v[44:47], v[152:155], v[192:195], v[44:47]
	v_mfma_f32_16x16x32_bf16 v[40:43], v[160:163], v[192:195], v[40:43]
	v_mfma_f32_16x16x32_bf16 v[28:31], v[152:155], v[200:203], v[28:31]
	v_mfma_f32_16x16x32_bf16 v[24:27], v[160:163], v[200:203], v[24:27]
	v_mfma_f32_16x16x32_bf16 v[12:15], v[152:155], v[208:211], v[12:15]
	v_mfma_f32_16x16x32_bf16 v[8:11], v[160:163], v[208:211], v[8:11]
	v_mfma_f32_16x16x32_bf16 v[60:63], v[156:159], v[188:191], v[60:63]
	v_mfma_f32_16x16x32_bf16 v[56:59], v[164:167], v[188:191], v[56:59]
	v_mfma_f32_16x16x32_bf16 v[44:47], v[156:159], v[196:199], v[44:47]
	v_mfma_f32_16x16x32_bf16 v[40:43], v[164:167], v[196:199], v[40:43]
	v_mfma_f32_16x16x32_bf16 v[28:31], v[156:159], v[204:207], v[28:31]
	v_mfma_f32_16x16x32_bf16 v[24:27], v[164:167], v[204:207], v[24:27]
	v_mfma_f32_16x16x32_bf16 v[12:15], v[156:159], v[212:215], v[12:15]
	v_mfma_f32_16x16x32_bf16 v[8:11], v[164:167], v[212:215], v[8:11]
	v_mfma_f32_16x16x32_bf16 v[52:55], v[168:171], v[184:187], v[52:55]
	v_mfma_f32_16x16x32_bf16 v[48:51], v[176:179], v[184:187], v[48:51]
	v_mfma_f32_16x16x32_bf16 v[36:39], v[168:171], v[192:195], v[36:39]
	v_mfma_f32_16x16x32_bf16 v[32:35], v[176:179], v[192:195], v[32:35]
	v_mfma_f32_16x16x32_bf16 v[20:23], v[168:171], v[200:203], v[20:23]
	v_mfma_f32_16x16x32_bf16 v[16:19], v[176:179], v[200:203], v[16:19]
	v_mfma_f32_16x16x32_bf16 v[4:7], v[168:171], v[208:211], v[4:7]
	v_mfma_f32_16x16x32_bf16 v[0:3], v[176:179], v[208:211], v[0:3]
	v_mfma_f32_16x16x32_bf16 v[52:55], v[172:175], v[188:191], v[52:55]
	v_mfma_f32_16x16x32_bf16 v[48:51], v[180:183], v[188:191], v[48:51]
	v_mfma_f32_16x16x32_bf16 v[36:39], v[172:175], v[196:199], v[36:39]
	v_mfma_f32_16x16x32_bf16 v[32:35], v[180:183], v[196:199], v[32:35]
	v_mfma_f32_16x16x32_bf16 v[20:23], v[172:175], v[204:207], v[20:23]
	v_mfma_f32_16x16x32_bf16 v[16:19], v[180:183], v[204:207], v[16:19]
	v_mfma_f32_16x16x32_bf16 v[4:7], v[172:175], v[212:215], v[4:7]
	v_mfma_f32_16x16x32_bf16 v[0:3], v[180:183], v[212:215], v[0:3]
	s_barrier
; #define PG8_STAGE(bufoff, gbase, voff) do { _Pragma("unroll") for (int _i = 0; _i < 2; ++_i) \
;         __builtin_amdgcn_global_load_lds((const unsigned*)((const char*)(gbase) + (voff)[_i]), (PG8_LAS unsigned*)(lds + (bufoff) + ldsw + _i * 8192), 16, 0, 0); } while (0)
; #define PG8_LDA(dst, b, h) do { _Pragma("unroll") for (int m = 0; m < 4; ++m) _Pragma("unroll") for (int k = 0; k < 2; ++k) dst[m][k] = *(const PG8_LAS bf16x8*)(lds + PG8_SA(b, h) + aoff + m * 2048 + k * 1024); } while (0)
; #define PG8_LDB(dst, b, h) do { _Pragma("unroll") for (int n = 0; n < 2; ++n) _Pragma("unroll") for (int k = 0; k < 2; ++k) dst[n][k] = *(const PG8_LAS bf16x8*)(lds + PG8_SB(b, h) + boff + n * 2048 + k * 1024); } while (0)
; #define PG8_MMA(ai, bj, At, Bt) do { __builtin_amdgcn_s_setprio(1); _Pragma("unroll") for (int m = 0; m < 4; ++m) _Pragma("unroll") for (int n = 0; n < 2; ++n) _Pragma("unroll") for (int k = 0; k < 2; ++k) \
;         acc[ai][bj][m][n] = __builtin_amdgcn_mfma_f32_16x16x32_bf16(Bt[n][k], At[m][k], acc[ai][bj][m][n], 0, 0, 0); __builtin_amdgcn_s_setprio(0); } while (0)
; #define PG8_WAIT_V(n) asm volatile("s_waitcnt vmcnt(" #n ")" ::: "memory")
; #define PG8_WAIT_L(n) asm volatile("s_waitcnt lgkmcnt(" #n ")" ::: "memory")
; #define PG8_BAR __builtin_amdgcn_s_barrier()
; #define PG8_SCHED __builtin_amdgcn_sched_barrier(0)
; template <class Epi, class Sched, bool ALIGN_EPI = false, bool SP2 = false>
; __device__ __forceinline__ void gemm_phase(PG8_LAS unsigned char* lds, const Gemm g, const Sched& S, const Epi& E) {
;     ...
;         for (int t = 0; t < nt; t += 2) {
;     ...
;             PG8_LDB(B0, 1, 0); PG8_LDB(B1, 1, 1); PG8_SCHED; PG8_LDA(At, 1, 0); PG8_STAGE(PG8_SA(0, 1), a2 + hstep, voffA);
;             PG8_WAIT_V(8); PG8_WAIT_L(0); PG8_BAR; PG8_MMA(0, 0, At, B0); PG8_MMA(0, 1, At, B1); PG8_BAR; PG8_SCHED;
;             PG8_LDA(At, 1, 1); PG8_STAGE(PG8_SB(1, 0), b3, voffB); PG8_STAGE(PG8_SB(1, 1), b3 + hstep, voffB); PG8_STAGE(PG8_SA(1, 0), a3, voffA);
;             PG8_WAIT_V(8); PG8_WAIT_L(0); PG8_BAR; PG8_MMA(1, 0, At, B0); PG8_MMA(1, 1, At, B1); PG8_BAR; PG8_SCHED;
	s_setprio 0
	s_add_i32 s55, 0, 0x18000
	v_add_u32_e32 v151, s55, v145
	s_add_i32 s56, 0, 0x1c000
	ds_read_b128 v[152:155], v151
	ds_read_b128 v[156:159], v151 offset:1024
	ds_read_b128 v[160:163], v151 offset:2048
	ds_read_b128 v[164:167], v151 offset:3072
	v_add_u32_e32 v151, s56, v145
	ds_read_b128 v[168:171], v151
	ds_read_b128 v[172:175], v151 offset:1024
	ds_read_b128 v[176:179], v151 offset:2048
	ds_read_b128 v[180:183], v151 offset:3072
	s_add_u32 s28, s28, 0x40000
	s_addc_u32 s29, s29, 0
	s_mov_b32 m0, s40
	ds_read_b128 v[184:187], v150 offset:32768
	ds_read_b128 v[188:191], v150 offset:33792
	ds_read_b128 v[192:195], v150 offset:34816
	ds_read_b128 v[196:199], v150 offset:35840
	ds_read_b128 v[200:203], v150 offset:36864
	ds_read_b128 v[204:207], v150 offset:37888
	ds_read_b128 v[208:211], v150 offset:38912
	ds_read_b128 v[212:215], v150 offset:39936
	global_load_lds_dwordx4 v134, s[28:29]
	s_mov_b32 m0, s41
	s_nop 0
	global_load_lds_dwordx4 v130, s[28:29]
	s_waitcnt vmcnt(8)
	s_waitcnt lgkmcnt(0)
	s_setprio 1
	s_barrier
	v_mfma_f32_16x16x32_bf16 v[124:127], v[152:155], v[184:187], v[124:127]
	v_mfma_f32_16x16x32_bf16 v[120:123], v[160:163], v[184:187], v[120:123]
	v_mfma_f32_16x16x32_bf16 v[108:111], v[152:155], v[192:195], v[108:111]
	v_mfma_f32_16x16x32_bf16 v[104:107], v[160:163], v[192:195], v[104:107]
	v_mfma_f32_16x16x32_bf16 v[92:95], v[152:155], v[200:203], v[92:95]
	v_mfma_f32_16x16x32_bf16 v[88:91], v[160:163], v[200:203], v[88:91]
	v_mfma_f32_16x16x32_bf16 v[76:79], v[152:155], v[208:211], v[76:79]
	v_mfma_f32_16x16x32_bf16 v[72:75], v[160:163], v[208:211], v[72:75]
	v_mfma_f32_16x16x32_bf16 v[124:127], v[156:159], v[188:191], v[124:127]
	v_mfma_f32_16x16x32_bf16 v[120:123], v[164:167], v[188:191], v[120:123]
	v_mfma_f32_16x16x32_bf16 v[108:111], v[156:159], v[196:199], v[108:111]
	v_mfma_f32_16x16x32_bf16 v[104:107], v[164:167], v[196:199], v[104:107]
	v_mfma_f32_16x16x32_bf16 v[92:95], v[156:159], v[204:207], v[92:95]
	v_mfma_f32_16x16x32_bf16 v[88:91], v[164:167], v[204:207], v[88:91]
	v_mfma_f32_16x16x32_bf16 v[76:79], v[156:159], v[212:215], v[76:79]
	v_mfma_f32_16x16x32_bf16 v[72:75], v[164:167], v[212:215], v[72:75]
	v_mfma_f32_16x16x32_bf16 v[116:119], v[168:171], v[184:187], v[116:119]
	v_mfma_f32_16x16x32_bf16 v[112:115], v[176:179], v[184:187], v[112:115]
	v_mfma_f32_16x16x32_bf16 v[100:103], v[168:171], v[192:195], v[100:103]
	v_mfma_f32_16x16x32_bf16 v[96:99], v[176:179], v[192:195], v[96:99]
	v_mfma_f32_16x16x32_bf16 v[84:87], v[168:171], v[200:203], v[84:87]
	v_mfma_f32_16x16x32_bf16 v[80:83], v[176:179], v[200:203], v[80:83]
	v_mfma_f32_16x16x32_bf16 v[68:71], v[168:171], v[208:211], v[68:71]
	v_mfma_f32_16x16x32_bf16 v[64:67], v[176:179], v[208:211], v[64:67]
	v_mfma_f32_16x16x32_bf16 v[116:119], v[172:175], v[188:191], v[116:119]
	v_mfma_f32_16x16x32_bf16 v[112:115], v[180:183], v[188:191], v[112:115]
	v_mfma_f32_16x16x32_bf16 v[100:103], v[172:175], v[196:199], v[100:103]
	v_mfma_f32_16x16x32_bf16 v[96:99], v[180:183], v[196:199], v[96:99]
	v_mfma_f32_16x16x32_bf16 v[84:87], v[172:175], v[204:207], v[84:87]
	v_mfma_f32_16x16x32_bf16 v[80:83], v[180:183], v[204:207], v[80:83]
	v_mfma_f32_16x16x32_bf16 v[68:71], v[172:175], v[212:215], v[68:71]
	v_mfma_f32_16x16x32_bf16 v[64:67], v[180:183], v[212:215], v[64:67]
	s_barrier
	s_setprio 0
	s_add_i32 s28, s55, s33
	v_lshl_add_u64 v[216:217], v[216:217], 0, s[8:9]
	s_mov_b32 m0, s28
	s_nop 0
	global_load_lds_dwordx4 v[216:217], off
	s_add_i32 m0, s28, 0x2000
	s_add_u32 s26, s26, 0x40080
	v_lshl_add_u64 v[216:217], v[218:219], 0, s[8:9]
	s_addc_u32 s27, s27, 0
	s_add_i32 s28, s56, s33
	global_load_lds_dwordx4 v[216:217], off
	s_mov_b32 m0, s28
	s_nop 0
	global_load_lds_dwordx4 v132, s[26:27]
	s_add_i32 m0, s28, 0x2000
	s_nop 0
	global_load_lds_dwordx4 v128, s[26:27]
	v_lshl_add_u64 v[216:217], v[220:221], 0, s[8:9]
	s_mov_b32 m0, s42
	s_nop 0
	global_load_lds_dwordx4 v[216:217], off
	v_lshl_add_u64 v[216:217], v[222:223], 0, s[8:9]
	s_mov_b32 m0, s43
	s_nop 0
	global_load_lds_dwordx4 v[216:217], off
	ds_read_b128 v[184:187], v150 offset:49152
	ds_read_b128 v[188:191], v150 offset:50176
	ds_read_b128 v[192:195], v150 offset:51200
	ds_read_b128 v[196:199], v150 offset:52224
	ds_read_b128 v[200:203], v150 offset:53248
	ds_read_b128 v[204:207], v150 offset:54272
	ds_read_b128 v[208:211], v150 offset:55296
	ds_read_b128 v[212:215], v150 offset:56320
	s_waitcnt vmcnt(8)
	s_waitcnt lgkmcnt(0)
	s_setprio 1
	s_barrier
	v_mfma_f32_16x16x32_bf16 v[60:63], v[152:155], v[184:187], v[60:63]
	v_mfma_f32_16x16x32_bf16 v[56:59], v[160:163], v[184:187], v[56:59]
	v_mfma_f32_16x16x32_bf16 v[44:47], v[152:155], v[192:195], v[44:47]
	v_mfma_f32_16x16x32_bf16 v[40:43], v[160:163], v[192:195], v[40:43]
	v_mfma_f32_16x16x32_bf16 v[28:31], v[152:155], v[200:203], v[28:31]
	v_mfma_f32_16x16x32_bf16 v[24:27], v[160:163], v[200:203], v[24:27]
	v_mfma_f32_16x16x32_bf16 v[12:15], v[152:155], v[208:211], v[12:15]
	v_mfma_f32_16x16x32_bf16 v[8:11], v[160:163], v[208:211], v[8:11]
	v_mfma_f32_16x16x32_bf16 v[60:63], v[156:159], v[188:191], v[60:63]
	v_mfma_f32_16x16x32_bf16 v[56:59], v[164:167], v[188:191], v[56:59]
	v_mfma_f32_16x16x32_bf16 v[44:47], v[156:159], v[196:199], v[44:47]
	v_mfma_f32_16x16x32_bf16 v[40:43], v[164:167], v[196:199], v[40:43]
	v_mfma_f32_16x16x32_bf16 v[28:31], v[156:159], v[204:207], v[28:31]
	v_mfma_f32_16x16x32_bf16 v[24:27], v[164:167], v[204:207], v[24:27]
	v_mfma_f32_16x16x32_bf16 v[12:15], v[156:159], v[212:215], v[12:15]
	v_mfma_f32_16x16x32_bf16 v[8:11], v[164:167], v[212:215], v[8:11]
	v_mfma_f32_16x16x32_bf16 v[52:55], v[168:171], v[184:187], v[52:55]
	v_mfma_f32_16x16x32_bf16 v[48:51], v[176:179], v[184:187], v[48:51]
	v_mfma_f32_16x16x32_bf16 v[36:39], v[168:171], v[192:195], v[36:39]
	v_mfma_f32_16x16x32_bf16 v[32:35], v[176:179], v[192:195], v[32:35]
	v_mfma_f32_16x16x32_bf16 v[20:23], v[168:171], v[200:203], v[20:23]
	v_mfma_f32_16x16x32_bf16 v[16:19], v[176:179], v[200:203], v[16:19]
	v_mfma_f32_16x16x32_bf16 v[4:7], v[168:171], v[208:211], v[4:7]
	v_mfma_f32_16x16x32_bf16 v[0:3], v[176:179], v[208:211], v[0:3]
	v_mfma_f32_16x16x32_bf16 v[52:55], v[172:175], v[188:191], v[52:55]
	v_mfma_f32_16x16x32_bf16 v[48:51], v[180:183], v[188:191], v[48:51]
	v_mfma_f32_16x16x32_bf16 v[36:39], v[172:175], v[196:199], v[36:39]
	v_mfma_f32_16x16x32_bf16 v[32:35], v[180:183], v[196:199], v[32:35]
	v_mfma_f32_16x16x32_bf16 v[20:23], v[172:175], v[204:207], v[20:23]
	v_mfma_f32_16x16x32_bf16 v[16:19], v[180:183], v[204:207], v[16:19]
	v_mfma_f32_16x16x32_bf16 v[4:7], v[172:175], v[212:215], v[4:7]
	v_mfma_f32_16x16x32_bf16 v[0:3], v[180:183], v[212:215], v[0:3]
	s_barrier
	s_setprio 0
	s_add_i32 s54, s54, 2
	s_add_u32 s24, s24, 0x100
	s_addc_u32 s25, s25, 0
	s_add_u32 s52, s52, 0x100
	s_addc_u32 s53, s53, 0
	s_cmp_gt_u32 s54, 13
	s_cbranch_scc0 .LBB0_337
	s_and_b64 vcc, exec, s[12:13]
	s_cbranch_vccz .LBB0_340
	s_barrier

; #define PG8_STAGE(bufoff, gbase, voff) do { _Pragma("unroll") for (int _i = 0; _i < 2; ++_i) \
;         __builtin_amdgcn_global_load_lds((const unsigned*)((const char*)(gbase) + (voff)[_i]), (PG8_LAS unsigned*)(lds + (bufoff) + ldsw + _i * 8192), 16, 0, 0); } while (0)
; #define PG8_LDA(dst, b, h) do { _Pragma("unroll") for (int m = 0; m < 4; ++m) _Pragma("unroll") for (int k = 0; k < 2; ++k) dst[m][k] = *(const PG8_LAS bf16x8*)(lds + PG8_SA(b, h) + aoff + m * 2048 + k * 1024); } while (0)
; #define PG8_BAR __builtin_amdgcn_s_barrier()
; template <class Epi, class Sched, bool ALIGN_EPI = false, bool SP2 = false>
; __device__ __forceinline__ void gemm_phase(PG8_LAS unsigned char* lds, const Gemm g, const Sched& S, const Epi& E) {
;     ...
;         const char* nA = has_next ? (const char*)g.A + (size_t)nxt.pm * tstep : cA; const char* nB = has_next ? (const char*)g.Bt + (size_t)nxt.pn * tstep : cB;
;         for (int t = 0; t < nt; t += 2) {
;             const bool last = (t == nt - 2);
;             const char* a1 = cA + (size_t)(t + 1) * kstep;
;             const char* a2 = last ? nA : cA + (size_t)(t + 2) * kstep; const char* b2 = last ? nB : cB + (size_t)(t + 2) * kstep;
;             const char* a3 = a2 + kstep; const char* b3 = b2 + kstep;
;             if (last && has_next) S.a_ready(nxt, ui + 1);
;             if constexpr (SP2) {
;             PG8_LDB(B0, 0, 0); PG8_LDB(B1, 0, 1); PG8_SCHED; PG8_LDA(At, 0, 0); PG8_STAGE(PG8_SA(1, 1), a1 + hstep, voffA);
;             PG8_WAIT_V(8); PG8_WAIT_L(0); PG8_BAR; PG8_MMA(0, 0, At, B0); PG8_MMA(0, 1, At, B1); PG8_BAR; PG8_SCHED;
;             PG8_LDA(At, 0, 1); PG8_STAGE(PG8_SB(0, 0), b2, voffB); PG8_STAGE(PG8_SB(0, 1), b2 + hstep, voffB); PG8_STAGE(PG8_SA(0, 0), a2, voffA);
;             PG8_WAIT_V(8); PG8_WAIT_L(0); PG8_BAR; PG8_MMA(1, 0, At, B0); PG8_MMA(1, 1, At, B1); PG8_BAR; PG8_SCHED;
;             PG8_LDB(B0, 1, 0); PG8_LDB(B1, 1, 1); PG8_SCHED; PG8_LDA(At, 1, 0); PG8_STAGE(PG8_SA(0, 1), a2 + hstep, voffA);
;             PG8_WAIT_V(8); PG8_WAIT_L(0); PG8_BAR; PG8_MMA(0, 0, At, B0); PG8_MMA(0, 1, At, B1); PG8_BAR; PG8_SCHED;
;             PG8_LDA(At, 1, 1); PG8_STAGE(PG8_SB(1, 0), b3, voffB); PG8_STAGE(PG8_SB(1, 1), b3 + hstep, voffB); PG8_STAGE(PG8_SA(1, 0), a3, voffA);
;             PG8_WAIT_V(8); PG8_WAIT_L(0); PG8_BAR; PG8_MMA(1, 0, At, B0); PG8_MMA(1, 1, At, B1); PG8_BAR; PG8_SCHED;
.LBB0_417:
	s_add_u32 s24, s24, 0xb0080
	s_addc_u32 s25, s25, 0
	s_add_u32 s51, s26, 0x100
	s_addc_u32 s52, s27, 0
	s_mov_b32 s53, -2
	s_waitcnt lgkmcnt(0)
	s_add_u32 s26, s24, 0xfff50080
	s_addc_u32 s27, s25, -1
	s_cmp_eq_u32 s53, 40
	s_cselect_b32 s29, s7, s27
	s_cselect_b32 s28, s6, s26
	s_cselect_b32 s27, s23, s52
	s_cselect_b32 s26, s22, s51
	s_add_i32 m0, s35, 0xc000
	s_nop 0
	global_load_lds_dwordx4 v200, s[24:25]
	s_add_i32 m0, s35, 0xe000
	s_nop 0
	global_load_lds_dwordx4 v202, s[24:25]
	s_waitcnt vmcnt(8)
	s_waitcnt lgkmcnt(0)
	s_setprio 1
	s_barrier
	v_mfma_f32_16x16x32_bf16 v[132:135], v[120:123], v[160:163], 0
	v_mfma_f32_16x16x32_bf16 v[124:127], v[136:139], v[160:163], 0
	v_mfma_f32_16x16x32_bf16 v[108:111], v[120:123], v[168:171], 0
	v_mfma_f32_16x16x32_bf16 v[104:107], v[136:139], v[168:171], 0
	v_mfma_f32_16x16x32_bf16 v[92:95], v[120:123], v[176:179], 0
	v_mfma_f32_16x16x32_bf16 v[88:91], v[136:139], v[176:179], 0
	v_mfma_f32_16x16x32_bf16 v[76:79], v[120:123], v[184:187], 0
	v_mfma_f32_16x16x32_bf16 v[72:75], v[136:139], v[184:187], 0
	v_mfma_f32_16x16x32_bf16 v[132:135], v[128:131], v[164:167], v[132:135]
	v_mfma_f32_16x16x32_bf16 v[124:127], v[140:143], v[164:167], v[124:127]
	v_mfma_f32_16x16x32_bf16 v[108:111], v[128:131], v[172:175], v[108:111]
	v_mfma_f32_16x16x32_bf16 v[104:107], v[140:143], v[172:175], v[104:107]
	v_mfma_f32_16x16x32_bf16 v[92:95], v[128:131], v[180:183], v[92:95]
	v_mfma_f32_16x16x32_bf16 v[88:91], v[140:143], v[180:183], v[88:91]
	v_mfma_f32_16x16x32_bf16 v[76:79], v[128:131], v[188:191], v[76:79]
	v_mfma_f32_16x16x32_bf16 v[72:75], v[140:143], v[188:191], v[72:75]
	v_mfma_f32_16x16x32_bf16 v[116:119], v[144:147], v[160:163], 0
	v_mfma_f32_16x16x32_bf16 v[112:115], v[152:155], v[160:163], 0
	v_mfma_f32_16x16x32_bf16 v[100:103], v[144:147], v[168:171], 0
	v_mfma_f32_16x16x32_bf16 v[96:99], v[152:155], v[168:171], 0
	v_mfma_f32_16x16x32_bf16 v[84:87], v[144:147], v[176:179], 0
	v_mfma_f32_16x16x32_bf16 v[80:83], v[152:155], v[176:179], 0
	v_mfma_f32_16x16x32_bf16 v[68:71], v[144:147], v[184:187], 0
	v_mfma_f32_16x16x32_bf16 v[64:67], v[152:155], v[184:187], 0
	v_mfma_f32_16x16x32_bf16 v[116:119], v[148:151], v[164:167], v[116:119]
	v_mfma_f32_16x16x32_bf16 v[112:115], v[156:159], v[164:167], v[112:115]
	v_mfma_f32_16x16x32_bf16 v[100:103], v[148:151], v[172:175], v[100:103]
	v_mfma_f32_16x16x32_bf16 v[96:99], v[156:159], v[172:175], v[96:99]
	v_mfma_f32_16x16x32_bf16 v[84:87], v[148:151], v[180:183], v[84:87]
	v_mfma_f32_16x16x32_bf16 v[80:83], v[156:159], v[180:183], v[80:83]
	v_mfma_f32_16x16x32_bf16 v[68:71], v[148:151], v[188:191], v[68:71]
	v_mfma_f32_16x16x32_bf16 v[64:67], v[156:159], v[188:191], v[64:67]
	s_barrier
	s_setprio 0
	s_add_i32 s54, s45, s34
	v_lshl_add_u64 v[204:205], s[26:27], 0, v[194:195]
	s_mov_b32 m0, s54
	s_nop 0
	global_load_lds_dwordx4 v[204:205], off
	s_add_i32 m0, s54, 0x2000
	s_add_u32 s54, s26, 0xb0000
	v_lshl_add_u64 v[206:207], s[26:27], 0, v[198:199]
	s_addc_u32 s55, s27, 0
	s_add_i32 s56, s46, s34
	global_load_lds_dwordx4 v[206:207], off
	s_mov_b32 m0, s56
	v_lshl_add_u64 v[210:211], s[28:29], 0, v[196:197]
	global_load_lds_dwordx4 v194, s[54:55]
	s_add_i32 m0, s56, 0x2000
	s_nop 0
	global_load_lds_dwordx4 v198, s[54:55]
	v_lshl_add_u64 v[208:209], s[28:29], 0, v[192:193]
	s_mov_b32 m0, s35
	s_nop 0
	global_load_lds_dwordx4 v[208:209], off
	s_mov_b32 m0, s36
	s_nop 0
	global_load_lds_dwordx4 v[210:211], off
	ds_read_b128 v[160:163], v247 offset:16384
	ds_read_b128 v[164:167], v247 offset:17408
	ds_read_b128 v[168:171], v247 offset:18432
	ds_read_b128 v[172:175], v247 offset:19456
	ds_read_b128 v[176:179], v247 offset:20480
	ds_read_b128 v[180:183], v247 offset:21504
	ds_read_b128 v[184:187], v247 offset:22528
	ds_read_b128 v[188:191], v247 offset:23552
	s_waitcnt vmcnt(8)
	s_waitcnt lgkmcnt(0)
	s_setprio 1
	s_barrier
	v_mfma_f32_16x16x32_bf16 v[60:63], v[120:123], v[160:163], 0
	v_mfma_f32_16x16x32_bf16 v[56:59], v[136:139], v[160:163], 0
	v_mfma_f32_16x16x32_bf16 v[44:47], v[120:123], v[168:171], 0
	v_mfma_f32_16x16x32_bf16 v[40:43], v[136:139], v[168:171], 0
	v_mfma_f32_16x16x32_bf16 v[28:31], v[120:123], v[176:179], 0
	v_mfma_f32_16x16x32_bf16 v[24:27], v[136:139], v[176:179], 0
	v_mfma_f32_16x16x32_bf16 v[12:15], v[120:123], v[184:187], 0
	v_mfma_f32_16x16x32_bf16 v[8:11], v[136:139], v[184:187], 0
	v_mfma_f32_16x16x32_bf16 v[60:63], v[128:131], v[164:167], v[60:63]
	v_mfma_f32_16x16x32_bf16 v[56:59], v[140:143], v[164:167], v[56:59]
	v_mfma_f32_16x16x32_bf16 v[44:47], v[128:131], v[172:175], v[44:47]
	v_mfma_f32_16x16x32_bf16 v[40:43], v[140:143], v[172:175], v[40:43]
	v_mfma_f32_16x16x32_bf16 v[28:31], v[128:131], v[180:183], v[28:31]
	v_mfma_f32_16x16x32_bf16 v[24:27], v[140:143], v[180:183], v[24:27]
	v_mfma_f32_16x16x32_bf16 v[12:15], v[128:131], v[188:191], v[12:15]
	v_mfma_f32_16x16x32_bf16 v[8:11], v[140:143], v[188:191], v[8:11]
	v_mfma_f32_16x16x32_bf16 v[52:55], v[144:147], v[160:163], 0
	v_mfma_f32_16x16x32_bf16 v[48:51], v[152:155], v[160:163], 0
	v_mfma_f32_16x16x32_bf16 v[36:39], v[144:147], v[168:171], 0
	v_mfma_f32_16x16x32_bf16 v[32:35], v[152:155], v[168:171], 0
	v_mfma_f32_16x16x32_bf16 v[20:23], v[144:147], v[176:179], 0
	v_mfma_f32_16x16x32_bf16 v[16:19], v[152:155], v[176:179], 0
	v_mfma_f32_16x16x32_bf16 v[4:7], v[144:147], v[184:187], 0
	v_mfma_f32_16x16x32_bf16 v[0:3], v[152:155], v[184:187], 0
	v_mfma_f32_16x16x32_bf16 v[52:55], v[148:151], v[164:167], v[52:55]
	v_mfma_f32_16x16x32_bf16 v[48:51], v[156:159], v[164:167], v[48:51]
	v_mfma_f32_16x16x32_bf16 v[36:39], v[148:151], v[172:175], v[36:39]
	v_mfma_f32_16x16x32_bf16 v[32:35], v[156:159], v[172:175], v[32:35]
	v_mfma_f32_16x16x32_bf16 v[20:23], v[148:151], v[180:183], v[20:23]
	v_mfma_f32_16x16x32_bf16 v[16:19], v[156:159], v[180:183], v[16:19]
	v_mfma_f32_16x16x32_bf16 v[4:7], v[148:151], v[188:191], v[4:7]
	v_mfma_f32_16x16x32_bf16 v[0:3], v[156:159], v[188:191], v[0:3]
	s_barrier
; #define PG8_STAGE(bufoff, gbase, voff) do { _Pragma("unroll") for (int _i = 0; _i < 2; ++_i) \
;         __builtin_amdgcn_global_load_lds((const unsigned*)((const char*)(gbase) + (voff)[_i]), (PG8_LAS unsigned*)(lds + (bufoff) + ldsw + _i * 8192), 16, 0, 0); } while (0)
; #define PG8_LDA(dst, b, h) do { _Pragma("unroll") for (int m = 0; m < 4; ++m) _Pragma("unroll") for (int k = 0; k < 2; ++k) dst[m][k] = *(const PG8_LAS bf16x8*)(lds + PG8_SA(b, h) + aoff + m * 2048 + k * 1024); } while (0)
; #define PG8_LDB(dst, b, h) do { _Pragma("unroll") for (int n = 0; n < 2; ++n) _Pragma("unroll") for (int k = 0; k < 2; ++k) dst[n][k] = *(const PG8_LAS bf16x8*)(lds + PG8_SB(b, h) + boff + n * 2048 + k * 1024); } while (0)
; #define PG8_MMA(ai, bj, At, Bt) do { __builtin_amdgcn_s_setprio(1); _Pragma("unroll") for (int m = 0; m < 4; ++m) _Pragma("unroll") for (int n = 0; n < 2; ++n) _Pragma("unroll") for (int k = 0; k < 2; ++k) \
;         acc[ai][bj][m][n] = __builtin_amdgcn_mfma_f32_16x16x32_bf16(Bt[n][k], At[m][k], acc[ai][bj][m][n], 0, 0, 0); __builtin_amdgcn_s_setprio(0); } while (0)
; #define PG8_WAIT_V(n) asm volatile("s_waitcnt vmcnt(" #n ")" ::: "memory")
; #define PG8_WAIT_L(n) asm volatile("s_waitcnt lgkmcnt(" #n ")" ::: "memory")
; #define PG8_BAR __builtin_amdgcn_s_barrier()
; #define PG8_SCHED __builtin_amdgcn_sched_barrier(0)
; template <class Epi, class Sched, bool ALIGN_EPI = false, bool SP2 = false>
; __device__ __forceinline__ void gemm_phase(PG8_LAS unsigned char* lds, const Gemm g, const Sched& S, const Epi& E) {
;     ...
;         for (int t = 0; t < nt; t += 2) {
;     ...
;             PG8_LDB(B0, 1, 0); PG8_LDB(B1, 1, 1); PG8_SCHED; PG8_LDA(At, 1, 0); PG8_STAGE(PG8_SA(0, 1), a2 + hstep, voffA);
;             PG8_WAIT_V(8); PG8_WAIT_L(0); PG8_BAR; PG8_MMA(0, 0, At, B0); PG8_MMA(0, 1, At, B1); PG8_BAR; PG8_SCHED;
;             PG8_LDA(At, 1, 1); PG8_STAGE(PG8_SB(1, 0), b3, voffB); PG8_STAGE(PG8_SB(1, 1), b3 + hstep, voffB); PG8_STAGE(PG8_SA(1, 0), a3, voffA);
;             PG8_WAIT_V(8); PG8_WAIT_L(0); PG8_BAR; PG8_MMA(1, 0, At, B0); PG8_MMA(1, 1, At, B1); PG8_BAR; PG8_SCHED;
	s_setprio 0
	s_add_i32 s54, 0, 0x18000
	s_add_i32 s55, 0, 0x1c000
	v_add_u32_e32 v140, s54, v243
	v_add_u32_e32 v156, s55, v243
	ds_read_b128 v[120:123], v140
	ds_read_b128 v[128:131], v140 offset:1024
	ds_read_b128 v[136:139], v140 offset:2048
	ds_read_b128 v[140:143], v140 offset:3072
	ds_read_b128 v[144:147], v156
	ds_read_b128 v[148:151], v156 offset:1024
	ds_read_b128 v[152:155], v156 offset:2048
	ds_read_b128 v[156:159], v156 offset:3072
	s_add_u32 s28, s28, 0xb0000
	s_addc_u32 s29, s29, 0
	s_mov_b32 m0, s37
	ds_read_b128 v[160:163], v247 offset:32768
	ds_read_b128 v[164:167], v247 offset:33792
	ds_read_b128 v[168:171], v247 offset:34816
	ds_read_b128 v[172:175], v247 offset:35840
	ds_read_b128 v[176:179], v247 offset:36864
	ds_read_b128 v[180:183], v247 offset:37888
	ds_read_b128 v[184:187], v247 offset:38912
	ds_read_b128 v[188:191], v247 offset:39936
	global_load_lds_dwordx4 v192, s[28:29]
	s_mov_b32 m0, s38
	s_nop 0
	global_load_lds_dwordx4 v196, s[28:29]
	s_waitcnt vmcnt(8)
	s_waitcnt lgkmcnt(0)
	s_setprio 1
	s_barrier
	v_mfma_f32_16x16x32_bf16 v[132:135], v[120:123], v[160:163], v[132:135]
	v_mfma_f32_16x16x32_bf16 v[124:127], v[136:139], v[160:163], v[124:127]
	v_mfma_f32_16x16x32_bf16 v[108:111], v[120:123], v[168:171], v[108:111]
	v_mfma_f32_16x16x32_bf16 v[104:107], v[136:139], v[168:171], v[104:107]
	v_mfma_f32_16x16x32_bf16 v[92:95], v[120:123], v[176:179], v[92:95]
	v_mfma_f32_16x16x32_bf16 v[88:91], v[136:139], v[176:179], v[88:91]
	v_mfma_f32_16x16x32_bf16 v[76:79], v[120:123], v[184:187], v[76:79]
	v_mfma_f32_16x16x32_bf16 v[72:75], v[136:139], v[184:187], v[72:75]
	v_mfma_f32_16x16x32_bf16 v[132:135], v[128:131], v[164:167], v[132:135]
	v_mfma_f32_16x16x32_bf16 v[124:127], v[140:143], v[164:167], v[124:127]
	v_mfma_f32_16x16x32_bf16 v[108:111], v[128:131], v[172:175], v[108:111]
	v_mfma_f32_16x16x32_bf16 v[104:107], v[140:143], v[172:175], v[104:107]
	v_mfma_f32_16x16x32_bf16 v[92:95], v[128:131], v[180:183], v[92:95]
	v_mfma_f32_16x16x32_bf16 v[88:91], v[140:143], v[180:183], v[88:91]
	v_mfma_f32_16x16x32_bf16 v[76:79], v[128:131], v[188:191], v[76:79]
	v_mfma_f32_16x16x32_bf16 v[72:75], v[140:143], v[188:191], v[72:75]
	v_mfma_f32_16x16x32_bf16 v[116:119], v[144:147], v[160:163], v[116:119]
	v_mfma_f32_16x16x32_bf16 v[112:115], v[152:155], v[160:163], v[112:115]
	v_mfma_f32_16x16x32_bf16 v[100:103], v[144:147], v[168:171], v[100:103]
	v_mfma_f32_16x16x32_bf16 v[96:99], v[152:155], v[168:171], v[96:99]
	v_mfma_f32_16x16x32_bf16 v[84:87], v[144:147], v[176:179], v[84:87]
	v_mfma_f32_16x16x32_bf16 v[80:83], v[152:155], v[176:179], v[80:83]
	v_mfma_f32_16x16x32_bf16 v[68:71], v[144:147], v[184:187], v[68:71]
	v_mfma_f32_16x16x32_bf16 v[64:67], v[152:155], v[184:187], v[64:67]
	v_mfma_f32_16x16x32_bf16 v[116:119], v[148:151], v[164:167], v[116:119]
	v_mfma_f32_16x16x32_bf16 v[112:115], v[156:159], v[164:167], v[112:115]
	v_mfma_f32_16x16x32_bf16 v[100:103], v[148:151], v[172:175], v[100:103]
	v_mfma_f32_16x16x32_bf16 v[96:99], v[156:159], v[172:175], v[96:99]
	v_mfma_f32_16x16x32_bf16 v[84:87], v[148:151], v[180:183], v[84:87]
	v_mfma_f32_16x16x32_bf16 v[80:83], v[156:159], v[180:183], v[80:83]
	v_mfma_f32_16x16x32_bf16 v[68:71], v[148:151], v[188:191], v[68:71]
	v_mfma_f32_16x16x32_bf16 v[64:67], v[156:159], v[188:191], v[64:67]
	s_barrier
	s_setprio 0
	s_add_i32 s28, s54, s34
	v_lshl_add_u64 v[204:205], v[204:205], 0, s[18:19]
	s_mov_b32 m0, s28
	s_nop 0
	global_load_lds_dwordx4 v[204:205], off
	s_add_i32 m0, s28, 0x2000
	s_add_u32 s26, s26, 0xb0080
	v_lshl_add_u64 v[204:205], v[206:207], 0, s[18:19]
	s_addc_u32 s27, s27, 0
	s_add_i32 s28, s55, s34
	global_load_lds_dwordx4 v[204:205], off
	s_mov_b32 m0, s28
	s_nop 0
	global_load_lds_dwordx4 v194, s[26:27]
	s_add_i32 m0, s28, 0x2000
	s_nop 0
	global_load_lds_dwordx4 v198, s[26:27]
	v_lshl_add_u64 v[204:205], v[208:209], 0, s[18:19]
	s_mov_b32 m0, s40
	s_nop 0
	global_load_lds_dwordx4 v[204:205], off
	v_lshl_add_u64 v[204:205], v[210:211], 0, s[18:19]
	s_mov_b32 m0, s41
	s_nop 0
	global_load_lds_dwordx4 v[204:205], off
	ds_read_b128 v[160:163], v247 offset:49152
	ds_read_b128 v[164:167], v247 offset:50176
	ds_read_b128 v[168:171], v247 offset:51200
	ds_read_b128 v[172:175], v247 offset:52224
	ds_read_b128 v[176:179], v247 offset:53248
	ds_read_b128 v[180:183], v247 offset:54272
	ds_read_b128 v[184:187], v247 offset:55296
	ds_read_b128 v[188:191], v247 offset:56320
	s_waitcnt vmcnt(8)
	s_waitcnt lgkmcnt(0)
	s_setprio 1
	s_barrier
	v_mfma_f32_16x16x32_bf16 v[60:63], v[120:123], v[160:163], v[60:63]
	v_mfma_f32_16x16x32_bf16 v[56:59], v[136:139], v[160:163], v[56:59]
	v_mfma_f32_16x16x32_bf16 v[44:47], v[120:123], v[168:171], v[44:47]
	v_mfma_f32_16x16x32_bf16 v[40:43], v[136:139], v[168:171], v[40:43]
	v_mfma_f32_16x16x32_bf16 v[28:31], v[120:123], v[176:179], v[28:31]
	v_mfma_f32_16x16x32_bf16 v[24:27], v[136:139], v[176:179], v[24:27]
	v_mfma_f32_16x16x32_bf16 v[12:15], v[120:123], v[184:187], v[12:15]
	v_mfma_f32_16x16x32_bf16 v[8:11], v[136:139], v[184:187], v[8:11]
	v_mfma_f32_16x16x32_bf16 v[60:63], v[128:131], v[164:167], v[60:63]
	v_mfma_f32_16x16x32_bf16 v[56:59], v[140:143], v[164:167], v[56:59]
	v_mfma_f32_16x16x32_bf16 v[44:47], v[128:131], v[172:175], v[44:47]
	v_mfma_f32_16x16x32_bf16 v[40:43], v[140:143], v[172:175], v[40:43]
	v_mfma_f32_16x16x32_bf16 v[28:31], v[128:131], v[180:183], v[28:31]
	v_mfma_f32_16x16x32_bf16 v[24:27], v[140:143], v[180:183], v[24:27]
	v_mfma_f32_16x16x32_bf16 v[12:15], v[128:131], v[188:191], v[12:15]
	v_mfma_f32_16x16x32_bf16 v[8:11], v[140:143], v[188:191], v[8:11]
	v_mfma_f32_16x16x32_bf16 v[52:55], v[144:147], v[160:163], v[52:55]
	v_mfma_f32_16x16x32_bf16 v[48:51], v[152:155], v[160:163], v[48:51]
	v_mfma_f32_16x16x32_bf16 v[36:39], v[144:147], v[168:171], v[36:39]
	v_mfma_f32_16x16x32_bf16 v[32:35], v[152:155], v[168:171], v[32:35]
	v_mfma_f32_16x16x32_bf16 v[20:23], v[144:147], v[176:179], v[20:23]
	v_mfma_f32_16x16x32_bf16 v[16:19], v[152:155], v[176:179], v[16:19]
	v_mfma_f32_16x16x32_bf16 v[4:7], v[144:147], v[184:187], v[4:7]
	v_mfma_f32_16x16x32_bf16 v[0:3], v[152:155], v[184:187], v[0:3]
	v_mfma_f32_16x16x32_bf16 v[52:55], v[148:151], v[164:167], v[52:55]
	v_mfma_f32_16x16x32_bf16 v[48:51], v[156:159], v[164:167], v[48:51]
	v_mfma_f32_16x16x32_bf16 v[36:39], v[148:151], v[172:175], v[36:39]
	v_mfma_f32_16x16x32_bf16 v[32:35], v[156:159], v[172:175], v[32:35]
	v_mfma_f32_16x16x32_bf16 v[20:23], v[148:151], v[180:183], v[20:23]
	v_mfma_f32_16x16x32_bf16 v[16:19], v[156:159], v[180:183], v[16:19]
	v_mfma_f32_16x16x32_bf16 v[4:7], v[148:151], v[188:191], v[4:7]
	v_mfma_f32_16x16x32_bf16 v[0:3], v[156:159], v[188:191], v[0:3]
	s_barrier
	s_setprio 0
	s_add_i32 s53, s53, 2
	s_add_u32 s24, s24, 0x100
	s_addc_u32 s25, s25, 0
	s_add_u32 s51, s51, 0x100
	s_addc_u32 s52, s52, 0
	s_cmp_gt_u32 s53, 41
; #define PG8_STAGE(bufoff, gbase, voff) do { _Pragma("unroll") for (int _i = 0; _i < 2; ++_i) \
;         __builtin_amdgcn_global_load_lds((const unsigned*)((const char*)(gbase) + (voff)[_i]), (PG8_LAS unsigned*)(lds + (bufoff) + ldsw + _i * 8192), 16, 0, 0); } while (0)
; #define PG8_LDA(dst, b, h) do { _Pragma("unroll") for (int m = 0; m < 4; ++m) _Pragma("unroll") for (int k = 0; k < 2; ++k) dst[m][k] = *(const PG8_LAS bf16x8*)(lds + PG8_SA(b, h) + aoff + m * 2048 + k * 1024); } while (0)
; #define PG8_LDB(dst, b, h) do { _Pragma("unroll") for (int n = 0; n < 2; ++n) _Pragma("unroll") for (int k = 0; k < 2; ++k) dst[n][k] = *(const PG8_LAS bf16x8*)(lds + PG8_SB(b, h) + boff + n * 2048 + k * 1024); } while (0)
; #define PG8_MMA(ai, bj, At, Bt) do { __builtin_amdgcn_s_setprio(1); _Pragma("unroll") for (int m = 0; m < 4; ++m) _Pragma("unroll") for (int n = 0; n < 2; ++n) _Pragma("unroll") for (int k = 0; k < 2; ++k) \
;         acc[ai][bj][m][n] = __builtin_amdgcn_mfma_f32_16x16x32_bf16(Bt[n][k], At[m][k], acc[ai][bj][m][n], 0, 0, 0); __builtin_amdgcn_s_setprio(0); } while (0)
; #define PG8_WAIT_V(n) asm volatile("s_waitcnt vmcnt(" #n ")" ::: "memory")
; #define PG8_WAIT_L(n) asm volatile("s_waitcnt lgkmcnt(" #n ")" ::: "memory")
; template <class Epi, class Sched, bool ALIGN_EPI = false, bool SP2 = false>
; __device__ __forceinline__ void gemm_phase(PG8_LAS unsigned char* lds, const Gemm g, const Sched& S, const Epi& E) {
;     ...
;             const bool last = (t == nt - 2);
;             const char* a1 = cA + (size_t)(t + 1) * kstep;
;             const char* a2 = last ? nA : cA + (size_t)(t + 2) * kstep; const char* b2 = last ? nB : cB + (size_t)(t + 2) * kstep;
;             const char* a3 = a2 + kstep; const char* b3 = b2 + kstep;
;             if (last && has_next) S.a_ready(nxt, ui + 1);
;             if constexpr (SP2) {
;             PG8_LDB(B0, 0, 0); PG8_LDB(B1, 0, 1); PG8_SCHED; PG8_LDA(At, 0, 0); PG8_STAGE(PG8_SA(1, 1), a1 + hstep, voffA);
;             PG8_WAIT_V(8); PG8_WAIT_L(0); PG8_BAR; PG8_MMA(0, 0, At, B0); PG8_MMA(0, 1, At, B1); PG8_BAR; PG8_SCHED;
;             PG8_LDA(At, 0, 1); PG8_STAGE(PG8_SB(0, 0), b2, voffB); PG8_STAGE(PG8_SB(0, 1), b2 + hstep, voffB); PG8_STAGE(PG8_SA(0, 0), a2, voffA);
;             PG8_WAIT_V(8); PG8_WAIT_L(0); PG8_BAR; PG8_MMA(1, 0, At, B0); PG8_MMA(1, 1, At, B1); PG8_BAR; PG8_SCHED;
.LBB0_418:
	s_add_u32 s26, s24, 0xfff50080
	s_addc_u32 s27, s25, -1
	s_cmp_eq_u32 s53, 40
	s_cselect_b32 s29, s7, s27
	s_cselect_b32 s28, s6, s26
	s_cselect_b32 s27, s23, s52
	s_cselect_b32 s26, s22, s51
	s_add_i32 m0, s35, 0xc000
	s_nop 0
	global_load_lds_dwordx4 v200, s[24:25]
	s_add_i32 m0, s35, 0xe000
	s_nop 0
	global_load_lds_dwordx4 v202, s[24:25]
	ds_read_b128 v[120:123], v245
	ds_read_b128 v[128:131], v245 offset:1024
	ds_read_b128 v[136:139], v245 offset:2048
	ds_read_b128 v[140:143], v245 offset:3072
	ds_read_b128 v[144:147], v246
	ds_read_b128 v[148:151], v246 offset:1024
	ds_read_b128 v[152:155], v246 offset:2048
	ds_read_b128 v[156:159], v246 offset:3072
	ds_read_b128 v[160:163], v247
	ds_read_b128 v[164:167], v247 offset:1024
	ds_read_b128 v[168:171], v247 offset:2048
	ds_read_b128 v[172:175], v247 offset:3072
	ds_read_b128 v[176:179], v247 offset:4096
	ds_read_b128 v[180:183], v247 offset:5120
	ds_read_b128 v[184:187], v247 offset:6144
	ds_read_b128 v[188:191], v247 offset:7168
	s_waitcnt vmcnt(8)
	s_waitcnt lgkmcnt(0)
	s_setprio 1
	s_barrier
	v_mfma_f32_16x16x32_bf16 v[132:135], v[120:123], v[160:163], v[132:135]
	v_mfma_f32_16x16x32_bf16 v[124:127], v[136:139], v[160:163], v[124:127]
	v_mfma_f32_16x16x32_bf16 v[108:111], v[120:123], v[168:171], v[108:111]
	v_mfma_f32_16x16x32_bf16 v[104:107], v[136:139], v[168:171], v[104:107]
	v_mfma_f32_16x16x32_bf16 v[92:95], v[120:123], v[176:179], v[92:95]
	v_mfma_f32_16x16x32_bf16 v[88:91], v[136:139], v[176:179], v[88:91]
	v_mfma_f32_16x16x32_bf16 v[76:79], v[120:123], v[184:187], v[76:79]
	v_mfma_f32_16x16x32_bf16 v[72:75], v[136:139], v[184:187], v[72:75]
	v_mfma_f32_16x16x32_bf16 v[132:135], v[128:131], v[164:167], v[132:135]
	v_mfma_f32_16x16x32_bf16 v[124:127], v[140:143], v[164:167], v[124:127]
	v_mfma_f32_16x16x32_bf16 v[108:111], v[128:131], v[172:175], v[108:111]
	v_mfma_f32_16x16x32_bf16 v[104:107], v[140:143], v[172:175], v[104:107]
	v_mfma_f32_16x16x32_bf16 v[92:95], v[128:131], v[180:183], v[92:95]
	v_mfma_f32_16x16x32_bf16 v[88:91], v[140:143], v[180:183], v[88:91]
	v_mfma_f32_16x16x32_bf16 v[76:79], v[128:131], v[188:191], v[76:79]
	v_mfma_f32_16x16x32_bf16 v[72:75], v[140:143], v[188:191], v[72:75]
	v_mfma_f32_16x16x32_bf16 v[116:119], v[144:147], v[160:163], v[116:119]
	v_mfma_f32_16x16x32_bf16 v[112:115], v[152:155], v[160:163], v[112:115]
	v_mfma_f32_16x16x32_bf16 v[100:103], v[144:147], v[168:171], v[100:103]
	v_mfma_f32_16x16x32_bf16 v[96:99], v[152:155], v[168:171], v[96:99]
	v_mfma_f32_16x16x32_bf16 v[84:87], v[144:147], v[176:179], v[84:87]
	v_mfma_f32_16x16x32_bf16 v[80:83], v[152:155], v[176:179], v[80:83]
	v_mfma_f32_16x16x32_bf16 v[68:71], v[144:147], v[184:187], v[68:71]
	v_mfma_f32_16x16x32_bf16 v[64:67], v[152:155], v[184:187], v[64:67]
	v_mfma_f32_16x16x32_bf16 v[116:119], v[148:151], v[164:167], v[116:119]
	v_mfma_f32_16x16x32_bf16 v[112:115], v[156:159], v[164:167], v[112:115]
	v_mfma_f32_16x16x32_bf16 v[100:103], v[148:151], v[172:175], v[100:103]
	v_mfma_f32_16x16x32_bf16 v[96:99], v[156:159], v[172:175], v[96:99]
	v_mfma_f32_16x16x32_bf16 v[84:87], v[148:151], v[180:183], v[84:87]
	v_mfma_f32_16x16x32_bf16 v[80:83], v[156:159], v[180:183], v[80:83]
	v_mfma_f32_16x16x32_bf16 v[68:71], v[148:151], v[188:191], v[68:71]
	v_mfma_f32_16x16x32_bf16 v[64:67], v[156:159], v[188:191], v[64:67]
	s_barrier
	s_setprio 0
	s_add_i32 s54, s45, s34
	v_lshl_add_u64 v[204:205], s[26:27], 0, v[194:195]
	s_mov_b32 m0, s54
	s_nop 0
	global_load_lds_dwordx4 v[204:205], off
	s_add_i32 m0, s54, 0x2000
	s_add_u32 s54, s26, 0xb0000
	v_lshl_add_u64 v[206:207], s[26:27], 0, v[198:199]
	s_addc_u32 s55, s27, 0
	s_add_i32 s56, s46, s34
	global_load_lds_dwordx4 v[206:207], off
	s_mov_b32 m0, s56
	v_lshl_add_u64 v[210:211], s[28:29], 0, v[196:197]
	global_load_lds_dwordx4 v194, s[54:55]
	s_add_i32 m0, s56, 0x2000
	s_nop 0
	global_load_lds_dwordx4 v198, s[54:55]
	v_lshl_add_u64 v[208:209], s[28:29], 0, v[192:193]
	s_mov_b32 m0, s35
	s_nop 0
	global_load_lds_dwordx4 v[208:209], off
	s_mov_b32 m0, s36
	s_nop 0
	global_load_lds_dwordx4 v[210:211], off
	ds_read_b128 v[160:163], v247 offset:16384
	ds_read_b128 v[164:167], v247 offset:17408
	ds_read_b128 v[168:171], v247 offset:18432
	ds_read_b128 v[172:175], v247 offset:19456
	ds_read_b128 v[176:179], v247 offset:20480
	ds_read_b128 v[180:183], v247 offset:21504
	ds_read_b128 v[184:187], v247 offset:22528
	ds_read_b128 v[188:191], v247 offset:23552
	s_waitcnt vmcnt(8)
	s_waitcnt lgkmcnt(0)
	s_setprio 1
	s_barrier
	v_mfma_f32_16x16x32_bf16 v[60:63], v[120:123], v[160:163], v[60:63]
	v_mfma_f32_16x16x32_bf16 v[56:59], v[136:139], v[160:163], v[56:59]
	v_mfma_f32_16x16x32_bf16 v[44:47], v[120:123], v[168:171], v[44:47]
	v_mfma_f32_16x16x32_bf16 v[40:43], v[136:139], v[168:171], v[40:43]
	v_mfma_f32_16x16x32_bf16 v[28:31], v[120:123], v[176:179], v[28:31]
	v_mfma_f32_16x16x32_bf16 v[24:27], v[136:139], v[176:179], v[24:27]
	v_mfma_f32_16x16x32_bf16 v[12:15], v[120:123], v[184:187], v[12:15]
	v_mfma_f32_16x16x32_bf16 v[8:11], v[136:139], v[184:187], v[8:11]
	v_mfma_f32_16x16x32_bf16 v[60:63], v[128:131], v[164:167], v[60:63]
	v_mfma_f32_16x16x32_bf16 v[56:59], v[140:143], v[164:167], v[56:59]
	v_mfma_f32_16x16x32_bf16 v[44:47], v[128:131], v[172:175], v[44:47]
	v_mfma_f32_16x16x32_bf16 v[40:43], v[140:143], v[172:175], v[40:43]
	v_mfma_f32_16x16x32_bf16 v[28:31], v[128:131], v[180:183], v[28:31]
	v_mfma_f32_16x16x32_bf16 v[24:27], v[140:143], v[180:183], v[24:27]
	v_mfma_f32_16x16x32_bf16 v[12:15], v[128:131], v[188:191], v[12:15]
	v_mfma_f32_16x16x32_bf16 v[8:11], v[140:143], v[188:191], v[8:11]
	v_mfma_f32_16x16x32_bf16 v[52:55], v[144:147], v[160:163], v[52:55]
	v_mfma_f32_16x16x32_bf16 v[48:51], v[152:155], v[160:163], v[48:51]
	v_mfma_f32_16x16x32_bf16 v[36:39], v[144:147], v[168:171], v[36:39]
	v_mfma_f32_16x16x32_bf16 v[32:35], v[152:155], v[168:171], v[32:35]
	v_mfma_f32_16x16x32_bf16 v[20:23], v[144:147], v[176:179], v[20:23]
	v_mfma_f32_16x16x32_bf16 v[16:19], v[152:155], v[176:179], v[16:19]
	v_mfma_f32_16x16x32_bf16 v[4:7], v[144:147], v[184:187], v[4:7]
	v_mfma_f32_16x16x32_bf16 v[0:3], v[152:155], v[184:187], v[0:3]
	v_mfma_f32_16x16x32_bf16 v[52:55], v[148:151], v[164:167], v[52:55]
	v_mfma_f32_16x16x32_bf16 v[48:51], v[156:159], v[164:167], v[48:51]
	v_mfma_f32_16x16x32_bf16 v[36:39], v[148:151], v[172:175], v[36:39]
	v_mfma_f32_16x16x32_bf16 v[32:35], v[156:159], v[172:175], v[32:35]
	v_mfma_f32_16x16x32_bf16 v[20:23], v[148:151], v[180:183], v[20:23]
	v_mfma_f32_16x16x32_bf16 v[16:19], v[156:159], v[180:183], v[16:19]
	v_mfma_f32_16x16x32_bf16 v[4:7], v[148:151], v[188:191], v[4:7]
	v_mfma_f32_16x16x32_bf16 v[0:3], v[156:159], v[188:191], v[0:3]
	s_barrier
; #define PG8_STAGE(bufoff, gbase, voff) do { _Pragma("unroll") for (int _i = 0; _i < 2; ++_i) \
;         __builtin_amdgcn_global_load_lds((const unsigned*)((const char*)(gbase) + (voff)[_i]), (PG8_LAS unsigned*)(lds + (bufoff) + ldsw + _i * 8192), 16, 0, 0); } while (0)
; #define PG8_LDA(dst, b, h) do { _Pragma("unroll") for (int m = 0; m < 4; ++m) _Pragma("unroll") for (int k = 0; k < 2; ++k) dst[m][k] = *(const PG8_LAS bf16x8*)(lds + PG8_SA(b, h) + aoff + m * 2048 + k * 1024); } while (0)
; #define PG8_LDB(dst, b, h) do { _Pragma("unroll") for (int n = 0; n < 2; ++n) _Pragma("unroll") for (int k = 0; k < 2; ++k) dst[n][k] = *(const PG8_LAS bf16x8*)(lds + PG8_SB(b, h) + boff + n * 2048 + k * 1024); } while (0)
; #define PG8_MMA(ai, bj, At, Bt) do { __builtin_amdgcn_s_setprio(1); _Pragma("unroll") for (int m = 0; m < 4; ++m) _Pragma("unroll") for (int n = 0; n < 2; ++n) _Pragma("unroll") for (int k = 0; k < 2; ++k) \
;         acc[ai][bj][m][n] = __builtin_amdgcn_mfma_f32_16x16x32_bf16(Bt[n][k], At[m][k], acc[ai][bj][m][n], 0, 0, 0); __builtin_amdgcn_s_setprio(0); } while (0)
; #define PG8_WAIT_V(n) asm volatile("s_waitcnt vmcnt(" #n ")" ::: "memory")
; #define PG8_WAIT_L(n) asm volatile("s_waitcnt lgkmcnt(" #n ")" ::: "memory")
; #define PG8_BAR __builtin_amdgcn_s_barrier()
; #define PG8_SCHED __builtin_amdgcn_sched_barrier(0)
; template <class Epi, class Sched, bool ALIGN_EPI = false, bool SP2 = false>
; __device__ __forceinline__ void gemm_phase(PG8_LAS unsigned char* lds, const Gemm g, const Sched& S, const Epi& E) {
;     ...
;         for (int t = 0; t < nt; t += 2) {
;     ...
;             PG8_LDB(B0, 1, 0); PG8_LDB(B1, 1, 1); PG8_SCHED; PG8_LDA(At, 1, 0); PG8_STAGE(PG8_SA(0, 1), a2 + hstep, voffA);
;             PG8_WAIT_V(8); PG8_WAIT_L(0); PG8_BAR; PG8_MMA(0, 0, At, B0); PG8_MMA(0, 1, At, B1); PG8_BAR; PG8_SCHED;
;             PG8_LDA(At, 1, 1); PG8_STAGE(PG8_SB(1, 0), b3, voffB); PG8_STAGE(PG8_SB(1, 1), b3 + hstep, voffB); PG8_STAGE(PG8_SA(1, 0), a3, voffA);
;             PG8_WAIT_V(8); PG8_WAIT_L(0); PG8_BAR; PG8_MMA(1, 0, At, B0); PG8_MMA(1, 1, At, B1); PG8_BAR; PG8_SCHED;
	s_setprio 0
	s_add_i32 s54, 0, 0x18000
	s_add_i32 s55, 0, 0x1c000
	v_add_u32_e32 v140, s54, v243
	v_add_u32_e32 v156, s55, v243
	ds_read_b128 v[120:123], v140
	ds_read_b128 v[128:131], v140 offset:1024
	ds_read_b128 v[136:139], v140 offset:2048
	ds_read_b128 v[140:143], v140 offset:3072
	ds_read_b128 v[144:147], v156
	ds_read_b128 v[148:151], v156 offset:1024
	ds_read_b128 v[152:155], v156 offset:2048
	ds_read_b128 v[156:159], v156 offset:3072
	s_add_u32 s28, s28, 0xb0000
	s_addc_u32 s29, s29, 0
	s_mov_b32 m0, s37
	ds_read_b128 v[160:163], v247 offset:32768
	ds_read_b128 v[164:167], v247 offset:33792
	ds_read_b128 v[168:171], v247 offset:34816
	ds_read_b128 v[172:175], v247 offset:35840
	ds_read_b128 v[176:179], v247 offset:36864
	ds_read_b128 v[180:183], v247 offset:37888
	ds_read_b128 v[184:187], v247 offset:38912
	ds_read_b128 v[188:191], v247 offset:39936
	global_load_lds_dwordx4 v192, s[28:29]
	v_lshl_add_u64 v[212:213], s[28:29], 0, v[196:197]
	s_mov_b32 m0, s38
	s_nop 0
	global_load_lds_dwordx4 v[212:213], off
	s_waitcnt vmcnt(8)
	s_waitcnt lgkmcnt(0)
	s_setprio 1
	s_barrier
	v_mfma_f32_16x16x32_bf16 v[132:135], v[120:123], v[160:163], v[132:135]
	v_mfma_f32_16x16x32_bf16 v[124:127], v[136:139], v[160:163], v[124:127]
	v_mfma_f32_16x16x32_bf16 v[108:111], v[120:123], v[168:171], v[108:111]
	v_mfma_f32_16x16x32_bf16 v[104:107], v[136:139], v[168:171], v[104:107]
	v_mfma_f32_16x16x32_bf16 v[92:95], v[120:123], v[176:179], v[92:95]
	v_mfma_f32_16x16x32_bf16 v[88:91], v[136:139], v[176:179], v[88:91]
	v_mfma_f32_16x16x32_bf16 v[76:79], v[120:123], v[184:187], v[76:79]
	v_mfma_f32_16x16x32_bf16 v[72:75], v[136:139], v[184:187], v[72:75]
	v_mfma_f32_16x16x32_bf16 v[132:135], v[128:131], v[164:167], v[132:135]
	v_mfma_f32_16x16x32_bf16 v[124:127], v[140:143], v[164:167], v[124:127]
	v_mfma_f32_16x16x32_bf16 v[108:111], v[128:131], v[172:175], v[108:111]
	v_mfma_f32_16x16x32_bf16 v[104:107], v[140:143], v[172:175], v[104:107]
	v_mfma_f32_16x16x32_bf16 v[92:95], v[128:131], v[180:183], v[92:95]
	v_mfma_f32_16x16x32_bf16 v[88:91], v[140:143], v[180:183], v[88:91]
	v_mfma_f32_16x16x32_bf16 v[76:79], v[128:131], v[188:191], v[76:79]
	v_mfma_f32_16x16x32_bf16 v[72:75], v[140:143], v[188:191], v[72:75]
	v_mfma_f32_16x16x32_bf16 v[116:119], v[144:147], v[160:163], v[116:119]
	v_mfma_f32_16x16x32_bf16 v[112:115], v[152:155], v[160:163], v[112:115]
	v_mfma_f32_16x16x32_bf16 v[100:103], v[144:147], v[168:171], v[100:103]
	v_mfma_f32_16x16x32_bf16 v[96:99], v[152:155], v[168:171], v[96:99]
	v_mfma_f32_16x16x32_bf16 v[84:87], v[144:147], v[176:179], v[84:87]
	v_mfma_f32_16x16x32_bf16 v[80:83], v[152:155], v[176:179], v[80:83]
	v_mfma_f32_16x16x32_bf16 v[68:71], v[144:147], v[184:187], v[68:71]
	v_mfma_f32_16x16x32_bf16 v[64:67], v[152:155], v[184:187], v[64:67]
	v_mfma_f32_16x16x32_bf16 v[116:119], v[148:151], v[164:167], v[116:119]
	v_mfma_f32_16x16x32_bf16 v[112:115], v[156:159], v[164:167], v[112:115]
	v_mfma_f32_16x16x32_bf16 v[100:103], v[148:151], v[172:175], v[100:103]
	v_mfma_f32_16x16x32_bf16 v[96:99], v[156:159], v[172:175], v[96:99]
	v_mfma_f32_16x16x32_bf16 v[84:87], v[148:151], v[180:183], v[84:87]
	v_mfma_f32_16x16x32_bf16 v[80:83], v[156:159], v[180:183], v[80:83]
	v_mfma_f32_16x16x32_bf16 v[68:71], v[148:151], v[188:191], v[68:71]
	v_mfma_f32_16x16x32_bf16 v[64:67], v[156:159], v[188:191], v[64:67]
	s_barrier
	s_setprio 0
	s_add_i32 s28, s54, s34
	v_lshl_add_u64 v[204:205], v[204:205], 0, s[18:19]
	s_mov_b32 m0, s28
	s_nop 0
	global_load_lds_dwordx4 v[204:205], off
	s_add_i32 m0, s28, 0x2000
	s_add_u32 s26, s26, 0xb0080
	v_lshl_add_u64 v[204:205], v[206:207], 0, s[18:19]
	s_addc_u32 s27, s27, 0
	s_add_i32 s28, s55, s34
	global_load_lds_dwordx4 v[204:205], off
	s_mov_b32 m0, s28
	s_nop 0
	global_load_lds_dwordx4 v194, s[26:27]
	s_add_i32 m0, s28, 0x2000
	s_nop 0
	global_load_lds_dwordx4 v198, s[26:27]
	v_lshl_add_u64 v[204:205], v[208:209], 0, s[18:19]
	s_mov_b32 m0, s40
	s_nop 0
	global_load_lds_dwordx4 v[204:205], off
	v_lshl_add_u64 v[204:205], v[210:211], 0, s[18:19]
	s_mov_b32 m0, s41
	s_nop 0
	global_load_lds_dwordx4 v[204:205], off
	ds_read_b128 v[160:163], v247 offset:49152
	ds_read_b128 v[164:167], v247 offset:50176
	ds_read_b128 v[168:171], v247 offset:51200
	ds_read_b128 v[172:175], v247 offset:52224
	ds_read_b128 v[176:179], v247 offset:53248
	ds_read_b128 v[180:183], v247 offset:54272
	ds_read_b128 v[184:187], v247 offset:55296
	ds_read_b128 v[188:191], v247 offset:56320
	s_waitcnt vmcnt(8)
	s_waitcnt lgkmcnt(0)
	s_setprio 1
	s_barrier
	v_mfma_f32_16x16x32_bf16 v[60:63], v[120:123], v[160:163], v[60:63]
	v_mfma_f32_16x16x32_bf16 v[56:59], v[136:139], v[160:163], v[56:59]
	v_mfma_f32_16x16x32_bf16 v[44:47], v[120:123], v[168:171], v[44:47]
	v_mfma_f32_16x16x32_bf16 v[40:43], v[136:139], v[168:171], v[40:43]
	v_mfma_f32_16x16x32_bf16 v[28:31], v[120:123], v[176:179], v[28:31]
	v_mfma_f32_16x16x32_bf16 v[24:27], v[136:139], v[176:179], v[24:27]
	v_mfma_f32_16x16x32_bf16 v[12:15], v[120:123], v[184:187], v[12:15]
	v_mfma_f32_16x16x32_bf16 v[8:11], v[136:139], v[184:187], v[8:11]
	v_mfma_f32_16x16x32_bf16 v[60:63], v[128:131], v[164:167], v[60:63]
	v_mfma_f32_16x16x32_bf16 v[56:59], v[140:143], v[164:167], v[56:59]
	v_mfma_f32_16x16x32_bf16 v[44:47], v[128:131], v[172:175], v[44:47]
	v_mfma_f32_16x16x32_bf16 v[40:43], v[140:143], v[172:175], v[40:43]
	v_mfma_f32_16x16x32_bf16 v[28:31], v[128:131], v[180:183], v[28:31]
	v_mfma_f32_16x16x32_bf16 v[24:27], v[140:143], v[180:183], v[24:27]
	v_mfma_f32_16x16x32_bf16 v[12:15], v[128:131], v[188:191], v[12:15]
	v_mfma_f32_16x16x32_bf16 v[8:11], v[140:143], v[188:191], v[8:11]
	v_mfma_f32_16x16x32_bf16 v[52:55], v[144:147], v[160:163], v[52:55]
	v_mfma_f32_16x16x32_bf16 v[48:51], v[152:155], v[160:163], v[48:51]
	v_mfma_f32_16x16x32_bf16 v[36:39], v[144:147], v[168:171], v[36:39]
	v_mfma_f32_16x16x32_bf16 v[32:35], v[152:155], v[168:171], v[32:35]
	v_mfma_f32_16x16x32_bf16 v[20:23], v[144:147], v[176:179], v[20:23]
	v_mfma_f32_16x16x32_bf16 v[16:19], v[152:155], v[176:179], v[16:19]
	v_mfma_f32_16x16x32_bf16 v[4:7], v[144:147], v[184:187], v[4:7]
	v_mfma_f32_16x16x32_bf16 v[0:3], v[152:155], v[184:187], v[0:3]
	v_mfma_f32_16x16x32_bf16 v[52:55], v[148:151], v[164:167], v[52:55]
	v_mfma_f32_16x16x32_bf16 v[48:51], v[156:159], v[164:167], v[48:51]
	v_mfma_f32_16x16x32_bf16 v[36:39], v[148:151], v[172:175], v[36:39]
	v_mfma_f32_16x16x32_bf16 v[32:35], v[156:159], v[172:175], v[32:35]
	v_mfma_f32_16x16x32_bf16 v[20:23], v[148:151], v[180:183], v[20:23]
	v_mfma_f32_16x16x32_bf16 v[16:19], v[156:159], v[180:183], v[16:19]
	v_mfma_f32_16x16x32_bf16 v[4:7], v[148:151], v[188:191], v[4:7]
	v_mfma_f32_16x16x32_bf16 v[0:3], v[156:159], v[188:191], v[0:3]
	s_barrier
	s_setprio 0
	s_add_i32 s53, s53, 2
	s_add_u32 s24, s24, 0x100
	s_addc_u32 s25, s25, 0
	s_add_u32 s51, s51, 0x100
	s_addc_u32 s52, s52, 0
	s_cmp_gt_u32 s53, 41
	s_cbranch_scc0 .LBB0_418
	s_and_b64 vcc, exec, s[20:21]
	s_cbranch_vccz .LBB0_421
	s_barrier

; #define PG8_STAGE(bufoff, gbase, voff) do { _Pragma("unroll") for (int _i = 0; _i < 2; ++_i) \
;         __builtin_amdgcn_global_load_lds((const unsigned*)((const char*)(gbase) + (voff)[_i]), (PG8_LAS unsigned*)(lds + (bufoff) + ldsw + _i * 8192), 16, 0, 0); } while (0)
; #define PG8_LDA(dst, b, h) do { _Pragma("unroll") for (int m = 0; m < 4; ++m) _Pragma("unroll") for (int k = 0; k < 2; ++k) dst[m][k] = *(const PG8_LAS bf16x8*)(lds + PG8_SA(b, h) + aoff + m * 2048 + k * 1024); } while (0)
; template <class Epi, class Sched, bool ALIGN_EPI = false, bool SP2 = false>
; __device__ __forceinline__ void gemm_phase(PG8_LAS unsigned char* lds, const Gemm g, const Sched& S, const Epi& E) {
;     ...
;         const bool has_next = S.next(ui + 1, nxt);
;         const char* nA = has_next ? (const char*)g.A + (size_t)nxt.pm * tstep : cA; const char* nB = has_next ? (const char*)g.Bt + (size_t)nxt.pn * tstep : cB;
;         for (int t = 0; t < nt; t += 2) {
;             const bool last = (t == nt - 2);
;             const char* a1 = cA + (size_t)(t + 1) * kstep;
;             const char* a2 = last ? nA : cA + (size_t)(t + 2) * kstep; const char* b2 = last ? nB : cB + (size_t)(t + 2) * kstep;
;             const char* a3 = a2 + kstep; const char* b3 = b2 + kstep;
;             if (last && has_next) S.a_ready(nxt, ui + 1);
;             if constexpr (SP2) {
;             PG8_LDB(B0, 0, 0); PG8_LDB(B1, 0, 1); PG8_SCHED; PG8_LDA(At, 0, 0); PG8_STAGE(PG8_SA(1, 1), a1 + hstep, voffA);
;             PG8_WAIT_V(8); PG8_WAIT_L(0); PG8_BAR; PG8_MMA(0, 0, At, B0); PG8_MMA(0, 1, At, B1); PG8_BAR; PG8_SCHED;
;             PG8_LDA(At, 0, 1); PG8_STAGE(PG8_SB(0, 0), b2, voffB); PG8_STAGE(PG8_SB(0, 1), b2 + hstep, voffB); PG8_STAGE(PG8_SA(0, 0), a2, voffA);
;             PG8_WAIT_V(8); PG8_WAIT_L(0); PG8_BAR; PG8_MMA(1, 0, At, B0); PG8_MMA(1, 1, At, B1); PG8_BAR; PG8_SCHED;
;             PG8_LDB(B0, 1, 0); PG8_LDB(B1, 1, 1); PG8_SCHED; PG8_LDA(At, 1, 0); PG8_STAGE(PG8_SA(0, 1), a2 + hstep, voffA);
;             PG8_WAIT_V(8); PG8_WAIT_L(0); PG8_BAR; PG8_MMA(0, 0, At, B0); PG8_MMA(0, 1, At, B1); PG8_BAR; PG8_SCHED;
;             PG8_LDA(At, 1, 1); PG8_STAGE(PG8_SB(1, 0), b3, voffB); PG8_STAGE(PG8_SB(1, 1), b3 + hstep, voffB); PG8_STAGE(PG8_SA(1, 0), a3, voffA);
;             PG8_WAIT_V(8); PG8_WAIT_L(0); PG8_BAR; PG8_MMA(1, 0, At, B0); PG8_MMA(1, 1, At, B1); PG8_BAR; PG8_SCHED;
.LBB0_508:
	s_ashr_i32 s31, s30, 31
	s_lshl_b64 s[34:35], s[30:31], 19
	s_add_u32 s34, s48, s34
	s_addc_u32 s35, s49, s35
	s_and_b64 s[36:37], s[4:5], exec
	s_cselect_b32 s9, s35, s39
	s_cselect_b32 s14, s34, s38
	s_ashr_i32 s29, s28, 31
	s_lshl_b64 s[36:37], s[28:29], 19
	s_add_u32 s36, s50, s36
	s_addc_u32 s37, s51, s37
	s_and_b64 s[42:43], s[4:5], exec
	s_cselect_b32 s29, s37, s41
	s_cselect_b32 s31, s36, s40
	s_add_u32 s38, s38, 0x40080
	s_addc_u32 s39, s39, 0
	s_add_u32 s44, s40, 0x100
	s_addc_u32 s45, s41, 0
	s_mov_b32 s70, -2
	s_add_u32 s40, s38, 0xfffc0080
	s_addc_u32 s41, s39, -1
	s_cmp_eq_u32 s70, 12
	s_cselect_b32 s43, s9, s41
	s_cselect_b32 s42, s14, s40
	s_cselect_b32 s41, s29, s45
	s_cselect_b32 s40, s31, s44
	v_lshl_add_u64 v[226:227], s[38:39], 0, v[132:133]
	s_add_i32 m0, s52, 0xc000
	s_nop 0
	global_load_lds_dwordx4 v[226:227], off
	v_lshl_add_u64 v[226:227], s[38:39], 0, v[134:135]
	s_add_i32 m0, s52, 0xe000
	s_nop 0
	global_load_lds_dwordx4 v[226:227], off
	s_waitcnt vmcnt(8)
	s_waitcnt lgkmcnt(0)
	s_setprio 1
	s_barrier
	v_mfma_f32_16x16x32_bf16 v[124:127], v[148:151], v[194:197], 0
	v_mfma_f32_16x16x32_bf16 v[120:123], v[170:173], v[194:197], 0
	v_mfma_f32_16x16x32_bf16 v[108:111], v[148:151], v[202:205], 0
	v_mfma_f32_16x16x32_bf16 v[104:107], v[170:173], v[202:205], 0
	v_mfma_f32_16x16x32_bf16 v[92:95], v[148:151], v[210:213], 0
	v_mfma_f32_16x16x32_bf16 v[88:91], v[170:173], v[210:213], 0
	v_mfma_f32_16x16x32_bf16 v[76:79], v[148:151], v[218:221], 0
	v_mfma_f32_16x16x32_bf16 v[72:75], v[170:173], v[218:221], 0
	v_mfma_f32_16x16x32_bf16 v[124:127], v[166:169], v[198:201], v[124:127]
	v_mfma_f32_16x16x32_bf16 v[120:123], v[174:177], v[198:201], v[120:123]
	v_mfma_f32_16x16x32_bf16 v[108:111], v[166:169], v[206:209], v[108:111]
	v_mfma_f32_16x16x32_bf16 v[104:107], v[174:177], v[206:209], v[104:107]
	v_mfma_f32_16x16x32_bf16 v[92:95], v[166:169], v[214:217], v[92:95]
	v_mfma_f32_16x16x32_bf16 v[88:91], v[174:177], v[214:217], v[88:91]
	v_mfma_f32_16x16x32_bf16 v[76:79], v[166:169], v[222:225], v[76:79]
	v_mfma_f32_16x16x32_bf16 v[72:75], v[174:177], v[222:225], v[72:75]
	v_mfma_f32_16x16x32_bf16 v[116:119], v[178:181], v[194:197], 0
	v_mfma_f32_16x16x32_bf16 v[112:115], v[186:189], v[194:197], 0
	v_mfma_f32_16x16x32_bf16 v[100:103], v[178:181], v[202:205], 0
	v_mfma_f32_16x16x32_bf16 v[96:99], v[186:189], v[202:205], 0
	v_mfma_f32_16x16x32_bf16 v[84:87], v[178:181], v[210:213], 0
	v_mfma_f32_16x16x32_bf16 v[80:83], v[186:189], v[210:213], 0
	v_mfma_f32_16x16x32_bf16 v[68:71], v[178:181], v[218:221], 0
	v_mfma_f32_16x16x32_bf16 v[64:67], v[186:189], v[218:221], 0
	v_mfma_f32_16x16x32_bf16 v[116:119], v[182:185], v[198:201], v[116:119]
	v_mfma_f32_16x16x32_bf16 v[112:115], v[190:193], v[198:201], v[112:115]
	v_mfma_f32_16x16x32_bf16 v[100:103], v[182:185], v[206:209], v[100:103]
	v_mfma_f32_16x16x32_bf16 v[96:99], v[190:193], v[206:209], v[96:99]
	v_mfma_f32_16x16x32_bf16 v[84:87], v[182:185], v[214:217], v[84:87]
	v_mfma_f32_16x16x32_bf16 v[80:83], v[190:193], v[214:217], v[80:83]
	v_mfma_f32_16x16x32_bf16 v[68:71], v[182:185], v[222:225], v[68:71]
	v_mfma_f32_16x16x32_bf16 v[64:67], v[190:193], v[222:225], v[64:67]
	s_barrier
	s_setprio 0
	s_add_i32 s71, s61, s33
	v_lshl_add_u64 v[226:227], s[40:41], 0, v[138:139]
	s_mov_b32 m0, s71
	s_nop 0
	global_load_lds_dwordx4 v[226:227], off
	s_add_i32 m0, s71, 0x2000
	s_add_u32 s72, s40, 0x40000
	v_lshl_add_u64 v[228:229], s[40:41], 0, v[142:143]
	s_addc_u32 s73, s41, 0
	s_add_i32 s71, s62, s33
	global_load_lds_dwordx4 v[228:229], off
	v_lshl_add_u64 v[230:231], s[72:73], 0, v[138:139]
	s_mov_b32 m0, s71
	v_lshl_add_u64 v[232:233], s[42:43], 0, v[140:141]
	global_load_lds_dwordx4 v[230:231], off
	v_lshl_add_u64 v[230:231], s[72:73], 0, v[142:143]
	s_add_i32 m0, s71, 0x2000
	s_nop 0
	global_load_lds_dwordx4 v[230:231], off
	v_lshl_add_u64 v[230:231], s[42:43], 0, v[136:137]
	s_mov_b32 m0, s52
	s_nop 0
	global_load_lds_dwordx4 v[230:231], off
	s_mov_b32 m0, s53
	s_nop 0
	global_load_lds_dwordx4 v[232:233], off
	ds_read_b128 v[194:197], v164 offset:16384
	ds_read_b128 v[198:201], v164 offset:17408
	ds_read_b128 v[202:205], v164 offset:18432
	ds_read_b128 v[206:209], v164 offset:19456
	ds_read_b128 v[210:213], v164 offset:20480
	ds_read_b128 v[214:217], v164 offset:21504
	ds_read_b128 v[218:221], v164 offset:22528
	ds_read_b128 v[222:225], v164 offset:23552
	s_waitcnt vmcnt(8)
	s_waitcnt lgkmcnt(0)
	s_setprio 1
	s_barrier
	v_mfma_f32_16x16x32_bf16 v[60:63], v[148:151], v[194:197], 0
	v_mfma_f32_16x16x32_bf16 v[56:59], v[170:173], v[194:197], 0
	v_mfma_f32_16x16x32_bf16 v[44:47], v[148:151], v[202:205], 0
	v_mfma_f32_16x16x32_bf16 v[40:43], v[170:173], v[202:205], 0
	v_mfma_f32_16x16x32_bf16 v[28:31], v[148:151], v[210:213], 0
	v_mfma_f32_16x16x32_bf16 v[24:27], v[170:173], v[210:213], 0
	v_mfma_f32_16x16x32_bf16 v[12:15], v[148:151], v[218:221], 0
	v_mfma_f32_16x16x32_bf16 v[8:11], v[170:173], v[218:221], 0
	v_mfma_f32_16x16x32_bf16 v[60:63], v[166:169], v[198:201], v[60:63]
	v_mfma_f32_16x16x32_bf16 v[56:59], v[174:177], v[198:201], v[56:59]
	v_mfma_f32_16x16x32_bf16 v[44:47], v[166:169], v[206:209], v[44:47]
	v_mfma_f32_16x16x32_bf16 v[40:43], v[174:177], v[206:209], v[40:43]
	v_mfma_f32_16x16x32_bf16 v[28:31], v[166:169], v[214:217], v[28:31]
	v_mfma_f32_16x16x32_bf16 v[24:27], v[174:177], v[214:217], v[24:27]
	v_mfma_f32_16x16x32_bf16 v[12:15], v[166:169], v[222:225], v[12:15]
	v_mfma_f32_16x16x32_bf16 v[8:11], v[174:177], v[222:225], v[8:11]
	v_mfma_f32_16x16x32_bf16 v[52:55], v[178:181], v[194:197], 0
	v_mfma_f32_16x16x32_bf16 v[48:51], v[186:189], v[194:197], 0
	v_mfma_f32_16x16x32_bf16 v[36:39], v[178:181], v[202:205], 0
	v_mfma_f32_16x16x32_bf16 v[32:35], v[186:189], v[202:205], 0
	v_mfma_f32_16x16x32_bf16 v[20:23], v[178:181], v[210:213], 0
	v_mfma_f32_16x16x32_bf16 v[16:19], v[186:189], v[210:213], 0
	v_mfma_f32_16x16x32_bf16 v[4:7], v[178:181], v[218:221], 0
	v_mfma_f32_16x16x32_bf16 v[0:3], v[186:189], v[218:221], 0
	v_mfma_f32_16x16x32_bf16 v[52:55], v[182:185], v[198:201], v[52:55]
	v_mfma_f32_16x16x32_bf16 v[48:51], v[190:193], v[198:201], v[48:51]
	v_mfma_f32_16x16x32_bf16 v[36:39], v[182:185], v[206:209], v[36:39]
	v_mfma_f32_16x16x32_bf16 v[32:35], v[190:193], v[206:209], v[32:35]
	v_mfma_f32_16x16x32_bf16 v[20:23], v[182:185], v[214:217], v[20:23]
	v_mfma_f32_16x16x32_bf16 v[16:19], v[190:193], v[214:217], v[16:19]
	v_mfma_f32_16x16x32_bf16 v[4:7], v[182:185], v[222:225], v[4:7]
	v_mfma_f32_16x16x32_bf16 v[0:3], v[190:193], v[222:225], v[0:3]
	s_barrier
; #define PG8_STAGE(bufoff, gbase, voff) do { _Pragma("unroll") for (int _i = 0; _i < 2; ++_i) \
;         __builtin_amdgcn_global_load_lds((const unsigned*)((const char*)(gbase) + (voff)[_i]), (PG8_LAS unsigned*)(lds + (bufoff) + ldsw + _i * 8192), 16, 0, 0); } while (0)
; #define PG8_LDA(dst, b, h) do { _Pragma("unroll") for (int m = 0; m < 4; ++m) _Pragma("unroll") for (int k = 0; k < 2; ++k) dst[m][k] = *(const PG8_LAS bf16x8*)(lds + PG8_SA(b, h) + aoff + m * 2048 + k * 1024); } while (0)
; #define PG8_LDB(dst, b, h) do { _Pragma("unroll") for (int n = 0; n < 2; ++n) _Pragma("unroll") for (int k = 0; k < 2; ++k) dst[n][k] = *(const PG8_LAS bf16x8*)(lds + PG8_SB(b, h) + boff + n * 2048 + k * 1024); } while (0)
; #define PG8_MMA(ai, bj, At, Bt) do { __builtin_amdgcn_s_setprio(1); _Pragma("unroll") for (int m = 0; m < 4; ++m) _Pragma("unroll") for (int n = 0; n < 2; ++n) _Pragma("unroll") for (int k = 0; k < 2; ++k) \
;         acc[ai][bj][m][n] = __builtin_amdgcn_mfma_f32_16x16x32_bf16(Bt[n][k], At[m][k], acc[ai][bj][m][n], 0, 0, 0); __builtin_amdgcn_s_setprio(0); } while (0)
; #define PG8_WAIT_V(n) asm volatile("s_waitcnt vmcnt(" #n ")" ::: "memory")
; #define PG8_WAIT_L(n) asm volatile("s_waitcnt lgkmcnt(" #n ")" ::: "memory")
; #define PG8_BAR __builtin_amdgcn_s_barrier()
; #define PG8_SCHED __builtin_amdgcn_sched_barrier(0)
; template <class Epi, class Sched, bool ALIGN_EPI = false, bool SP2 = false>
; __device__ __forceinline__ void gemm_phase(PG8_LAS unsigned char* lds, const Gemm g, const Sched& S, const Epi& E) {
;     ...
;             PG8_LDB(B0, 1, 0); PG8_LDB(B1, 1, 1); PG8_SCHED; PG8_LDA(At, 1, 0); PG8_STAGE(PG8_SA(0, 1), a2 + hstep, voffA);
;             PG8_WAIT_V(8); PG8_WAIT_L(0); PG8_BAR; PG8_MMA(0, 0, At, B0); PG8_MMA(0, 1, At, B1); PG8_BAR; PG8_SCHED;
;             PG8_LDA(At, 1, 1); PG8_STAGE(PG8_SB(1, 0), b3, voffB); PG8_STAGE(PG8_SB(1, 1), b3 + hstep, voffB); PG8_STAGE(PG8_SA(1, 0), a3, voffA);
;             PG8_WAIT_V(8); PG8_WAIT_L(0); PG8_BAR; PG8_MMA(1, 0, At, B0); PG8_MMA(1, 1, At, B1); PG8_BAR; PG8_SCHED;
	s_setprio 0
	s_add_i32 s71, 0, 0x18000
	v_add_u32_e32 v130, s71, v160
	s_add_i32 s72, 0, 0x1c000
	ds_read_b128 v[148:151], v130
	ds_read_b128 v[166:169], v130 offset:1024
	ds_read_b128 v[170:173], v130 offset:2048
	ds_read_b128 v[174:177], v130 offset:3072
	v_add_u32_e32 v130, s72, v160
	ds_read_b128 v[178:181], v130
	ds_read_b128 v[182:185], v130 offset:1024
	ds_read_b128 v[186:189], v130 offset:2048
	ds_read_b128 v[190:193], v130 offset:3072
	s_add_u32 s42, s42, 0x40000
	s_addc_u32 s43, s43, 0
	s_mov_b32 m0, s54
	v_lshl_add_u64 v[234:235], s[42:43], 0, v[136:137]
	ds_read_b128 v[194:197], v164 offset:32768
	ds_read_b128 v[198:201], v164 offset:33792
	ds_read_b128 v[202:205], v164 offset:34816
	ds_read_b128 v[206:209], v164 offset:35840
	ds_read_b128 v[210:213], v164 offset:36864
	ds_read_b128 v[214:217], v164 offset:37888
	ds_read_b128 v[218:221], v164 offset:38912
	ds_read_b128 v[222:225], v164 offset:39936
	global_load_lds_dwordx4 v[234:235], off
	v_lshl_add_u64 v[234:235], s[42:43], 0, v[140:141]
	s_mov_b32 m0, s55
	s_nop 0
	global_load_lds_dwordx4 v[234:235], off
	s_waitcnt vmcnt(8)
	s_waitcnt lgkmcnt(0)
	s_setprio 1
	s_barrier
	v_mfma_f32_16x16x32_bf16 v[124:127], v[148:151], v[194:197], v[124:127]
	v_mfma_f32_16x16x32_bf16 v[120:123], v[170:173], v[194:197], v[120:123]
	v_mfma_f32_16x16x32_bf16 v[108:111], v[148:151], v[202:205], v[108:111]
	v_mfma_f32_16x16x32_bf16 v[104:107], v[170:173], v[202:205], v[104:107]
	v_mfma_f32_16x16x32_bf16 v[92:95], v[148:151], v[210:213], v[92:95]
	v_mfma_f32_16x16x32_bf16 v[88:91], v[170:173], v[210:213], v[88:91]
	v_mfma_f32_16x16x32_bf16 v[76:79], v[148:151], v[218:221], v[76:79]
	v_mfma_f32_16x16x32_bf16 v[72:75], v[170:173], v[218:221], v[72:75]
	v_mfma_f32_16x16x32_bf16 v[124:127], v[166:169], v[198:201], v[124:127]
	v_mfma_f32_16x16x32_bf16 v[120:123], v[174:177], v[198:201], v[120:123]
	v_mfma_f32_16x16x32_bf16 v[108:111], v[166:169], v[206:209], v[108:111]
	v_mfma_f32_16x16x32_bf16 v[104:107], v[174:177], v[206:209], v[104:107]
	v_mfma_f32_16x16x32_bf16 v[92:95], v[166:169], v[214:217], v[92:95]
	v_mfma_f32_16x16x32_bf16 v[88:91], v[174:177], v[214:217], v[88:91]
	v_mfma_f32_16x16x32_bf16 v[76:79], v[166:169], v[222:225], v[76:79]
	v_mfma_f32_16x16x32_bf16 v[72:75], v[174:177], v[222:225], v[72:75]
	v_mfma_f32_16x16x32_bf16 v[116:119], v[178:181], v[194:197], v[116:119]
	v_mfma_f32_16x16x32_bf16 v[112:115], v[186:189], v[194:197], v[112:115]
	v_mfma_f32_16x16x32_bf16 v[100:103], v[178:181], v[202:205], v[100:103]
	v_mfma_f32_16x16x32_bf16 v[96:99], v[186:189], v[202:205], v[96:99]
	v_mfma_f32_16x16x32_bf16 v[84:87], v[178:181], v[210:213], v[84:87]
	v_mfma_f32_16x16x32_bf16 v[80:83], v[186:189], v[210:213], v[80:83]
	v_mfma_f32_16x16x32_bf16 v[68:71], v[178:181], v[218:221], v[68:71]
	v_mfma_f32_16x16x32_bf16 v[64:67], v[186:189], v[218:221], v[64:67]
	v_mfma_f32_16x16x32_bf16 v[116:119], v[182:185], v[198:201], v[116:119]
	v_mfma_f32_16x16x32_bf16 v[112:115], v[190:193], v[198:201], v[112:115]
	v_mfma_f32_16x16x32_bf16 v[100:103], v[182:185], v[206:209], v[100:103]
	v_mfma_f32_16x16x32_bf16 v[96:99], v[190:193], v[206:209], v[96:99]
	v_mfma_f32_16x16x32_bf16 v[84:87], v[182:185], v[214:217], v[84:87]
	v_mfma_f32_16x16x32_bf16 v[80:83], v[190:193], v[214:217], v[80:83]
	v_mfma_f32_16x16x32_bf16 v[68:71], v[182:185], v[222:225], v[68:71]
	v_mfma_f32_16x16x32_bf16 v[64:67], v[190:193], v[222:225], v[64:67]
	s_barrier
	s_setprio 0
	s_add_i32 s42, s71, s33
	v_lshl_add_u64 v[226:227], v[226:227], 0, s[24:25]
	s_mov_b32 m0, s42
	s_nop 0
	global_load_lds_dwordx4 v[226:227], off
	s_add_i32 m0, s42, 0x2000
	s_add_u32 s40, s40, 0x40080
	v_lshl_add_u64 v[226:227], v[228:229], 0, s[24:25]
	s_addc_u32 s41, s41, 0
	s_add_i32 s42, s72, s33
	global_load_lds_dwordx4 v[226:227], off
	v_lshl_add_u64 v[226:227], s[40:41], 0, v[138:139]
	s_mov_b32 m0, s42
	s_nop 0
	global_load_lds_dwordx4 v[226:227], off
	v_lshl_add_u64 v[226:227], s[40:41], 0, v[142:143]
	s_add_i32 m0, s42, 0x2000
	s_nop 0
	global_load_lds_dwordx4 v[226:227], off
	v_lshl_add_u64 v[226:227], v[230:231], 0, s[24:25]
	s_mov_b32 m0, s57
	s_nop 0
	global_load_lds_dwordx4 v[226:227], off
	v_lshl_add_u64 v[226:227], v[232:233], 0, s[24:25]
	s_mov_b32 m0, s58
	s_nop 0
	global_load_lds_dwordx4 v[226:227], off
	ds_read_b128 v[194:197], v164 offset:49152
	ds_read_b128 v[198:201], v164 offset:50176
	ds_read_b128 v[202:205], v164 offset:51200
	ds_read_b128 v[206:209], v164 offset:52224
	ds_read_b128 v[210:213], v164 offset:53248
	ds_read_b128 v[214:217], v164 offset:54272
	ds_read_b128 v[218:221], v164 offset:55296
	ds_read_b128 v[222:225], v164 offset:56320
	s_waitcnt vmcnt(8)
	s_waitcnt lgkmcnt(0)
	s_setprio 1
	s_barrier
; #define PG8_STAGE(bufoff, gbase, voff) do { _Pragma("unroll") for (int _i = 0; _i < 2; ++_i) \
;         __builtin_amdgcn_global_load_lds((const unsigned*)((const char*)(gbase) + (voff)[_i]), (PG8_LAS unsigned*)(lds + (bufoff) + ldsw + _i * 8192), 16, 0, 0); } while (0)
; #define PG8_LDA(dst, b, h) do { _Pragma("unroll") for (int m = 0; m < 4; ++m) _Pragma("unroll") for (int k = 0; k < 2; ++k) dst[m][k] = *(const PG8_LAS bf16x8*)(lds + PG8_SA(b, h) + aoff + m * 2048 + k * 1024); } while (0)
; #define PG8_LDB(dst, b, h) do { _Pragma("unroll") for (int n = 0; n < 2; ++n) _Pragma("unroll") for (int k = 0; k < 2; ++k) dst[n][k] = *(const PG8_LAS bf16x8*)(lds + PG8_SB(b, h) + boff + n * 2048 + k * 1024); } while (0)
; #define PG8_MMA(ai, bj, At, Bt) do { __builtin_amdgcn_s_setprio(1); _Pragma("unroll") for (int m = 0; m < 4; ++m) _Pragma("unroll") for (int n = 0; n < 2; ++n) _Pragma("unroll") for (int k = 0; k < 2; ++k) \
;         acc[ai][bj][m][n] = __builtin_amdgcn_mfma_f32_16x16x32_bf16(Bt[n][k], At[m][k], acc[ai][bj][m][n], 0, 0, 0); __builtin_amdgcn_s_setprio(0); } while (0)
; #define PG8_WAIT_V(n) asm volatile("s_waitcnt vmcnt(" #n ")" ::: "memory")
; #define PG8_BAR __builtin_amdgcn_s_barrier()
; template <class Epi, class Sched, bool ALIGN_EPI = false, bool SP2 = false>
; __device__ __forceinline__ void gemm_phase(PG8_LAS unsigned char* lds, const Gemm g, const Sched& S, const Epi& E) {
;     ...
;         for (int t = 0; t < nt; t += 2) {
;             const bool last = (t == nt - 2);
;             const char* a1 = cA + (size_t)(t + 1) * kstep;
;             const char* a2 = last ? nA : cA + (size_t)(t + 2) * kstep; const char* b2 = last ? nB : cB + (size_t)(t + 2) * kstep;
;             const char* a3 = a2 + kstep; const char* b3 = b2 + kstep;
;             if (last && has_next) S.a_ready(nxt, ui + 1);
;             if constexpr (SP2) {
;             PG8_LDB(B0, 0, 0); PG8_LDB(B1, 0, 1); PG8_SCHED; PG8_LDA(At, 0, 0); PG8_STAGE(PG8_SA(1, 1), a1 + hstep, voffA);
;             PG8_WAIT_V(8); PG8_WAIT_L(0); PG8_BAR; PG8_MMA(0, 0, At, B0); PG8_MMA(0, 1, At, B1); PG8_BAR; PG8_SCHED;
;             PG8_LDA(At, 0, 1); PG8_STAGE(PG8_SB(0, 0), b2, voffB); PG8_STAGE(PG8_SB(0, 1), b2 + hstep, voffB); PG8_STAGE(PG8_SA(0, 0), a2, voffA);
;             PG8_WAIT_V(8); PG8_WAIT_L(0); PG8_BAR; PG8_MMA(1, 0, At, B0); PG8_MMA(1, 1, At, B1); PG8_BAR; PG8_SCHED;
	v_mfma_f32_16x16x32_bf16 v[60:63], v[148:151], v[194:197], v[60:63]
	v_mfma_f32_16x16x32_bf16 v[56:59], v[170:173], v[194:197], v[56:59]
	v_mfma_f32_16x16x32_bf16 v[44:47], v[148:151], v[202:205], v[44:47]
	v_mfma_f32_16x16x32_bf16 v[40:43], v[170:173], v[202:205], v[40:43]
	v_mfma_f32_16x16x32_bf16 v[28:31], v[148:151], v[210:213], v[28:31]
	v_mfma_f32_16x16x32_bf16 v[24:27], v[170:173], v[210:213], v[24:27]
	v_mfma_f32_16x16x32_bf16 v[12:15], v[148:151], v[218:221], v[12:15]
	v_mfma_f32_16x16x32_bf16 v[8:11], v[170:173], v[218:221], v[8:11]
	v_mfma_f32_16x16x32_bf16 v[60:63], v[166:169], v[198:201], v[60:63]
	v_mfma_f32_16x16x32_bf16 v[56:59], v[174:177], v[198:201], v[56:59]
	v_mfma_f32_16x16x32_bf16 v[44:47], v[166:169], v[206:209], v[44:47]
	v_mfma_f32_16x16x32_bf16 v[40:43], v[174:177], v[206:209], v[40:43]
	v_mfma_f32_16x16x32_bf16 v[28:31], v[166:169], v[214:217], v[28:31]
	v_mfma_f32_16x16x32_bf16 v[24:27], v[174:177], v[214:217], v[24:27]
	v_mfma_f32_16x16x32_bf16 v[12:15], v[166:169], v[222:225], v[12:15]
	v_mfma_f32_16x16x32_bf16 v[8:11], v[174:177], v[222:225], v[8:11]
	v_mfma_f32_16x16x32_bf16 v[52:55], v[178:181], v[194:197], v[52:55]
	v_mfma_f32_16x16x32_bf16 v[48:51], v[186:189], v[194:197], v[48:51]
	v_mfma_f32_16x16x32_bf16 v[36:39], v[178:181], v[202:205], v[36:39]
	v_mfma_f32_16x16x32_bf16 v[32:35], v[186:189], v[202:205], v[32:35]
	v_mfma_f32_16x16x32_bf16 v[20:23], v[178:181], v[210:213], v[20:23]
	v_mfma_f32_16x16x32_bf16 v[16:19], v[186:189], v[210:213], v[16:19]
	v_mfma_f32_16x16x32_bf16 v[4:7], v[178:181], v[218:221], v[4:7]
	v_mfma_f32_16x16x32_bf16 v[0:3], v[186:189], v[218:221], v[0:3]
	v_mfma_f32_16x16x32_bf16 v[52:55], v[182:185], v[198:201], v[52:55]
	v_mfma_f32_16x16x32_bf16 v[48:51], v[190:193], v[198:201], v[48:51]
	v_mfma_f32_16x16x32_bf16 v[36:39], v[182:185], v[206:209], v[36:39]
	v_mfma_f32_16x16x32_bf16 v[32:35], v[190:193], v[206:209], v[32:35]
	v_mfma_f32_16x16x32_bf16 v[20:23], v[182:185], v[214:217], v[20:23]
	v_mfma_f32_16x16x32_bf16 v[16:19], v[190:193], v[214:217], v[16:19]
	v_mfma_f32_16x16x32_bf16 v[4:7], v[182:185], v[222:225], v[4:7]
	v_mfma_f32_16x16x32_bf16 v[0:3], v[190:193], v[222:225], v[0:3]
	s_barrier
	s_setprio 0
	s_add_i32 s70, s70, 2
	s_add_u32 s38, s38, 0x100
	s_addc_u32 s39, s39, 0
	s_add_u32 s44, s44, 0x100
	s_addc_u32 s45, s45, 0
	s_cmp_gt_u32 s70, 13
.LBB0_509:
	s_add_u32 s40, s38, 0xfffc0080
	s_addc_u32 s41, s39, -1
	s_cmp_eq_u32 s70, 12
	s_cselect_b32 s43, s9, s41
	s_cselect_b32 s42, s14, s40
	s_cselect_b32 s41, s29, s45
	s_cselect_b32 s40, s31, s44
	v_lshl_add_u64 v[226:227], s[38:39], 0, v[132:133]
	s_add_i32 m0, s52, 0xc000
	s_nop 0
	global_load_lds_dwordx4 v[226:227], off
	v_lshl_add_u64 v[226:227], s[38:39], 0, v[134:135]
	s_add_i32 m0, s52, 0xe000
	s_nop 0
	global_load_lds_dwordx4 v[226:227], off
	ds_read_b128 v[148:151], v162
	ds_read_b128 v[166:169], v162 offset:1024
	ds_read_b128 v[170:173], v162 offset:2048
	ds_read_b128 v[174:177], v162 offset:3072
	ds_read_b128 v[178:181], v163
	ds_read_b128 v[182:185], v163 offset:1024
	ds_read_b128 v[186:189], v163 offset:2048
	ds_read_b128 v[190:193], v163 offset:3072
	ds_read_b128 v[194:197], v164
	ds_read_b128 v[198:201], v164 offset:1024
	ds_read_b128 v[202:205], v164 offset:2048
	ds_read_b128 v[206:209], v164 offset:3072
	ds_read_b128 v[210:213], v164 offset:4096
	ds_read_b128 v[214:217], v164 offset:5120
	ds_read_b128 v[218:221], v164 offset:6144
	ds_read_b128 v[222:225], v164 offset:7168
	s_waitcnt vmcnt(8)
	s_waitcnt lgkmcnt(0)
	s_setprio 1
	s_barrier
	v_mfma_f32_16x16x32_bf16 v[124:127], v[148:151], v[194:197], v[124:127]
	v_mfma_f32_16x16x32_bf16 v[120:123], v[170:173], v[194:197], v[120:123]
	v_mfma_f32_16x16x32_bf16 v[108:111], v[148:151], v[202:205], v[108:111]
	v_mfma_f32_16x16x32_bf16 v[104:107], v[170:173], v[202:205], v[104:107]
	v_mfma_f32_16x16x32_bf16 v[92:95], v[148:151], v[210:213], v[92:95]
	v_mfma_f32_16x16x32_bf16 v[88:91], v[170:173], v[210:213], v[88:91]
	v_mfma_f32_16x16x32_bf16 v[76:79], v[148:151], v[218:221], v[76:79]
	v_mfma_f32_16x16x32_bf16 v[72:75], v[170:173], v[218:221], v[72:75]
	v_mfma_f32_16x16x32_bf16 v[124:127], v[166:169], v[198:201], v[124:127]
	v_mfma_f32_16x16x32_bf16 v[120:123], v[174:177], v[198:201], v[120:123]
	v_mfma_f32_16x16x32_bf16 v[108:111], v[166:169], v[206:209], v[108:111]
	v_mfma_f32_16x16x32_bf16 v[104:107], v[174:177], v[206:209], v[104:107]
	v_mfma_f32_16x16x32_bf16 v[92:95], v[166:169], v[214:217], v[92:95]
	v_mfma_f32_16x16x32_bf16 v[88:91], v[174:177], v[214:217], v[88:91]
	v_mfma_f32_16x16x32_bf16 v[76:79], v[166:169], v[222:225], v[76:79]
	v_mfma_f32_16x16x32_bf16 v[72:75], v[174:177], v[222:225], v[72:75]
	v_mfma_f32_16x16x32_bf16 v[116:119], v[178:181], v[194:197], v[116:119]
	v_mfma_f32_16x16x32_bf16 v[112:115], v[186:189], v[194:197], v[112:115]
	v_mfma_f32_16x16x32_bf16 v[100:103], v[178:181], v[202:205], v[100:103]
	v_mfma_f32_16x16x32_bf16 v[96:99], v[186:189], v[202:205], v[96:99]
	v_mfma_f32_16x16x32_bf16 v[84:87], v[178:181], v[210:213], v[84:87]
	v_mfma_f32_16x16x32_bf16 v[80:83], v[186:189], v[210:213], v[80:83]
	v_mfma_f32_16x16x32_bf16 v[68:71], v[178:181], v[218:221], v[68:71]
	v_mfma_f32_16x16x32_bf16 v[64:67], v[186:189], v[218:221], v[64:67]
	v_mfma_f32_16x16x32_bf16 v[116:119], v[182:185], v[198:201], v[116:119]
	v_mfma_f32_16x16x32_bf16 v[112:115], v[190:193], v[198:201], v[112:115]
	v_mfma_f32_16x16x32_bf16 v[100:103], v[182:185], v[206:209], v[100:103]
	v_mfma_f32_16x16x32_bf16 v[96:99], v[190:193], v[206:209], v[96:99]
	v_mfma_f32_16x16x32_bf16 v[84:87], v[182:185], v[214:217], v[84:87]
	v_mfma_f32_16x16x32_bf16 v[80:83], v[190:193], v[214:217], v[80:83]
	v_mfma_f32_16x16x32_bf16 v[68:71], v[182:185], v[222:225], v[68:71]
	v_mfma_f32_16x16x32_bf16 v[64:67], v[190:193], v[222:225], v[64:67]
	s_barrier
; #define PG8_STAGE(bufoff, gbase, voff) do { _Pragma("unroll") for (int _i = 0; _i < 2; ++_i) \
;         __builtin_amdgcn_global_load_lds((const unsigned*)((const char*)(gbase) + (voff)[_i]), (PG8_LAS unsigned*)(lds + (bufoff) + ldsw + _i * 8192), 16, 0, 0); } while (0)
; #define PG8_LDA(dst, b, h) do { _Pragma("unroll") for (int m = 0; m < 4; ++m) _Pragma("unroll") for (int k = 0; k < 2; ++k) dst[m][k] = *(const PG8_LAS bf16x8*)(lds + PG8_SA(b, h) + aoff + m * 2048 + k * 1024); } while (0)
; #define PG8_LDB(dst, b, h) do { _Pragma("unroll") for (int n = 0; n < 2; ++n) _Pragma("unroll") for (int k = 0; k < 2; ++k) dst[n][k] = *(const PG8_LAS bf16x8*)(lds + PG8_SB(b, h) + boff + n * 2048 + k * 1024); } while (0)
; #define PG8_MMA(ai, bj, At, Bt) do { __builtin_amdgcn_s_setprio(1); _Pragma("unroll") for (int m = 0; m < 4; ++m) _Pragma("unroll") for (int n = 0; n < 2; ++n) _Pragma("unroll") for (int k = 0; k < 2; ++k) \
;         acc[ai][bj][m][n] = __builtin_amdgcn_mfma_f32_16x16x32_bf16(Bt[n][k], At[m][k], acc[ai][bj][m][n], 0, 0, 0); __builtin_amdgcn_s_setprio(0); } while (0)
; #define PG8_WAIT_V(n) asm volatile("s_waitcnt vmcnt(" #n ")" ::: "memory")
; #define PG8_WAIT_L(n) asm volatile("s_waitcnt lgkmcnt(" #n ")" ::: "memory")
; #define PG8_BAR __builtin_amdgcn_s_barrier()
; #define PG8_SCHED __builtin_amdgcn_sched_barrier(0)
; template <class Epi, class Sched, bool ALIGN_EPI = false, bool SP2 = false>
; __device__ __forceinline__ void gemm_phase(PG8_LAS unsigned char* lds, const Gemm g, const Sched& S, const Epi& E) {
;     ...
;             PG8_LDA(At, 0, 1); PG8_STAGE(PG8_SB(0, 0), b2, voffB); PG8_STAGE(PG8_SB(0, 1), b2 + hstep, voffB); PG8_STAGE(PG8_SA(0, 0), a2, voffA);
;             PG8_WAIT_V(8); PG8_WAIT_L(0); PG8_BAR; PG8_MMA(1, 0, At, B0); PG8_MMA(1, 1, At, B1); PG8_BAR; PG8_SCHED;
;             PG8_LDB(B0, 1, 0); PG8_LDB(B1, 1, 1); PG8_SCHED; PG8_LDA(At, 1, 0); PG8_STAGE(PG8_SA(0, 1), a2 + hstep, voffA);
;             PG8_WAIT_V(8); PG8_WAIT_L(0); PG8_BAR; PG8_MMA(0, 0, At, B0); PG8_MMA(0, 1, At, B1); PG8_BAR; PG8_SCHED;
	s_setprio 0
	s_add_i32 s71, s61, s33
	v_lshl_add_u64 v[226:227], s[40:41], 0, v[138:139]
	s_mov_b32 m0, s71
	s_nop 0
	global_load_lds_dwordx4 v[226:227], off
	s_add_i32 m0, s71, 0x2000
	s_add_u32 s72, s40, 0x40000
	v_lshl_add_u64 v[228:229], s[40:41], 0, v[142:143]
	s_addc_u32 s73, s41, 0
	s_add_i32 s71, s62, s33
	global_load_lds_dwordx4 v[228:229], off
	v_lshl_add_u64 v[230:231], s[72:73], 0, v[138:139]
	s_mov_b32 m0, s71
	v_lshl_add_u64 v[232:233], s[42:43], 0, v[140:141]
	global_load_lds_dwordx4 v[230:231], off
	v_lshl_add_u64 v[230:231], s[72:73], 0, v[142:143]
	s_add_i32 m0, s71, 0x2000
	s_nop 0
	global_load_lds_dwordx4 v[230:231], off
	v_lshl_add_u64 v[230:231], s[42:43], 0, v[136:137]
	s_mov_b32 m0, s52
	s_nop 0
	global_load_lds_dwordx4 v[230:231], off
	s_mov_b32 m0, s53
	s_nop 0
	global_load_lds_dwordx4 v[232:233], off
	ds_read_b128 v[194:197], v164 offset:16384
	ds_read_b128 v[198:201], v164 offset:17408
	ds_read_b128 v[202:205], v164 offset:18432
	ds_read_b128 v[206:209], v164 offset:19456
	ds_read_b128 v[210:213], v164 offset:20480
	ds_read_b128 v[214:217], v164 offset:21504
	ds_read_b128 v[218:221], v164 offset:22528
	ds_read_b128 v[222:225], v164 offset:23552
	s_waitcnt vmcnt(8)
	s_waitcnt lgkmcnt(0)
	s_setprio 1
	s_barrier
	v_mfma_f32_16x16x32_bf16 v[60:63], v[148:151], v[194:197], v[60:63]
	v_mfma_f32_16x16x32_bf16 v[56:59], v[170:173], v[194:197], v[56:59]
	v_mfma_f32_16x16x32_bf16 v[44:47], v[148:151], v[202:205], v[44:47]
	v_mfma_f32_16x16x32_bf16 v[40:43], v[170:173], v[202:205], v[40:43]
	v_mfma_f32_16x16x32_bf16 v[28:31], v[148:151], v[210:213], v[28:31]
	v_mfma_f32_16x16x32_bf16 v[24:27], v[170:173], v[210:213], v[24:27]
	v_mfma_f32_16x16x32_bf16 v[12:15], v[148:151], v[218:221], v[12:15]
	v_mfma_f32_16x16x32_bf16 v[8:11], v[170:173], v[218:221], v[8:11]
	v_mfma_f32_16x16x32_bf16 v[60:63], v[166:169], v[198:201], v[60:63]
	v_mfma_f32_16x16x32_bf16 v[56:59], v[174:177], v[198:201], v[56:59]
	v_mfma_f32_16x16x32_bf16 v[44:47], v[166:169], v[206:209], v[44:47]
	v_mfma_f32_16x16x32_bf16 v[40:43], v[174:177], v[206:209], v[40:43]
	v_mfma_f32_16x16x32_bf16 v[28:31], v[166:169], v[214:217], v[28:31]
	v_mfma_f32_16x16x32_bf16 v[24:27], v[174:177], v[214:217], v[24:27]
	v_mfma_f32_16x16x32_bf16 v[12:15], v[166:169], v[222:225], v[12:15]
	v_mfma_f32_16x16x32_bf16 v[8:11], v[174:177], v[222:225], v[8:11]
	v_mfma_f32_16x16x32_bf16 v[52:55], v[178:181], v[194:197], v[52:55]
	v_mfma_f32_16x16x32_bf16 v[48:51], v[186:189], v[194:197], v[48:51]
	v_mfma_f32_16x16x32_bf16 v[36:39], v[178:181], v[202:205], v[36:39]
	v_mfma_f32_16x16x32_bf16 v[32:35], v[186:189], v[202:205], v[32:35]
	v_mfma_f32_16x16x32_bf16 v[20:23], v[178:181], v[210:213], v[20:23]
	v_mfma_f32_16x16x32_bf16 v[16:19], v[186:189], v[210:213], v[16:19]
	v_mfma_f32_16x16x32_bf16 v[4:7], v[178:181], v[218:221], v[4:7]
	v_mfma_f32_16x16x32_bf16 v[0:3], v[186:189], v[218:221], v[0:3]
	v_mfma_f32_16x16x32_bf16 v[52:55], v[182:185], v[198:201], v[52:55]
	v_mfma_f32_16x16x32_bf16 v[48:51], v[190:193], v[198:201], v[48:51]
	v_mfma_f32_16x16x32_bf16 v[36:39], v[182:185], v[206:209], v[36:39]
	v_mfma_f32_16x16x32_bf16 v[32:35], v[190:193], v[206:209], v[32:35]
	v_mfma_f32_16x16x32_bf16 v[20:23], v[182:185], v[214:217], v[20:23]
	v_mfma_f32_16x16x32_bf16 v[16:19], v[190:193], v[214:217], v[16:19]
	v_mfma_f32_16x16x32_bf16 v[4:7], v[182:185], v[222:225], v[4:7]
	v_mfma_f32_16x16x32_bf16 v[0:3], v[190:193], v[222:225], v[0:3]
	s_barrier
	s_setprio 0
	s_add_i32 s71, 0, 0x18000
	v_add_u32_e32 v130, s71, v160
	s_add_i32 s72, 0, 0x1c000
	ds_read_b128 v[148:151], v130
	ds_read_b128 v[166:169], v130 offset:1024
	ds_read_b128 v[170:173], v130 offset:2048
	ds_read_b128 v[174:177], v130 offset:3072
	v_add_u32_e32 v130, s72, v160
	ds_read_b128 v[178:181], v130
	ds_read_b128 v[182:185], v130 offset:1024
	ds_read_b128 v[186:189], v130 offset:2048
	ds_read_b128 v[190:193], v130 offset:3072
	s_add_u32 s42, s42, 0x40000
	s_addc_u32 s43, s43, 0
	s_mov_b32 m0, s54
	v_lshl_add_u64 v[234:235], s[42:43], 0, v[136:137]
	ds_read_b128 v[194:197], v164 offset:32768
	ds_read_b128 v[198:201], v164 offset:33792
	ds_read_b128 v[202:205], v164 offset:34816
	ds_read_b128 v[206:209], v164 offset:35840
	ds_read_b128 v[210:213], v164 offset:36864
	ds_read_b128 v[214:217], v164 offset:37888
	ds_read_b128 v[218:221], v164 offset:38912
	ds_read_b128 v[222:225], v164 offset:39936
	global_load_lds_dwordx4 v[234:235], off
	v_lshl_add_u64 v[234:235], s[42:43], 0, v[140:141]
	s_mov_b32 m0, s55
	s_nop 0
	global_load_lds_dwordx4 v[234:235], off
	s_waitcnt vmcnt(8)
	s_waitcnt lgkmcnt(0)
	s_setprio 1
	s_barrier
; #define PG8_STAGE(bufoff, gbase, voff) do { _Pragma("unroll") for (int _i = 0; _i < 2; ++_i) \
;         __builtin_amdgcn_global_load_lds((const unsigned*)((const char*)(gbase) + (voff)[_i]), (PG8_LAS unsigned*)(lds + (bufoff) + ldsw + _i * 8192), 16, 0, 0); } while (0)
; #define PG8_LDA(dst, b, h) do { _Pragma("unroll") for (int m = 0; m < 4; ++m) _Pragma("unroll") for (int k = 0; k < 2; ++k) dst[m][k] = *(const PG8_LAS bf16x8*)(lds + PG8_SA(b, h) + aoff + m * 2048 + k * 1024); } while (0)
; #define PG8_LDB(dst, b, h) do { _Pragma("unroll") for (int n = 0; n < 2; ++n) _Pragma("unroll") for (int k = 0; k < 2; ++k) dst[n][k] = *(const PG8_LAS bf16x8*)(lds + PG8_SB(b, h) + boff + n * 2048 + k * 1024); } while (0)
; #define PG8_MMA(ai, bj, At, Bt) do { __builtin_amdgcn_s_setprio(1); _Pragma("unroll") for (int m = 0; m < 4; ++m) _Pragma("unroll") for (int n = 0; n < 2; ++n) _Pragma("unroll") for (int k = 0; k < 2; ++k) \
;         acc[ai][bj][m][n] = __builtin_amdgcn_mfma_f32_16x16x32_bf16(Bt[n][k], At[m][k], acc[ai][bj][m][n], 0, 0, 0); __builtin_amdgcn_s_setprio(0); } while (0)
; #define PG8_WAIT_V(n) asm volatile("s_waitcnt vmcnt(" #n ")" ::: "memory")
; #define PG8_WAIT_L(n) asm volatile("s_waitcnt lgkmcnt(" #n ")" ::: "memory")
; #define PG8_BAR __builtin_amdgcn_s_barrier()
; #define PG8_SCHED __builtin_amdgcn_sched_barrier(0)
; template <class Epi, class Sched, bool ALIGN_EPI = false, bool SP2 = false>
; __device__ __forceinline__ void gemm_phase(PG8_LAS unsigned char* lds, const Gemm g, const Sched& S, const Epi& E) {
;     ...
;         for (int t = 0; t < nt; t += 2) {
;     ...
;             PG8_LDB(B0, 1, 0); PG8_LDB(B1, 1, 1); PG8_SCHED; PG8_LDA(At, 1, 0); PG8_STAGE(PG8_SA(0, 1), a2 + hstep, voffA);
;             PG8_WAIT_V(8); PG8_WAIT_L(0); PG8_BAR; PG8_MMA(0, 0, At, B0); PG8_MMA(0, 1, At, B1); PG8_BAR; PG8_SCHED;
;             PG8_LDA(At, 1, 1); PG8_STAGE(PG8_SB(1, 0), b3, voffB); PG8_STAGE(PG8_SB(1, 1), b3 + hstep, voffB); PG8_STAGE(PG8_SA(1, 0), a3, voffA);
;             PG8_WAIT_V(8); PG8_WAIT_L(0); PG8_BAR; PG8_MMA(1, 0, At, B0); PG8_MMA(1, 1, At, B1); PG8_BAR; PG8_SCHED;
	v_mfma_f32_16x16x32_bf16 v[124:127], v[148:151], v[194:197], v[124:127]
	v_mfma_f32_16x16x32_bf16 v[120:123], v[170:173], v[194:197], v[120:123]
	v_mfma_f32_16x16x32_bf16 v[108:111], v[148:151], v[202:205], v[108:111]
	v_mfma_f32_16x16x32_bf16 v[104:107], v[170:173], v[202:205], v[104:107]
	v_mfma_f32_16x16x32_bf16 v[92:95], v[148:151], v[210:213], v[92:95]
	v_mfma_f32_16x16x32_bf16 v[88:91], v[170:173], v[210:213], v[88:91]
	v_mfma_f32_16x16x32_bf16 v[76:79], v[148:151], v[218:221], v[76:79]
	v_mfma_f32_16x16x32_bf16 v[72:75], v[170:173], v[218:221], v[72:75]
	v_mfma_f32_16x16x32_bf16 v[124:127], v[166:169], v[198:201], v[124:127]
	v_mfma_f32_16x16x32_bf16 v[120:123], v[174:177], v[198:201], v[120:123]
	v_mfma_f32_16x16x32_bf16 v[108:111], v[166:169], v[206:209], v[108:111]
	v_mfma_f32_16x16x32_bf16 v[104:107], v[174:177], v[206:209], v[104:107]
	v_mfma_f32_16x16x32_bf16 v[92:95], v[166:169], v[214:217], v[92:95]
	v_mfma_f32_16x16x32_bf16 v[88:91], v[174:177], v[214:217], v[88:91]
	v_mfma_f32_16x16x32_bf16 v[76:79], v[166:169], v[222:225], v[76:79]
	v_mfma_f32_16x16x32_bf16 v[72:75], v[174:177], v[222:225], v[72:75]
	v_mfma_f32_16x16x32_bf16 v[116:119], v[178:181], v[194:197], v[116:119]
	v_mfma_f32_16x16x32_bf16 v[112:115], v[186:189], v[194:197], v[112:115]
	v_mfma_f32_16x16x32_bf16 v[100:103], v[178:181], v[202:205], v[100:103]
	v_mfma_f32_16x16x32_bf16 v[96:99], v[186:189], v[202:205], v[96:99]
	v_mfma_f32_16x16x32_bf16 v[84:87], v[178:181], v[210:213], v[84:87]
	v_mfma_f32_16x16x32_bf16 v[80:83], v[186:189], v[210:213], v[80:83]
	v_mfma_f32_16x16x32_bf16 v[68:71], v[178:181], v[218:221], v[68:71]
	v_mfma_f32_16x16x32_bf16 v[64:67], v[186:189], v[218:221], v[64:67]
	v_mfma_f32_16x16x32_bf16 v[116:119], v[182:185], v[198:201], v[116:119]
	v_mfma_f32_16x16x32_bf16 v[112:115], v[190:193], v[198:201], v[112:115]
	v_mfma_f32_16x16x32_bf16 v[100:103], v[182:185], v[206:209], v[100:103]
	v_mfma_f32_16x16x32_bf16 v[96:99], v[190:193], v[206:209], v[96:99]
	v_mfma_f32_16x16x32_bf16 v[84:87], v[182:185], v[214:217], v[84:87]
	v_mfma_f32_16x16x32_bf16 v[80:83], v[190:193], v[214:217], v[80:83]
	v_mfma_f32_16x16x32_bf16 v[68:71], v[182:185], v[222:225], v[68:71]
	v_mfma_f32_16x16x32_bf16 v[64:67], v[190:193], v[222:225], v[64:67]
	s_barrier
	s_setprio 0
	s_add_i32 s42, s71, s33
	v_lshl_add_u64 v[226:227], v[226:227], 0, s[24:25]
	s_mov_b32 m0, s42
	s_nop 0
	global_load_lds_dwordx4 v[226:227], off
	s_add_i32 m0, s42, 0x2000
	s_add_u32 s40, s40, 0x40080
	v_lshl_add_u64 v[226:227], v[228:229], 0, s[24:25]
	s_addc_u32 s41, s41, 0
	s_add_i32 s42, s72, s33
	global_load_lds_dwordx4 v[226:227], off
	v_lshl_add_u64 v[226:227], s[40:41], 0, v[138:139]
	s_mov_b32 m0, s42
	s_nop 0
	global_load_lds_dwordx4 v[226:227], off
	v_lshl_add_u64 v[226:227], s[40:41], 0, v[142:143]
	s_add_i32 m0, s42, 0x2000
	s_nop 0
	global_load_lds_dwordx4 v[226:227], off
	v_lshl_add_u64 v[226:227], v[230:231], 0, s[24:25]
	s_mov_b32 m0, s57
	s_nop 0
	global_load_lds_dwordx4 v[226:227], off
	v_lshl_add_u64 v[226:227], v[232:233], 0, s[24:25]
	s_mov_b32 m0, s58
	s_nop 0
	global_load_lds_dwordx4 v[226:227], off
	ds_read_b128 v[194:197], v164 offset:49152
	ds_read_b128 v[198:201], v164 offset:50176
	ds_read_b128 v[202:205], v164 offset:51200
	ds_read_b128 v[206:209], v164 offset:52224
	ds_read_b128 v[210:213], v164 offset:53248
	ds_read_b128 v[214:217], v164 offset:54272
	ds_read_b128 v[218:221], v164 offset:55296
	ds_read_b128 v[222:225], v164 offset:56320
	s_waitcnt vmcnt(8)
	s_waitcnt lgkmcnt(0)
	s_setprio 1
	s_barrier
	v_mfma_f32_16x16x32_bf16 v[60:63], v[148:151], v[194:197], v[60:63]
	v_mfma_f32_16x16x32_bf16 v[56:59], v[170:173], v[194:197], v[56:59]
	v_mfma_f32_16x16x32_bf16 v[44:47], v[148:151], v[202:205], v[44:47]
	v_mfma_f32_16x16x32_bf16 v[40:43], v[170:173], v[202:205], v[40:43]
	v_mfma_f32_16x16x32_bf16 v[28:31], v[148:151], v[210:213], v[28:31]
	v_mfma_f32_16x16x32_bf16 v[24:27], v[170:173], v[210:213], v[24:27]
	v_mfma_f32_16x16x32_bf16 v[12:15], v[148:151], v[218:221], v[12:15]
	v_mfma_f32_16x16x32_bf16 v[8:11], v[170:173], v[218:221], v[8:11]
	v_mfma_f32_16x16x32_bf16 v[60:63], v[166:169], v[198:201], v[60:63]
	v_mfma_f32_16x16x32_bf16 v[56:59], v[174:177], v[198:201], v[56:59]
	v_mfma_f32_16x16x32_bf16 v[44:47], v[166:169], v[206:209], v[44:47]
	v_mfma_f32_16x16x32_bf16 v[40:43], v[174:177], v[206:209], v[40:43]
	v_mfma_f32_16x16x32_bf16 v[28:31], v[166:169], v[214:217], v[28:31]
	v_mfma_f32_16x16x32_bf16 v[24:27], v[174:177], v[214:217], v[24:27]
	v_mfma_f32_16x16x32_bf16 v[12:15], v[166:169], v[222:225], v[12:15]
	v_mfma_f32_16x16x32_bf16 v[8:11], v[174:177], v[222:225], v[8:11]
	v_mfma_f32_16x16x32_bf16 v[52:55], v[178:181], v[194:197], v[52:55]
	v_mfma_f32_16x16x32_bf16 v[48:51], v[186:189], v[194:197], v[48:51]
	v_mfma_f32_16x16x32_bf16 v[36:39], v[178:181], v[202:205], v[36:39]
	v_mfma_f32_16x16x32_bf16 v[32:35], v[186:189], v[202:205], v[32:35]
	v_mfma_f32_16x16x32_bf16 v[20:23], v[178:181], v[210:213], v[20:23]
	v_mfma_f32_16x16x32_bf16 v[16:19], v[186:189], v[210:213], v[16:19]
	v_mfma_f32_16x16x32_bf16 v[4:7], v[178:181], v[218:221], v[4:7]
	v_mfma_f32_16x16x32_bf16 v[0:3], v[186:189], v[218:221], v[0:3]
	v_mfma_f32_16x16x32_bf16 v[52:55], v[182:185], v[198:201], v[52:55]
	v_mfma_f32_16x16x32_bf16 v[48:51], v[190:193], v[198:201], v[48:51]
	v_mfma_f32_16x16x32_bf16 v[36:39], v[182:185], v[206:209], v[36:39]
	v_mfma_f32_16x16x32_bf16 v[32:35], v[190:193], v[206:209], v[32:35]
	v_mfma_f32_16x16x32_bf16 v[20:23], v[182:185], v[214:217], v[20:23]
	v_mfma_f32_16x16x32_bf16 v[16:19], v[190:193], v[214:217], v[16:19]
	v_mfma_f32_16x16x32_bf16 v[4:7], v[182:185], v[222:225], v[4:7]
	v_mfma_f32_16x16x32_bf16 v[0:3], v[190:193], v[222:225], v[0:3]
	s_barrier
	s_setprio 0
	s_add_i32 s70, s70, 2
	s_add_u32 s38, s38, 0x100
	s_addc_u32 s39, s39, 0
	s_add_u32 s44, s44, 0x100
	s_addc_u32 s45, s45, 0
	s_cmp_gt_u32 s70, 13
	s_cbranch_scc0 .LBB0_509
	s_and_b64 vcc, exec, s[26:27]
	s_cbranch_vccz .LBB0_512
	s_barrier

; #define PG8_STAGE(bufoff, gbase, voff) do { _Pragma("unroll") for (int _i = 0; _i < 2; ++_i) \
;         __builtin_amdgcn_global_load_lds((const unsigned*)((const char*)(gbase) + (voff)[_i]), (PG8_LAS unsigned*)(lds + (bufoff) + ldsw + _i * 8192), 16, 0, 0); } while (0)
; #define PG8_LDA(dst, b, h) do { _Pragma("unroll") for (int m = 0; m < 4; ++m) _Pragma("unroll") for (int k = 0; k < 2; ++k) dst[m][k] = *(const PG8_LAS bf16x8*)(lds + PG8_SA(b, h) + aoff + m * 2048 + k * 1024); } while (0)
; template <class Epi, class Sched, bool ALIGN_EPI = false, bool SP2 = false>
; __device__ __forceinline__ void gemm_phase(PG8_LAS unsigned char* lds, const Gemm g, const Sched& S, const Epi& E) {
;     ...
;         const bool has_next = S.next(ui + 1, nxt);
;         const char* nA = has_next ? (const char*)g.A + (size_t)nxt.pm * tstep : cA; const char* nB = has_next ? (const char*)g.Bt + (size_t)nxt.pn * tstep : cB;
;         for (int t = 0; t < nt; t += 2) {
;             const bool last = (t == nt - 2);
;             const char* a1 = cA + (size_t)(t + 1) * kstep;
;             const char* a2 = last ? nA : cA + (size_t)(t + 2) * kstep; const char* b2 = last ? nB : cB + (size_t)(t + 2) * kstep;
;             const char* a3 = a2 + kstep; const char* b3 = b2 + kstep;
;             if (last && has_next) S.a_ready(nxt, ui + 1);
;             if constexpr (SP2) {
;             PG8_LDB(B0, 0, 0); PG8_LDB(B1, 0, 1); PG8_SCHED; PG8_LDA(At, 0, 0); PG8_STAGE(PG8_SA(1, 1), a1 + hstep, voffA);
;             PG8_WAIT_V(8); PG8_WAIT_L(0); PG8_BAR; PG8_MMA(0, 0, At, B0); PG8_MMA(0, 1, At, B1); PG8_BAR; PG8_SCHED;
;             PG8_LDA(At, 0, 1); PG8_STAGE(PG8_SB(0, 0), b2, voffB); PG8_STAGE(PG8_SB(0, 1), b2 + hstep, voffB); PG8_STAGE(PG8_SA(0, 0), a2, voffA);
;             PG8_WAIT_V(8); PG8_WAIT_L(0); PG8_BAR; PG8_MMA(1, 0, At, B0); PG8_MMA(1, 1, At, B1); PG8_BAR; PG8_SCHED;
;             PG8_LDB(B0, 1, 0); PG8_LDB(B1, 1, 1); PG8_SCHED; PG8_LDA(At, 1, 0); PG8_STAGE(PG8_SA(0, 1), a2 + hstep, voffA);
;             PG8_WAIT_V(8); PG8_WAIT_L(0); PG8_BAR; PG8_MMA(0, 0, At, B0); PG8_MMA(0, 1, At, B1); PG8_BAR; PG8_SCHED;
;             PG8_LDA(At, 1, 1); PG8_STAGE(PG8_SB(1, 0), b3, voffB); PG8_STAGE(PG8_SB(1, 1), b3 + hstep, voffB); PG8_STAGE(PG8_SA(1, 0), a3, voffA);
;             PG8_WAIT_V(8); PG8_WAIT_L(0); PG8_BAR; PG8_MMA(1, 0, At, B0); PG8_MMA(1, 1, At, B1); PG8_BAR; PG8_SCHED;
.LBB0_606:
	s_ashr_i32 s21, s20, 31
	s_lshl_b64 s[22:23], s[20:21], 19
	s_add_u32 s22, s36, s22
	s_addc_u32 s23, s37, s23
	s_and_b64 s[24:25], s[4:5], exec
	s_cselect_b32 s21, s23, s29
	s_cselect_b32 s55, s22, s28
	s_ashr_i32 s19, s18, 31
	s_lshl_b64 s[24:25], s[18:19], 19
	s_add_u32 s24, s48, s24
	s_addc_u32 s25, s49, s25
	s_and_b64 s[34:35], s[4:5], exec
	s_cselect_b32 s19, s25, s31
	s_cselect_b32 s56, s24, s30
	s_add_u32 s28, s28, 0x40080
	s_addc_u32 s29, s29, 0
	s_add_u32 s57, s30, 0x100
	s_addc_u32 s58, s31, 0
	s_mov_b32 s59, -2
	s_add_u32 s30, s28, 0xfffc0080
	s_addc_u32 s31, s29, -1
	s_cmp_eq_u32 s59, 12
	s_cselect_b32 s35, s21, s31
	s_cselect_b32 s34, s55, s30
	s_cselect_b32 s31, s19, s58
	s_cselect_b32 s30, s56, s57
	v_lshl_add_u64 v[160:161], s[28:29], 0, v[152:153]
	s_add_i32 m0, s38, 0xc000
	s_nop 0
	global_load_lds_dwordx4 v[160:161], off
	v_lshl_add_u64 v[160:161], s[28:29], 0, v[154:155]
	s_add_i32 m0, s38, 0xe000
	s_nop 0
	global_load_lds_dwordx4 v[160:161], off
	s_waitcnt vmcnt(8)
	s_waitcnt lgkmcnt(0)
	s_setprio 1
	s_barrier
	v_mfma_f32_16x16x32_bf16 v[124:127], v[128:131], v[198:201], 0
	v_mfma_f32_16x16x32_bf16 v[120:123], v[174:177], v[198:201], 0
	v_mfma_f32_16x16x32_bf16 v[116:119], v[128:131], v[206:209], 0
	v_mfma_f32_16x16x32_bf16 v[112:115], v[174:177], v[206:209], 0
	v_mfma_f32_16x16x32_bf16 v[108:111], v[128:131], v[214:217], 0
	v_mfma_f32_16x16x32_bf16 v[104:107], v[174:177], v[214:217], 0
	v_mfma_f32_16x16x32_bf16 v[100:103], v[128:131], v[222:225], 0
	v_mfma_f32_16x16x32_bf16 v[96:99], v[174:177], v[222:225], 0
	v_mfma_f32_16x16x32_bf16 v[124:127], v[132:135], v[202:205], v[124:127]
	v_mfma_f32_16x16x32_bf16 v[120:123], v[178:181], v[202:205], v[120:123]
	v_mfma_f32_16x16x32_bf16 v[116:119], v[132:135], v[210:213], v[116:119]
	v_mfma_f32_16x16x32_bf16 v[112:115], v[178:181], v[210:213], v[112:115]
	v_mfma_f32_16x16x32_bf16 v[108:111], v[132:135], v[218:221], v[108:111]
	v_mfma_f32_16x16x32_bf16 v[104:107], v[178:181], v[218:221], v[104:107]
	v_mfma_f32_16x16x32_bf16 v[100:103], v[132:135], v[226:229], v[100:103]
	v_mfma_f32_16x16x32_bf16 v[96:99], v[178:181], v[226:229], v[96:99]
	v_mfma_f32_16x16x32_bf16 v[60:63], v[182:185], v[198:201], 0
	v_mfma_f32_16x16x32_bf16 v[56:59], v[190:193], v[198:201], 0
	v_mfma_f32_16x16x32_bf16 v[52:55], v[182:185], v[206:209], 0
	v_mfma_f32_16x16x32_bf16 v[48:51], v[190:193], v[206:209], 0
	v_mfma_f32_16x16x32_bf16 v[44:47], v[182:185], v[214:217], 0
	v_mfma_f32_16x16x32_bf16 v[40:43], v[190:193], v[214:217], 0
	v_mfma_f32_16x16x32_bf16 v[36:39], v[182:185], v[222:225], 0
	v_mfma_f32_16x16x32_bf16 v[32:35], v[190:193], v[222:225], 0
	v_mfma_f32_16x16x32_bf16 v[60:63], v[186:189], v[202:205], v[60:63]
	v_mfma_f32_16x16x32_bf16 v[56:59], v[194:197], v[202:205], v[56:59]
	v_mfma_f32_16x16x32_bf16 v[52:55], v[186:189], v[210:213], v[52:55]
	v_mfma_f32_16x16x32_bf16 v[48:51], v[194:197], v[210:213], v[48:51]
	v_mfma_f32_16x16x32_bf16 v[44:47], v[186:189], v[218:221], v[44:47]
	v_mfma_f32_16x16x32_bf16 v[40:43], v[194:197], v[218:221], v[40:43]
	v_mfma_f32_16x16x32_bf16 v[36:39], v[186:189], v[226:229], v[36:39]
	v_mfma_f32_16x16x32_bf16 v[32:35], v[194:197], v[226:229], v[32:35]
	s_barrier
	s_setprio 0
	s_add_i32 s60, s45, s33
	v_lshl_add_u64 v[160:161], s[30:31], 0, v[138:139]
	s_mov_b32 m0, s60
	s_nop 0
	global_load_lds_dwordx4 v[160:161], off
	s_add_i32 m0, s60, 0x2000
	s_add_u32 s60, s30, 0x40000
	v_lshl_add_u64 v[230:231], s[30:31], 0, v[142:143]
	s_addc_u32 s61, s31, 0
	s_add_i32 s62, s50, s33
	global_load_lds_dwordx4 v[230:231], off
	v_lshl_add_u64 v[232:233], s[60:61], 0, v[138:139]
	s_mov_b32 m0, s62
	v_lshl_add_u64 v[234:235], s[34:35], 0, v[140:141]
	global_load_lds_dwordx4 v[232:233], off
	v_lshl_add_u64 v[232:233], s[60:61], 0, v[142:143]
	s_add_i32 m0, s62, 0x2000
	s_nop 0
	global_load_lds_dwordx4 v[232:233], off
	v_lshl_add_u64 v[232:233], s[34:35], 0, v[136:137]
	s_mov_b32 m0, s38
	s_nop 0
	global_load_lds_dwordx4 v[232:233], off
	s_mov_b32 m0, s39
	s_nop 0
	global_load_lds_dwordx4 v[234:235], off
	ds_read_b128 v[198:201], v172 offset:16384
	ds_read_b128 v[202:205], v172 offset:17408
	ds_read_b128 v[206:209], v172 offset:18432
	ds_read_b128 v[210:213], v172 offset:19456
	ds_read_b128 v[214:217], v172 offset:20480
	ds_read_b128 v[218:221], v172 offset:21504
	ds_read_b128 v[222:225], v172 offset:22528
	ds_read_b128 v[226:229], v172 offset:23552
	s_waitcnt vmcnt(8)
	s_waitcnt lgkmcnt(0)
	s_setprio 1
	s_barrier
	v_mfma_f32_16x16x32_bf16 v[92:95], v[128:131], v[198:201], 0
	v_mfma_f32_16x16x32_bf16 v[88:91], v[174:177], v[198:201], 0
	v_mfma_f32_16x16x32_bf16 v[84:87], v[128:131], v[206:209], 0
	v_mfma_f32_16x16x32_bf16 v[80:83], v[174:177], v[206:209], 0
	v_mfma_f32_16x16x32_bf16 v[76:79], v[128:131], v[214:217], 0
	v_mfma_f32_16x16x32_bf16 v[72:75], v[174:177], v[214:217], 0
	v_mfma_f32_16x16x32_bf16 v[68:71], v[128:131], v[222:225], 0
	v_mfma_f32_16x16x32_bf16 v[64:67], v[174:177], v[222:225], 0
	v_mfma_f32_16x16x32_bf16 v[92:95], v[132:135], v[202:205], v[92:95]
	v_mfma_f32_16x16x32_bf16 v[88:91], v[178:181], v[202:205], v[88:91]
	v_mfma_f32_16x16x32_bf16 v[84:87], v[132:135], v[210:213], v[84:87]
	v_mfma_f32_16x16x32_bf16 v[80:83], v[178:181], v[210:213], v[80:83]
	v_mfma_f32_16x16x32_bf16 v[76:79], v[132:135], v[218:221], v[76:79]
	v_mfma_f32_16x16x32_bf16 v[72:75], v[178:181], v[218:221], v[72:75]
	v_mfma_f32_16x16x32_bf16 v[68:71], v[132:135], v[226:229], v[68:71]
	v_mfma_f32_16x16x32_bf16 v[64:67], v[178:181], v[226:229], v[64:67]
	v_mfma_f32_16x16x32_bf16 v[28:31], v[182:185], v[198:201], 0
	v_mfma_f32_16x16x32_bf16 v[24:27], v[190:193], v[198:201], 0
	v_mfma_f32_16x16x32_bf16 v[20:23], v[182:185], v[206:209], 0
	v_mfma_f32_16x16x32_bf16 v[16:19], v[190:193], v[206:209], 0
	v_mfma_f32_16x16x32_bf16 v[12:15], v[182:185], v[214:217], 0
	v_mfma_f32_16x16x32_bf16 v[8:11], v[190:193], v[214:217], 0
	v_mfma_f32_16x16x32_bf16 v[4:7], v[182:185], v[222:225], 0
	v_mfma_f32_16x16x32_bf16 v[0:3], v[190:193], v[222:225], 0
	v_mfma_f32_16x16x32_bf16 v[28:31], v[186:189], v[202:205], v[28:31]
	v_mfma_f32_16x16x32_bf16 v[24:27], v[194:197], v[202:205], v[24:27]
	v_mfma_f32_16x16x32_bf16 v[20:23], v[186:189], v[210:213], v[20:23]
	v_mfma_f32_16x16x32_bf16 v[16:19], v[194:197], v[210:213], v[16:19]
	v_mfma_f32_16x16x32_bf16 v[12:15], v[186:189], v[218:221], v[12:15]
	v_mfma_f32_16x16x32_bf16 v[8:11], v[194:197], v[218:221], v[8:11]
	v_mfma_f32_16x16x32_bf16 v[4:7], v[186:189], v[226:229], v[4:7]
	v_mfma_f32_16x16x32_bf16 v[0:3], v[194:197], v[226:229], v[0:3]
	s_barrier
; #define PG8_STAGE(bufoff, gbase, voff) do { _Pragma("unroll") for (int _i = 0; _i < 2; ++_i) \
;         __builtin_amdgcn_global_load_lds((const unsigned*)((const char*)(gbase) + (voff)[_i]), (PG8_LAS unsigned*)(lds + (bufoff) + ldsw + _i * 8192), 16, 0, 0); } while (0)
; #define PG8_LDA(dst, b, h) do { _Pragma("unroll") for (int m = 0; m < 4; ++m) _Pragma("unroll") for (int k = 0; k < 2; ++k) dst[m][k] = *(const PG8_LAS bf16x8*)(lds + PG8_SA(b, h) + aoff + m * 2048 + k * 1024); } while (0)
; #define PG8_LDB(dst, b, h) do { _Pragma("unroll") for (int n = 0; n < 2; ++n) _Pragma("unroll") for (int k = 0; k < 2; ++k) dst[n][k] = *(const PG8_LAS bf16x8*)(lds + PG8_SB(b, h) + boff + n * 2048 + k * 1024); } while (0)
; #define PG8_MMA(ai, bj, At, Bt) do { __builtin_amdgcn_s_setprio(1); _Pragma("unroll") for (int m = 0; m < 4; ++m) _Pragma("unroll") for (int n = 0; n < 2; ++n) _Pragma("unroll") for (int k = 0; k < 2; ++k) \
;         acc[ai][bj][m][n] = __builtin_amdgcn_mfma_f32_16x16x32_bf16(Bt[n][k], At[m][k], acc[ai][bj][m][n], 0, 0, 0); __builtin_amdgcn_s_setprio(0); } while (0)
; #define PG8_WAIT_V(n) asm volatile("s_waitcnt vmcnt(" #n ")" ::: "memory")
; #define PG8_WAIT_L(n) asm volatile("s_waitcnt lgkmcnt(" #n ")" ::: "memory")
; #define PG8_BAR __builtin_amdgcn_s_barrier()
; #define PG8_SCHED __builtin_amdgcn_sched_barrier(0)
; template <class Epi, class Sched, bool ALIGN_EPI = false, bool SP2 = false>
; __device__ __forceinline__ void gemm_phase(PG8_LAS unsigned char* lds, const Gemm g, const Sched& S, const Epi& E) {
;     ...
;             PG8_LDB(B0, 1, 0); PG8_LDB(B1, 1, 1); PG8_SCHED; PG8_LDA(At, 1, 0); PG8_STAGE(PG8_SA(0, 1), a2 + hstep, voffA);
;             PG8_WAIT_V(8); PG8_WAIT_L(0); PG8_BAR; PG8_MMA(0, 0, At, B0); PG8_MMA(0, 1, At, B1); PG8_BAR; PG8_SCHED;
;             PG8_LDA(At, 1, 1); PG8_STAGE(PG8_SB(1, 0), b3, voffB); PG8_STAGE(PG8_SB(1, 1), b3 + hstep, voffB); PG8_STAGE(PG8_SA(1, 0), a3, voffA);
;             PG8_WAIT_V(8); PG8_WAIT_L(0); PG8_BAR; PG8_MMA(1, 0, At, B0); PG8_MMA(1, 1, At, B1); PG8_BAR; PG8_SCHED;
	s_setprio 0
	s_add_i32 s60, 0, 0x18000
	s_add_i32 s61, 0, 0x1c000
	v_add_u32_e32 v178, s60, v163
	v_add_u32_e32 v194, s61, v163
	ds_read_b128 v[128:131], v178
	ds_read_b128 v[132:135], v178 offset:1024
	ds_read_b128 v[174:177], v178 offset:2048
	ds_read_b128 v[178:181], v178 offset:3072
	ds_read_b128 v[182:185], v194
	ds_read_b128 v[186:189], v194 offset:1024
	ds_read_b128 v[190:193], v194 offset:2048
	ds_read_b128 v[194:197], v194 offset:3072
	s_add_u32 s34, s34, 0x40000
	s_addc_u32 s35, s35, 0
	s_mov_b32 m0, s40
	v_lshl_add_u64 v[236:237], s[34:35], 0, v[136:137]
	ds_read_b128 v[198:201], v172 offset:32768
	ds_read_b128 v[202:205], v172 offset:33792
	ds_read_b128 v[206:209], v172 offset:34816
	ds_read_b128 v[210:213], v172 offset:35840
	ds_read_b128 v[214:217], v172 offset:36864
	ds_read_b128 v[218:221], v172 offset:37888
	ds_read_b128 v[222:225], v172 offset:38912
	ds_read_b128 v[226:229], v172 offset:39936
	global_load_lds_dwordx4 v[236:237], off
	v_lshl_add_u64 v[236:237], s[34:35], 0, v[140:141]
	s_mov_b32 m0, s41
	s_nop 0
	global_load_lds_dwordx4 v[236:237], off
	s_waitcnt vmcnt(8)
	s_waitcnt lgkmcnt(0)
	s_setprio 1
	s_barrier
	v_mfma_f32_16x16x32_bf16 v[124:127], v[128:131], v[198:201], v[124:127]
	v_mfma_f32_16x16x32_bf16 v[120:123], v[174:177], v[198:201], v[120:123]
	v_mfma_f32_16x16x32_bf16 v[116:119], v[128:131], v[206:209], v[116:119]
	v_mfma_f32_16x16x32_bf16 v[112:115], v[174:177], v[206:209], v[112:115]
	v_mfma_f32_16x16x32_bf16 v[108:111], v[128:131], v[214:217], v[108:111]
	v_mfma_f32_16x16x32_bf16 v[104:107], v[174:177], v[214:217], v[104:107]
	v_mfma_f32_16x16x32_bf16 v[100:103], v[128:131], v[222:225], v[100:103]
	v_mfma_f32_16x16x32_bf16 v[96:99], v[174:177], v[222:225], v[96:99]
	v_mfma_f32_16x16x32_bf16 v[124:127], v[132:135], v[202:205], v[124:127]
	v_mfma_f32_16x16x32_bf16 v[120:123], v[178:181], v[202:205], v[120:123]
	v_mfma_f32_16x16x32_bf16 v[116:119], v[132:135], v[210:213], v[116:119]
	v_mfma_f32_16x16x32_bf16 v[112:115], v[178:181], v[210:213], v[112:115]
	v_mfma_f32_16x16x32_bf16 v[108:111], v[132:135], v[218:221], v[108:111]
	v_mfma_f32_16x16x32_bf16 v[104:107], v[178:181], v[218:221], v[104:107]
	v_mfma_f32_16x16x32_bf16 v[100:103], v[132:135], v[226:229], v[100:103]
	v_mfma_f32_16x16x32_bf16 v[96:99], v[178:181], v[226:229], v[96:99]
	v_mfma_f32_16x16x32_bf16 v[60:63], v[182:185], v[198:201], v[60:63]
	v_mfma_f32_16x16x32_bf16 v[56:59], v[190:193], v[198:201], v[56:59]
	v_mfma_f32_16x16x32_bf16 v[52:55], v[182:185], v[206:209], v[52:55]
	v_mfma_f32_16x16x32_bf16 v[48:51], v[190:193], v[206:209], v[48:51]
	v_mfma_f32_16x16x32_bf16 v[44:47], v[182:185], v[214:217], v[44:47]
	v_mfma_f32_16x16x32_bf16 v[40:43], v[190:193], v[214:217], v[40:43]
	v_mfma_f32_16x16x32_bf16 v[36:39], v[182:185], v[222:225], v[36:39]
	v_mfma_f32_16x16x32_bf16 v[32:35], v[190:193], v[222:225], v[32:35]
	v_mfma_f32_16x16x32_bf16 v[60:63], v[186:189], v[202:205], v[60:63]
	v_mfma_f32_16x16x32_bf16 v[56:59], v[194:197], v[202:205], v[56:59]
	v_mfma_f32_16x16x32_bf16 v[52:55], v[186:189], v[210:213], v[52:55]
	v_mfma_f32_16x16x32_bf16 v[48:51], v[194:197], v[210:213], v[48:51]
	v_mfma_f32_16x16x32_bf16 v[44:47], v[186:189], v[218:221], v[44:47]
	v_mfma_f32_16x16x32_bf16 v[40:43], v[194:197], v[218:221], v[40:43]
	v_mfma_f32_16x16x32_bf16 v[36:39], v[186:189], v[226:229], v[36:39]
	v_mfma_f32_16x16x32_bf16 v[32:35], v[194:197], v[226:229], v[32:35]
	s_barrier
	s_setprio 0
	s_add_i32 s34, s60, s33
	v_lshl_add_u64 v[160:161], v[160:161], 0, s[16:17]
	s_mov_b32 m0, s34
	s_nop 0
	global_load_lds_dwordx4 v[160:161], off
	s_add_i32 m0, s34, 0x2000
	s_add_u32 s30, s30, 0x40080
	v_lshl_add_u64 v[160:161], v[230:231], 0, s[16:17]
	s_addc_u32 s31, s31, 0
	s_add_i32 s34, s61, s33
	global_load_lds_dwordx4 v[160:161], off
	v_lshl_add_u64 v[160:161], s[30:31], 0, v[138:139]
	s_mov_b32 m0, s34
	s_nop 0
	global_load_lds_dwordx4 v[160:161], off
	v_lshl_add_u64 v[160:161], s[30:31], 0, v[142:143]
	s_add_i32 m0, s34, 0x2000
	s_nop 0
	global_load_lds_dwordx4 v[160:161], off
	v_lshl_add_u64 v[160:161], v[232:233], 0, s[16:17]
	s_mov_b32 m0, s42
	s_nop 0
	global_load_lds_dwordx4 v[160:161], off
	v_lshl_add_u64 v[160:161], v[234:235], 0, s[16:17]
	s_mov_b32 m0, s43
	s_nop 0
	global_load_lds_dwordx4 v[160:161], off
	ds_read_b128 v[198:201], v172 offset:49152
	ds_read_b128 v[202:205], v172 offset:50176
	ds_read_b128 v[206:209], v172 offset:51200
	ds_read_b128 v[210:213], v172 offset:52224
	ds_read_b128 v[214:217], v172 offset:53248
	ds_read_b128 v[218:221], v172 offset:54272
	ds_read_b128 v[222:225], v172 offset:55296
	ds_read_b128 v[226:229], v172 offset:56320
	s_waitcnt vmcnt(8)
	s_waitcnt lgkmcnt(0)
	s_setprio 1
	s_barrier
; #define PG8_STAGE(bufoff, gbase, voff) do { _Pragma("unroll") for (int _i = 0; _i < 2; ++_i) \
;         __builtin_amdgcn_global_load_lds((const unsigned*)((const char*)(gbase) + (voff)[_i]), (PG8_LAS unsigned*)(lds + (bufoff) + ldsw + _i * 8192), 16, 0, 0); } while (0)
; #define PG8_LDA(dst, b, h) do { _Pragma("unroll") for (int m = 0; m < 4; ++m) _Pragma("unroll") for (int k = 0; k < 2; ++k) dst[m][k] = *(const PG8_LAS bf16x8*)(lds + PG8_SA(b, h) + aoff + m * 2048 + k * 1024); } while (0)
; #define PG8_LDB(dst, b, h) do { _Pragma("unroll") for (int n = 0; n < 2; ++n) _Pragma("unroll") for (int k = 0; k < 2; ++k) dst[n][k] = *(const PG8_LAS bf16x8*)(lds + PG8_SB(b, h) + boff + n * 2048 + k * 1024); } while (0)
; #define PG8_MMA(ai, bj, At, Bt) do { __builtin_amdgcn_s_setprio(1); _Pragma("unroll") for (int m = 0; m < 4; ++m) _Pragma("unroll") for (int n = 0; n < 2; ++n) _Pragma("unroll") for (int k = 0; k < 2; ++k) \
;         acc[ai][bj][m][n] = __builtin_amdgcn_mfma_f32_16x16x32_bf16(Bt[n][k], At[m][k], acc[ai][bj][m][n], 0, 0, 0); __builtin_amdgcn_s_setprio(0); } while (0)
; #define PG8_WAIT_V(n) asm volatile("s_waitcnt vmcnt(" #n ")" ::: "memory")
; #define PG8_BAR __builtin_amdgcn_s_barrier()
; template <class Epi, class Sched, bool ALIGN_EPI = false, bool SP2 = false>
; __device__ __forceinline__ void gemm_phase(PG8_LAS unsigned char* lds, const Gemm g, const Sched& S, const Epi& E) {
;     ...
;         for (int t = 0; t < nt; t += 2) {
;             const bool last = (t == nt - 2);
;             const char* a1 = cA + (size_t)(t + 1) * kstep;
;             const char* a2 = last ? nA : cA + (size_t)(t + 2) * kstep; const char* b2 = last ? nB : cB + (size_t)(t + 2) * kstep;
;             const char* a3 = a2 + kstep; const char* b3 = b2 + kstep;
;             if (last && has_next) S.a_ready(nxt, ui + 1);
;             if constexpr (SP2) {
;             PG8_LDB(B0, 0, 0); PG8_LDB(B1, 0, 1); PG8_SCHED; PG8_LDA(At, 0, 0); PG8_STAGE(PG8_SA(1, 1), a1 + hstep, voffA);
;             PG8_WAIT_V(8); PG8_WAIT_L(0); PG8_BAR; PG8_MMA(0, 0, At, B0); PG8_MMA(0, 1, At, B1); PG8_BAR; PG8_SCHED;
;             PG8_LDA(At, 0, 1); PG8_STAGE(PG8_SB(0, 0), b2, voffB); PG8_STAGE(PG8_SB(0, 1), b2 + hstep, voffB); PG8_STAGE(PG8_SA(0, 0), a2, voffA);
;             PG8_WAIT_V(8); PG8_WAIT_L(0); PG8_BAR; PG8_MMA(1, 0, At, B0); PG8_MMA(1, 1, At, B1); PG8_BAR; PG8_SCHED;
	v_mfma_f32_16x16x32_bf16 v[92:95], v[128:131], v[198:201], v[92:95]
	v_mfma_f32_16x16x32_bf16 v[88:91], v[174:177], v[198:201], v[88:91]
	v_mfma_f32_16x16x32_bf16 v[84:87], v[128:131], v[206:209], v[84:87]
	v_mfma_f32_16x16x32_bf16 v[80:83], v[174:177], v[206:209], v[80:83]
	v_mfma_f32_16x16x32_bf16 v[76:79], v[128:131], v[214:217], v[76:79]
	v_mfma_f32_16x16x32_bf16 v[72:75], v[174:177], v[214:217], v[72:75]
	v_mfma_f32_16x16x32_bf16 v[68:71], v[128:131], v[222:225], v[68:71]
	v_mfma_f32_16x16x32_bf16 v[64:67], v[174:177], v[222:225], v[64:67]
	v_mfma_f32_16x16x32_bf16 v[92:95], v[132:135], v[202:205], v[92:95]
	v_mfma_f32_16x16x32_bf16 v[88:91], v[178:181], v[202:205], v[88:91]
	v_mfma_f32_16x16x32_bf16 v[84:87], v[132:135], v[210:213], v[84:87]
	v_mfma_f32_16x16x32_bf16 v[80:83], v[178:181], v[210:213], v[80:83]
	v_mfma_f32_16x16x32_bf16 v[76:79], v[132:135], v[218:221], v[76:79]
	v_mfma_f32_16x16x32_bf16 v[72:75], v[178:181], v[218:221], v[72:75]
	v_mfma_f32_16x16x32_bf16 v[68:71], v[132:135], v[226:229], v[68:71]
	v_mfma_f32_16x16x32_bf16 v[64:67], v[178:181], v[226:229], v[64:67]
	v_mfma_f32_16x16x32_bf16 v[28:31], v[182:185], v[198:201], v[28:31]
	v_mfma_f32_16x16x32_bf16 v[24:27], v[190:193], v[198:201], v[24:27]
	v_mfma_f32_16x16x32_bf16 v[20:23], v[182:185], v[206:209], v[20:23]
	v_mfma_f32_16x16x32_bf16 v[16:19], v[190:193], v[206:209], v[16:19]
	v_mfma_f32_16x16x32_bf16 v[12:15], v[182:185], v[214:217], v[12:15]
	v_mfma_f32_16x16x32_bf16 v[8:11], v[190:193], v[214:217], v[8:11]
	v_mfma_f32_16x16x32_bf16 v[4:7], v[182:185], v[222:225], v[4:7]
	v_mfma_f32_16x16x32_bf16 v[0:3], v[190:193], v[222:225], v[0:3]
	v_mfma_f32_16x16x32_bf16 v[28:31], v[186:189], v[202:205], v[28:31]
	v_mfma_f32_16x16x32_bf16 v[24:27], v[194:197], v[202:205], v[24:27]
	v_mfma_f32_16x16x32_bf16 v[20:23], v[186:189], v[210:213], v[20:23]
	v_mfma_f32_16x16x32_bf16 v[16:19], v[194:197], v[210:213], v[16:19]
	v_mfma_f32_16x16x32_bf16 v[12:15], v[186:189], v[218:221], v[12:15]
	v_mfma_f32_16x16x32_bf16 v[8:11], v[194:197], v[218:221], v[8:11]
	v_mfma_f32_16x16x32_bf16 v[4:7], v[186:189], v[226:229], v[4:7]
	v_mfma_f32_16x16x32_bf16 v[0:3], v[194:197], v[226:229], v[0:3]
	s_barrier
	s_setprio 0
	s_add_i32 s59, s59, 2
	s_add_u32 s28, s28, 0x100
	s_addc_u32 s29, s29, 0
	s_add_u32 s57, s57, 0x100
	s_addc_u32 s58, s58, 0
	s_cmp_gt_u32 s59, 13
.LBB0_607:
	s_add_u32 s30, s28, 0xfffc0080
	s_addc_u32 s31, s29, -1
	s_cmp_eq_u32 s59, 12
	s_cselect_b32 s35, s21, s31
	s_cselect_b32 s34, s55, s30
	s_cselect_b32 s31, s19, s58
	s_cselect_b32 s30, s56, s57
	v_lshl_add_u64 v[160:161], s[28:29], 0, v[152:153]
	s_add_i32 m0, s38, 0xc000
	s_nop 0
	global_load_lds_dwordx4 v[160:161], off
	v_lshl_add_u64 v[160:161], s[28:29], 0, v[154:155]
	s_add_i32 m0, s38, 0xe000
	s_nop 0
	global_load_lds_dwordx4 v[160:161], off
	ds_read_b128 v[128:131], v170
	ds_read_b128 v[132:135], v170 offset:1024
	ds_read_b128 v[174:177], v170 offset:2048
	ds_read_b128 v[178:181], v170 offset:3072
	ds_read_b128 v[182:185], v171
	ds_read_b128 v[186:189], v171 offset:1024
	ds_read_b128 v[190:193], v171 offset:2048
	ds_read_b128 v[194:197], v171 offset:3072
	ds_read_b128 v[198:201], v172
	ds_read_b128 v[202:205], v172 offset:1024
	ds_read_b128 v[206:209], v172 offset:2048
	ds_read_b128 v[210:213], v172 offset:3072
	ds_read_b128 v[214:217], v172 offset:4096
	ds_read_b128 v[218:221], v172 offset:5120
	ds_read_b128 v[222:225], v172 offset:6144
	ds_read_b128 v[226:229], v172 offset:7168
	s_waitcnt vmcnt(8)
	s_waitcnt lgkmcnt(0)
	s_setprio 1
	s_barrier
	v_mfma_f32_16x16x32_bf16 v[124:127], v[128:131], v[198:201], v[124:127]
	v_mfma_f32_16x16x32_bf16 v[120:123], v[174:177], v[198:201], v[120:123]
	v_mfma_f32_16x16x32_bf16 v[116:119], v[128:131], v[206:209], v[116:119]
	v_mfma_f32_16x16x32_bf16 v[112:115], v[174:177], v[206:209], v[112:115]
	v_mfma_f32_16x16x32_bf16 v[108:111], v[128:131], v[214:217], v[108:111]
	v_mfma_f32_16x16x32_bf16 v[104:107], v[174:177], v[214:217], v[104:107]
	v_mfma_f32_16x16x32_bf16 v[100:103], v[128:131], v[222:225], v[100:103]
	v_mfma_f32_16x16x32_bf16 v[96:99], v[174:177], v[222:225], v[96:99]
	v_mfma_f32_16x16x32_bf16 v[124:127], v[132:135], v[202:205], v[124:127]
	v_mfma_f32_16x16x32_bf16 v[120:123], v[178:181], v[202:205], v[120:123]
	v_mfma_f32_16x16x32_bf16 v[116:119], v[132:135], v[210:213], v[116:119]
	v_mfma_f32_16x16x32_bf16 v[112:115], v[178:181], v[210:213], v[112:115]
	v_mfma_f32_16x16x32_bf16 v[108:111], v[132:135], v[218:221], v[108:111]
	v_mfma_f32_16x16x32_bf16 v[104:107], v[178:181], v[218:221], v[104:107]
	v_mfma_f32_16x16x32_bf16 v[100:103], v[132:135], v[226:229], v[100:103]
	v_mfma_f32_16x16x32_bf16 v[96:99], v[178:181], v[226:229], v[96:99]
	v_mfma_f32_16x16x32_bf16 v[60:63], v[182:185], v[198:201], v[60:63]
	v_mfma_f32_16x16x32_bf16 v[56:59], v[190:193], v[198:201], v[56:59]
	v_mfma_f32_16x16x32_bf16 v[52:55], v[182:185], v[206:209], v[52:55]
	v_mfma_f32_16x16x32_bf16 v[48:51], v[190:193], v[206:209], v[48:51]
	v_mfma_f32_16x16x32_bf16 v[44:47], v[182:185], v[214:217], v[44:47]
	v_mfma_f32_16x16x32_bf16 v[40:43], v[190:193], v[214:217], v[40:43]
	v_mfma_f32_16x16x32_bf16 v[36:39], v[182:185], v[222:225], v[36:39]
	v_mfma_f32_16x16x32_bf16 v[32:35], v[190:193], v[222:225], v[32:35]
	v_mfma_f32_16x16x32_bf16 v[60:63], v[186:189], v[202:205], v[60:63]
	v_mfma_f32_16x16x32_bf16 v[56:59], v[194:197], v[202:205], v[56:59]
	v_mfma_f32_16x16x32_bf16 v[52:55], v[186:189], v[210:213], v[52:55]
	v_mfma_f32_16x16x32_bf16 v[48:51], v[194:197], v[210:213], v[48:51]
	v_mfma_f32_16x16x32_bf16 v[44:47], v[186:189], v[218:221], v[44:47]
	v_mfma_f32_16x16x32_bf16 v[40:43], v[194:197], v[218:221], v[40:43]
	v_mfma_f32_16x16x32_bf16 v[36:39], v[186:189], v[226:229], v[36:39]
	v_mfma_f32_16x16x32_bf16 v[32:35], v[194:197], v[226:229], v[32:35]
	s_barrier
; #define PG8_STAGE(bufoff, gbase, voff) do { _Pragma("unroll") for (int _i = 0; _i < 2; ++_i) \
;         __builtin_amdgcn_global_load_lds((const unsigned*)((const char*)(gbase) + (voff)[_i]), (PG8_LAS unsigned*)(lds + (bufoff) + ldsw + _i * 8192), 16, 0, 0); } while (0)
; #define PG8_LDA(dst, b, h) do { _Pragma("unroll") for (int m = 0; m < 4; ++m) _Pragma("unroll") for (int k = 0; k < 2; ++k) dst[m][k] = *(const PG8_LAS bf16x8*)(lds + PG8_SA(b, h) + aoff + m * 2048 + k * 1024); } while (0)
; #define PG8_LDB(dst, b, h) do { _Pragma("unroll") for (int n = 0; n < 2; ++n) _Pragma("unroll") for (int k = 0; k < 2; ++k) dst[n][k] = *(const PG8_LAS bf16x8*)(lds + PG8_SB(b, h) + boff + n * 2048 + k * 1024); } while (0)
; #define PG8_MMA(ai, bj, At, Bt) do { __builtin_amdgcn_s_setprio(1); _Pragma("unroll") for (int m = 0; m < 4; ++m) _Pragma("unroll") for (int n = 0; n < 2; ++n) _Pragma("unroll") for (int k = 0; k < 2; ++k) \
;         acc[ai][bj][m][n] = __builtin_amdgcn_mfma_f32_16x16x32_bf16(Bt[n][k], At[m][k], acc[ai][bj][m][n], 0, 0, 0); __builtin_amdgcn_s_setprio(0); } while (0)
; #define PG8_WAIT_V(n) asm volatile("s_waitcnt vmcnt(" #n ")" ::: "memory")
; #define PG8_WAIT_L(n) asm volatile("s_waitcnt lgkmcnt(" #n ")" ::: "memory")
; #define PG8_BAR __builtin_amdgcn_s_barrier()
; #define PG8_SCHED __builtin_amdgcn_sched_barrier(0)
; template <class Epi, class Sched, bool ALIGN_EPI = false, bool SP2 = false>
; __device__ __forceinline__ void gemm_phase(PG8_LAS unsigned char* lds, const Gemm g, const Sched& S, const Epi& E) {
;     ...
;             PG8_LDA(At, 0, 1); PG8_STAGE(PG8_SB(0, 0), b2, voffB); PG8_STAGE(PG8_SB(0, 1), b2 + hstep, voffB); PG8_STAGE(PG8_SA(0, 0), a2, voffA);
;             PG8_WAIT_V(8); PG8_WAIT_L(0); PG8_BAR; PG8_MMA(1, 0, At, B0); PG8_MMA(1, 1, At, B1); PG8_BAR; PG8_SCHED;
;             PG8_LDB(B0, 1, 0); PG8_LDB(B1, 1, 1); PG8_SCHED; PG8_LDA(At, 1, 0); PG8_STAGE(PG8_SA(0, 1), a2 + hstep, voffA);
;             PG8_WAIT_V(8); PG8_WAIT_L(0); PG8_BAR; PG8_MMA(0, 0, At, B0); PG8_MMA(0, 1, At, B1); PG8_BAR; PG8_SCHED;
	s_setprio 0
	s_add_i32 s60, s45, s33
	v_lshl_add_u64 v[160:161], s[30:31], 0, v[138:139]
	s_mov_b32 m0, s60
	s_nop 0
	global_load_lds_dwordx4 v[160:161], off
	s_add_i32 m0, s60, 0x2000
	s_add_u32 s60, s30, 0x40000
	v_lshl_add_u64 v[230:231], s[30:31], 0, v[142:143]
	s_addc_u32 s61, s31, 0
	s_add_i32 s62, s50, s33
	global_load_lds_dwordx4 v[230:231], off
	v_lshl_add_u64 v[232:233], s[60:61], 0, v[138:139]
	s_mov_b32 m0, s62
	v_lshl_add_u64 v[234:235], s[34:35], 0, v[140:141]
	global_load_lds_dwordx4 v[232:233], off
	v_lshl_add_u64 v[232:233], s[60:61], 0, v[142:143]
	s_add_i32 m0, s62, 0x2000
	s_nop 0
	global_load_lds_dwordx4 v[232:233], off
	v_lshl_add_u64 v[232:233], s[34:35], 0, v[136:137]
	s_mov_b32 m0, s38
	s_nop 0
	global_load_lds_dwordx4 v[232:233], off
	s_mov_b32 m0, s39
	s_nop 0
	global_load_lds_dwordx4 v[234:235], off
	ds_read_b128 v[198:201], v172 offset:16384
	ds_read_b128 v[202:205], v172 offset:17408
	ds_read_b128 v[206:209], v172 offset:18432
	ds_read_b128 v[210:213], v172 offset:19456
	ds_read_b128 v[214:217], v172 offset:20480
	ds_read_b128 v[218:221], v172 offset:21504
	ds_read_b128 v[222:225], v172 offset:22528
	ds_read_b128 v[226:229], v172 offset:23552
	s_waitcnt vmcnt(8)
	s_waitcnt lgkmcnt(0)
	s_setprio 1
	s_barrier
	v_mfma_f32_16x16x32_bf16 v[92:95], v[128:131], v[198:201], v[92:95]
	v_mfma_f32_16x16x32_bf16 v[88:91], v[174:177], v[198:201], v[88:91]
	v_mfma_f32_16x16x32_bf16 v[84:87], v[128:131], v[206:209], v[84:87]
	v_mfma_f32_16x16x32_bf16 v[80:83], v[174:177], v[206:209], v[80:83]
	v_mfma_f32_16x16x32_bf16 v[76:79], v[128:131], v[214:217], v[76:79]
	v_mfma_f32_16x16x32_bf16 v[72:75], v[174:177], v[214:217], v[72:75]
	v_mfma_f32_16x16x32_bf16 v[68:71], v[128:131], v[222:225], v[68:71]
	v_mfma_f32_16x16x32_bf16 v[64:67], v[174:177], v[222:225], v[64:67]
	v_mfma_f32_16x16x32_bf16 v[92:95], v[132:135], v[202:205], v[92:95]
	v_mfma_f32_16x16x32_bf16 v[88:91], v[178:181], v[202:205], v[88:91]
	v_mfma_f32_16x16x32_bf16 v[84:87], v[132:135], v[210:213], v[84:87]
	v_mfma_f32_16x16x32_bf16 v[80:83], v[178:181], v[210:213], v[80:83]
	v_mfma_f32_16x16x32_bf16 v[76:79], v[132:135], v[218:221], v[76:79]
	v_mfma_f32_16x16x32_bf16 v[72:75], v[178:181], v[218:221], v[72:75]
	v_mfma_f32_16x16x32_bf16 v[68:71], v[132:135], v[226:229], v[68:71]
	v_mfma_f32_16x16x32_bf16 v[64:67], v[178:181], v[226:229], v[64:67]
	v_mfma_f32_16x16x32_bf16 v[28:31], v[182:185], v[198:201], v[28:31]
	v_mfma_f32_16x16x32_bf16 v[24:27], v[190:193], v[198:201], v[24:27]
	v_mfma_f32_16x16x32_bf16 v[20:23], v[182:185], v[206:209], v[20:23]
	v_mfma_f32_16x16x32_bf16 v[16:19], v[190:193], v[206:209], v[16:19]
	v_mfma_f32_16x16x32_bf16 v[12:15], v[182:185], v[214:217], v[12:15]
	v_mfma_f32_16x16x32_bf16 v[8:11], v[190:193], v[214:217], v[8:11]
	v_mfma_f32_16x16x32_bf16 v[4:7], v[182:185], v[222:225], v[4:7]
	v_mfma_f32_16x16x32_bf16 v[0:3], v[190:193], v[222:225], v[0:3]
	v_mfma_f32_16x16x32_bf16 v[28:31], v[186:189], v[202:205], v[28:31]
	v_mfma_f32_16x16x32_bf16 v[24:27], v[194:197], v[202:205], v[24:27]
	v_mfma_f32_16x16x32_bf16 v[20:23], v[186:189], v[210:213], v[20:23]
	v_mfma_f32_16x16x32_bf16 v[16:19], v[194:197], v[210:213], v[16:19]
	v_mfma_f32_16x16x32_bf16 v[12:15], v[186:189], v[218:221], v[12:15]
	v_mfma_f32_16x16x32_bf16 v[8:11], v[194:197], v[218:221], v[8:11]
	v_mfma_f32_16x16x32_bf16 v[4:7], v[186:189], v[226:229], v[4:7]
	v_mfma_f32_16x16x32_bf16 v[0:3], v[194:197], v[226:229], v[0:3]
	s_barrier
	s_setprio 0
	s_add_i32 s60, 0, 0x18000
	s_add_i32 s61, 0, 0x1c000
	v_add_u32_e32 v178, s60, v163
	v_add_u32_e32 v194, s61, v163
	ds_read_b128 v[128:131], v178
	ds_read_b128 v[132:135], v178 offset:1024
	ds_read_b128 v[174:177], v178 offset:2048
	ds_read_b128 v[178:181], v178 offset:3072
	ds_read_b128 v[182:185], v194
	ds_read_b128 v[186:189], v194 offset:1024
	ds_read_b128 v[190:193], v194 offset:2048
	ds_read_b128 v[194:197], v194 offset:3072
	s_add_u32 s34, s34, 0x40000
	s_addc_u32 s35, s35, 0
	s_mov_b32 m0, s40
	v_lshl_add_u64 v[236:237], s[34:35], 0, v[136:137]
	ds_read_b128 v[198:201], v172 offset:32768
	ds_read_b128 v[202:205], v172 offset:33792
	ds_read_b128 v[206:209], v172 offset:34816
	ds_read_b128 v[210:213], v172 offset:35840
	ds_read_b128 v[214:217], v172 offset:36864
	ds_read_b128 v[218:221], v172 offset:37888
	ds_read_b128 v[222:225], v172 offset:38912
	ds_read_b128 v[226:229], v172 offset:39936
	global_load_lds_dwordx4 v[236:237], off
	v_lshl_add_u64 v[236:237], s[34:35], 0, v[140:141]
	s_mov_b32 m0, s41
	s_nop 0
	global_load_lds_dwordx4 v[236:237], off
	s_waitcnt vmcnt(8)
	s_waitcnt lgkmcnt(0)
	s_setprio 1
	s_barrier
; #define PG8_STAGE(bufoff, gbase, voff) do { _Pragma("unroll") for (int _i = 0; _i < 2; ++_i) \
;         __builtin_amdgcn_global_load_lds((const unsigned*)((const char*)(gbase) + (voff)[_i]), (PG8_LAS unsigned*)(lds + (bufoff) + ldsw + _i * 8192), 16, 0, 0); } while (0)
; #define PG8_LDA(dst, b, h) do { _Pragma("unroll") for (int m = 0; m < 4; ++m) _Pragma("unroll") for (int k = 0; k < 2; ++k) dst[m][k] = *(const PG8_LAS bf16x8*)(lds + PG8_SA(b, h) + aoff + m * 2048 + k * 1024); } while (0)
; #define PG8_MMA(ai, bj, At, Bt) do { __builtin_amdgcn_s_setprio(1); _Pragma("unroll") for (int m = 0; m < 4; ++m) _Pragma("unroll") for (int n = 0; n < 2; ++n) _Pragma("unroll") for (int k = 0; k < 2; ++k) \
;         acc[ai][bj][m][n] = __builtin_amdgcn_mfma_f32_16x16x32_bf16(Bt[n][k], At[m][k], acc[ai][bj][m][n], 0, 0, 0); __builtin_amdgcn_s_setprio(0); } while (0)
; #define PG8_WAIT_V(n) asm volatile("s_waitcnt vmcnt(" #n ")" ::: "memory")
; #define PG8_WAIT_L(n) asm volatile("s_waitcnt lgkmcnt(" #n ")" ::: "memory")
; #define PG8_BAR __builtin_amdgcn_s_barrier()
; #define PG8_SCHED __builtin_amdgcn_sched_barrier(0)
; template <class Epi, class Sched, bool ALIGN_EPI = false, bool SP2 = false>
; __device__ __forceinline__ void gemm_phase(PG8_LAS unsigned char* lds, const Gemm g, const Sched& S, const Epi& E) {
;     ...
;             PG8_WAIT_V(8); PG8_WAIT_L(0); PG8_BAR; PG8_MMA(0, 0, At, B0); PG8_MMA(0, 1, At, B1); PG8_BAR; PG8_SCHED;
;             PG8_LDA(At, 1, 1); PG8_STAGE(PG8_SB(1, 0), b3, voffB); PG8_STAGE(PG8_SB(1, 1), b3 + hstep, voffB); PG8_STAGE(PG8_SA(1, 0), a3, voffA);
;             PG8_WAIT_V(8); PG8_WAIT_L(0); PG8_BAR; PG8_MMA(1, 0, At, B0); PG8_MMA(1, 1, At, B1); PG8_BAR; PG8_SCHED;
;     ...
;         if constexpr (ALIGN_EPI) { if (wr == 0) PG8_BAR; }
	v_mfma_f32_16x16x32_bf16 v[124:127], v[128:131], v[198:201], v[124:127]
	v_mfma_f32_16x16x32_bf16 v[120:123], v[174:177], v[198:201], v[120:123]
	v_mfma_f32_16x16x32_bf16 v[116:119], v[128:131], v[206:209], v[116:119]
	v_mfma_f32_16x16x32_bf16 v[112:115], v[174:177], v[206:209], v[112:115]
	v_mfma_f32_16x16x32_bf16 v[108:111], v[128:131], v[214:217], v[108:111]
	v_mfma_f32_16x16x32_bf16 v[104:107], v[174:177], v[214:217], v[104:107]
	v_mfma_f32_16x16x32_bf16 v[100:103], v[128:131], v[222:225], v[100:103]
	v_mfma_f32_16x16x32_bf16 v[96:99], v[174:177], v[222:225], v[96:99]
	v_mfma_f32_16x16x32_bf16 v[124:127], v[132:135], v[202:205], v[124:127]
	v_mfma_f32_16x16x32_bf16 v[120:123], v[178:181], v[202:205], v[120:123]
	v_mfma_f32_16x16x32_bf16 v[116:119], v[132:135], v[210:213], v[116:119]
	v_mfma_f32_16x16x32_bf16 v[112:115], v[178:181], v[210:213], v[112:115]
	v_mfma_f32_16x16x32_bf16 v[108:111], v[132:135], v[218:221], v[108:111]
	v_mfma_f32_16x16x32_bf16 v[104:107], v[178:181], v[218:221], v[104:107]
	v_mfma_f32_16x16x32_bf16 v[100:103], v[132:135], v[226:229], v[100:103]
	v_mfma_f32_16x16x32_bf16 v[96:99], v[178:181], v[226:229], v[96:99]
	v_mfma_f32_16x16x32_bf16 v[60:63], v[182:185], v[198:201], v[60:63]
	v_mfma_f32_16x16x32_bf16 v[56:59], v[190:193], v[198:201], v[56:59]
	v_mfma_f32_16x16x32_bf16 v[52:55], v[182:185], v[206:209], v[52:55]
	v_mfma_f32_16x16x32_bf16 v[48:51], v[190:193], v[206:209], v[48:51]
	v_mfma_f32_16x16x32_bf16 v[44:47], v[182:185], v[214:217], v[44:47]
	v_mfma_f32_16x16x32_bf16 v[40:43], v[190:193], v[214:217], v[40:43]
	v_mfma_f32_16x16x32_bf16 v[36:39], v[182:185], v[222:225], v[36:39]
	v_mfma_f32_16x16x32_bf16 v[32:35], v[190:193], v[222:225], v[32:35]
	v_mfma_f32_16x16x32_bf16 v[60:63], v[186:189], v[202:205], v[60:63]
	v_mfma_f32_16x16x32_bf16 v[56:59], v[194:197], v[202:205], v[56:59]
	v_mfma_f32_16x16x32_bf16 v[52:55], v[186:189], v[210:213], v[52:55]
	v_mfma_f32_16x16x32_bf16 v[48:51], v[194:197], v[210:213], v[48:51]
	v_mfma_f32_16x16x32_bf16 v[44:47], v[186:189], v[218:221], v[44:47]
	v_mfma_f32_16x16x32_bf16 v[40:43], v[194:197], v[218:221], v[40:43]
	v_mfma_f32_16x16x32_bf16 v[36:39], v[186:189], v[226:229], v[36:39]
	v_mfma_f32_16x16x32_bf16 v[32:35], v[194:197], v[226:229], v[32:35]
	s_barrier
	s_setprio 0
	s_add_i32 s34, s60, s33
	v_lshl_add_u64 v[160:161], v[160:161], 0, s[16:17]
	s_mov_b32 m0, s34
	s_nop 0
	global_load_lds_dwordx4 v[160:161], off
	s_add_i32 m0, s34, 0x2000
	s_add_u32 s30, s30, 0x40080
	v_lshl_add_u64 v[160:161], v[230:231], 0, s[16:17]
	s_addc_u32 s31, s31, 0
	s_add_i32 s34, s61, s33
	global_load_lds_dwordx4 v[160:161], off
	v_lshl_add_u64 v[160:161], s[30:31], 0, v[138:139]
	s_mov_b32 m0, s34
	s_nop 0
	global_load_lds_dwordx4 v[160:161], off
	v_lshl_add_u64 v[160:161], s[30:31], 0, v[142:143]
	s_add_i32 m0, s34, 0x2000
	s_nop 0
	global_load_lds_dwordx4 v[160:161], off
	v_lshl_add_u64 v[160:161], v[232:233], 0, s[16:17]
	s_mov_b32 m0, s42
	s_nop 0
	global_load_lds_dwordx4 v[160:161], off
	v_lshl_add_u64 v[160:161], v[234:235], 0, s[16:17]
	s_mov_b32 m0, s43
	s_nop 0
	global_load_lds_dwordx4 v[160:161], off
	ds_read_b128 v[198:201], v172 offset:49152
	ds_read_b128 v[202:205], v172 offset:50176
	ds_read_b128 v[206:209], v172 offset:51200
	ds_read_b128 v[210:213], v172 offset:52224
	ds_read_b128 v[214:217], v172 offset:53248
	ds_read_b128 v[218:221], v172 offset:54272
	ds_read_b128 v[222:225], v172 offset:55296
	ds_read_b128 v[226:229], v172 offset:56320
	s_waitcnt vmcnt(8)
	s_waitcnt lgkmcnt(0)
	s_setprio 1
	s_barrier
	v_mfma_f32_16x16x32_bf16 v[92:95], v[128:131], v[198:201], v[92:95]
	v_mfma_f32_16x16x32_bf16 v[88:91], v[174:177], v[198:201], v[88:91]
	v_mfma_f32_16x16x32_bf16 v[84:87], v[128:131], v[206:209], v[84:87]
	v_mfma_f32_16x16x32_bf16 v[80:83], v[174:177], v[206:209], v[80:83]
	v_mfma_f32_16x16x32_bf16 v[76:79], v[128:131], v[214:217], v[76:79]
	v_mfma_f32_16x16x32_bf16 v[72:75], v[174:177], v[214:217], v[72:75]
	v_mfma_f32_16x16x32_bf16 v[68:71], v[128:131], v[222:225], v[68:71]
	v_mfma_f32_16x16x32_bf16 v[64:67], v[174:177], v[222:225], v[64:67]
	v_mfma_f32_16x16x32_bf16 v[92:95], v[132:135], v[202:205], v[92:95]
	v_mfma_f32_16x16x32_bf16 v[88:91], v[178:181], v[202:205], v[88:91]
	v_mfma_f32_16x16x32_bf16 v[84:87], v[132:135], v[210:213], v[84:87]
	v_mfma_f32_16x16x32_bf16 v[80:83], v[178:181], v[210:213], v[80:83]
	v_mfma_f32_16x16x32_bf16 v[76:79], v[132:135], v[218:221], v[76:79]
	v_mfma_f32_16x16x32_bf16 v[72:75], v[178:181], v[218:221], v[72:75]
	v_mfma_f32_16x16x32_bf16 v[68:71], v[132:135], v[226:229], v[68:71]
	v_mfma_f32_16x16x32_bf16 v[64:67], v[178:181], v[226:229], v[64:67]
	v_mfma_f32_16x16x32_bf16 v[28:31], v[182:185], v[198:201], v[28:31]
	v_mfma_f32_16x16x32_bf16 v[24:27], v[190:193], v[198:201], v[24:27]
	v_mfma_f32_16x16x32_bf16 v[20:23], v[182:185], v[206:209], v[20:23]
	v_mfma_f32_16x16x32_bf16 v[16:19], v[190:193], v[206:209], v[16:19]
	v_mfma_f32_16x16x32_bf16 v[12:15], v[182:185], v[214:217], v[12:15]
	v_mfma_f32_16x16x32_bf16 v[8:11], v[190:193], v[214:217], v[8:11]
	v_mfma_f32_16x16x32_bf16 v[4:7], v[182:185], v[222:225], v[4:7]
	v_mfma_f32_16x16x32_bf16 v[0:3], v[190:193], v[222:225], v[0:3]
	v_mfma_f32_16x16x32_bf16 v[28:31], v[186:189], v[202:205], v[28:31]
	v_mfma_f32_16x16x32_bf16 v[24:27], v[194:197], v[202:205], v[24:27]
	v_mfma_f32_16x16x32_bf16 v[20:23], v[186:189], v[210:213], v[20:23]
	v_mfma_f32_16x16x32_bf16 v[16:19], v[194:197], v[210:213], v[16:19]
	v_mfma_f32_16x16x32_bf16 v[12:15], v[186:189], v[218:221], v[12:15]
	v_mfma_f32_16x16x32_bf16 v[8:11], v[194:197], v[218:221], v[8:11]
	v_mfma_f32_16x16x32_bf16 v[4:7], v[186:189], v[226:229], v[4:7]
	v_mfma_f32_16x16x32_bf16 v[0:3], v[194:197], v[226:229], v[0:3]
	s_barrier
	s_setprio 0
	s_add_i32 s59, s59, 2
	s_add_u32 s28, s28, 0x100
	s_addc_u32 s29, s29, 0
	s_add_u32 s57, s57, 0x100
	s_addc_u32 s58, s58, 0
	s_cmp_gt_u32 s59, 13
	s_cbranch_scc0 .LBB0_607
	s_and_b64 vcc, exec, s[0:1]
	s_cbranch_vccz .LBB0_610
	s_barrier

; #define PG8_STAGE(bufoff, gbase, voff) do { _Pragma("unroll") for (int _i = 0; _i < 2; ++_i) \
;         __builtin_amdgcn_global_load_lds((const unsigned*)((const char*)(gbase) + (voff)[_i]), (PG8_LAS unsigned*)(lds + (bufoff) + ldsw + _i * 8192), 16, 0, 0); } while (0)
; #define PG8_LDA(dst, b, h) do { _Pragma("unroll") for (int m = 0; m < 4; ++m) _Pragma("unroll") for (int k = 0; k < 2; ++k) dst[m][k] = *(const PG8_LAS bf16x8*)(lds + PG8_SA(b, h) + aoff + m * 2048 + k * 1024); } while (0)
; #define PG8_LDB(dst, b, h) do { _Pragma("unroll") for (int n = 0; n < 2; ++n) _Pragma("unroll") for (int k = 0; k < 2; ++k) dst[n][k] = *(const PG8_LAS bf16x8*)(lds + PG8_SB(b, h) + boff + n * 2048 + k * 1024); } while (0)
; #define PG8_WAIT_V(n) asm volatile("s_waitcnt vmcnt(" #n ")" ::: "memory")
; #define PG8_WAIT_L(n) asm volatile("s_waitcnt lgkmcnt(" #n ")" ::: "memory")
; #define PG8_BAR __builtin_amdgcn_s_barrier()
; #define PG8_SCHED __builtin_amdgcn_sched_barrier(0)
; template <class Epi, class Sched, bool ALIGN_EPI = false, bool SP2 = false>
; __device__ __forceinline__ void gemm_phase(PG8_LAS unsigned char* lds, const Gemm g, const Sched& S, const Epi& E) {
;     ...
;         const char* nA = has_next ? (const char*)g.A + (size_t)nxt.pm * tstep : cA; const char* nB = has_next ? (const char*)g.Bt + (size_t)nxt.pn * tstep : cB;
;         for (int t = 0; t < nt; t += 2) {
;             const bool last = (t == nt - 2);
;             const char* a1 = cA + (size_t)(t + 1) * kstep;
;             const char* a2 = last ? nA : cA + (size_t)(t + 2) * kstep; const char* b2 = last ? nB : cB + (size_t)(t + 2) * kstep;
;             const char* a3 = a2 + kstep; const char* b3 = b2 + kstep;
;             if (last && has_next) S.a_ready(nxt, ui + 1);
;             if constexpr (SP2) {
;             PG8_LDB(B0, 0, 0); PG8_LDB(B1, 0, 1); PG8_SCHED; PG8_LDA(At, 0, 0); PG8_STAGE(PG8_SA(1, 1), a1 + hstep, voffA);
;             PG8_WAIT_V(8); PG8_WAIT_L(0); PG8_BAR; PG8_MMA(0, 0, At, B0); PG8_MMA(0, 1, At, B1); PG8_BAR; PG8_SCHED;
;             PG8_LDA(At, 0, 1); PG8_STAGE(PG8_SB(0, 0), b2, voffB); PG8_STAGE(PG8_SB(0, 1), b2 + hstep, voffB); PG8_STAGE(PG8_SA(0, 0), a2, voffA);
;             PG8_WAIT_V(8); PG8_WAIT_L(0); PG8_BAR; PG8_MMA(1, 0, At, B0); PG8_MMA(1, 1, At, B1); PG8_BAR; PG8_SCHED;
.LBB0_959:
	s_ashr_i32 s23, s22, 31
	s_lshl_b64 s[24:25], s[22:23], 19
	s_add_u32 s24, s3, s24
	s_addc_u32 s25, s33, s25
	s_and_b64 s[26:27], s[4:5], exec
	s_cselect_b32 s23, s25, s31
	s_cselect_b32 s29, s24, s30
	s_ashr_i32 s21, s20, 31
	s_lshl_b64 s[26:27], s[20:21], 19
	s_add_u32 s26, s38, s26
	s_addc_u32 s27, s39, s27
	s_and_b64 s[36:37], s[4:5], exec
	s_cselect_b32 s21, s27, s35
	s_cselect_b32 s54, s26, s34
	s_add_u32 s30, s30, 0x40080
	s_addc_u32 s31, s31, 0
	s_add_u32 s55, s34, 0x100
	s_addc_u32 s56, s35, 0
	s_mov_b32 s57, -2
	s_add_u32 s34, s30, 0xfffc0080
	s_addc_u32 s35, s31, -1
	s_cmp_eq_u32 s57, 12
	s_cselect_b32 s37, s23, s35
	s_cselect_b32 s36, s29, s34
	s_cselect_b32 s35, s21, s56
	s_cselect_b32 s34, s54, s55
	s_add_i32 m0, s41, 0xc000
	s_nop 0
	global_load_lds_dwordx4 v200, s[30:31]
	s_add_i32 m0, s41, 0xe000
	s_nop 0
	global_load_lds_dwordx4 v202, s[30:31]
	s_waitcnt vmcnt(8)
	s_waitcnt lgkmcnt(0)
	s_setprio 1
	s_barrier
	v_mfma_f32_16x16x32_bf16 v[132:135], v[120:123], v[160:163], 0
	v_mfma_f32_16x16x32_bf16 v[124:127], v[136:139], v[160:163], 0
	v_mfma_f32_16x16x32_bf16 v[108:111], v[120:123], v[168:171], 0
	v_mfma_f32_16x16x32_bf16 v[104:107], v[136:139], v[168:171], 0
	v_mfma_f32_16x16x32_bf16 v[92:95], v[120:123], v[176:179], 0
	v_mfma_f32_16x16x32_bf16 v[88:91], v[136:139], v[176:179], 0
	v_mfma_f32_16x16x32_bf16 v[76:79], v[120:123], v[184:187], 0
	v_mfma_f32_16x16x32_bf16 v[72:75], v[136:139], v[184:187], 0
	v_mfma_f32_16x16x32_bf16 v[132:135], v[128:131], v[164:167], v[132:135]
	v_mfma_f32_16x16x32_bf16 v[124:127], v[140:143], v[164:167], v[124:127]
	v_mfma_f32_16x16x32_bf16 v[108:111], v[128:131], v[172:175], v[108:111]
	v_mfma_f32_16x16x32_bf16 v[104:107], v[140:143], v[172:175], v[104:107]
	v_mfma_f32_16x16x32_bf16 v[92:95], v[128:131], v[180:183], v[92:95]
	v_mfma_f32_16x16x32_bf16 v[88:91], v[140:143], v[180:183], v[88:91]
	v_mfma_f32_16x16x32_bf16 v[76:79], v[128:131], v[188:191], v[76:79]
	v_mfma_f32_16x16x32_bf16 v[72:75], v[140:143], v[188:191], v[72:75]
	v_mfma_f32_16x16x32_bf16 v[116:119], v[144:147], v[160:163], 0
	v_mfma_f32_16x16x32_bf16 v[112:115], v[152:155], v[160:163], 0
	v_mfma_f32_16x16x32_bf16 v[100:103], v[144:147], v[168:171], 0
	v_mfma_f32_16x16x32_bf16 v[96:99], v[152:155], v[168:171], 0
	v_mfma_f32_16x16x32_bf16 v[84:87], v[144:147], v[176:179], 0
	v_mfma_f32_16x16x32_bf16 v[80:83], v[152:155], v[176:179], 0
	v_mfma_f32_16x16x32_bf16 v[68:71], v[144:147], v[184:187], 0
	v_mfma_f32_16x16x32_bf16 v[64:67], v[152:155], v[184:187], 0
	v_mfma_f32_16x16x32_bf16 v[116:119], v[148:151], v[164:167], v[116:119]
	v_mfma_f32_16x16x32_bf16 v[112:115], v[156:159], v[164:167], v[112:115]
	v_mfma_f32_16x16x32_bf16 v[100:103], v[148:151], v[172:175], v[100:103]
	v_mfma_f32_16x16x32_bf16 v[96:99], v[156:159], v[172:175], v[96:99]
	v_mfma_f32_16x16x32_bf16 v[84:87], v[148:151], v[180:183], v[84:87]
	v_mfma_f32_16x16x32_bf16 v[80:83], v[156:159], v[180:183], v[80:83]
	v_mfma_f32_16x16x32_bf16 v[68:71], v[148:151], v[188:191], v[68:71]
	v_mfma_f32_16x16x32_bf16 v[64:67], v[156:159], v[188:191], v[64:67]
	s_barrier
	s_setprio 0
	s_add_i32 s58, s51, s40
	v_lshl_add_u64 v[204:205], s[34:35], 0, v[194:195]
	s_mov_b32 m0, s58
	s_nop 0
	global_load_lds_dwordx4 v[204:205], off
	s_add_i32 m0, s58, 0x2000
	s_add_u32 s58, s34, 0x40000
	v_lshl_add_u64 v[206:207], s[34:35], 0, v[198:199]
	s_addc_u32 s59, s35, 0
	s_add_i32 s60, s52, s40
	global_load_lds_dwordx4 v[206:207], off
	s_mov_b32 m0, s60
	v_lshl_add_u64 v[210:211], s[36:37], 0, v[196:197]
	global_load_lds_dwordx4 v194, s[58:59]
	s_add_i32 m0, s60, 0x2000
	s_nop 0
	global_load_lds_dwordx4 v198, s[58:59]
	v_lshl_add_u64 v[208:209], s[36:37], 0, v[192:193]
	s_mov_b32 m0, s41
	s_nop 0
	global_load_lds_dwordx4 v[208:209], off
	s_mov_b32 m0, s42
	s_nop 0
	global_load_lds_dwordx4 v[210:211], off
	ds_read_b128 v[160:163], v247 offset:16384
	ds_read_b128 v[164:167], v247 offset:17408
	ds_read_b128 v[168:171], v247 offset:18432
	ds_read_b128 v[172:175], v247 offset:19456
	ds_read_b128 v[176:179], v247 offset:20480
	ds_read_b128 v[180:183], v247 offset:21504
	ds_read_b128 v[184:187], v247 offset:22528
	ds_read_b128 v[188:191], v247 offset:23552
	s_waitcnt vmcnt(8)
	s_waitcnt lgkmcnt(0)
	s_setprio 1
	s_barrier
	v_mfma_f32_16x16x32_bf16 v[60:63], v[120:123], v[160:163], 0
	v_mfma_f32_16x16x32_bf16 v[56:59], v[136:139], v[160:163], 0
	v_mfma_f32_16x16x32_bf16 v[44:47], v[120:123], v[168:171], 0
	v_mfma_f32_16x16x32_bf16 v[40:43], v[136:139], v[168:171], 0
	v_mfma_f32_16x16x32_bf16 v[28:31], v[120:123], v[176:179], 0
	v_mfma_f32_16x16x32_bf16 v[24:27], v[136:139], v[176:179], 0
	v_mfma_f32_16x16x32_bf16 v[12:15], v[120:123], v[184:187], 0
	v_mfma_f32_16x16x32_bf16 v[8:11], v[136:139], v[184:187], 0
	v_mfma_f32_16x16x32_bf16 v[60:63], v[128:131], v[164:167], v[60:63]
	v_mfma_f32_16x16x32_bf16 v[56:59], v[140:143], v[164:167], v[56:59]
	v_mfma_f32_16x16x32_bf16 v[44:47], v[128:131], v[172:175], v[44:47]
	v_mfma_f32_16x16x32_bf16 v[40:43], v[140:143], v[172:175], v[40:43]
	v_mfma_f32_16x16x32_bf16 v[28:31], v[128:131], v[180:183], v[28:31]
	v_mfma_f32_16x16x32_bf16 v[24:27], v[140:143], v[180:183], v[24:27]
	v_mfma_f32_16x16x32_bf16 v[12:15], v[128:131], v[188:191], v[12:15]
	v_mfma_f32_16x16x32_bf16 v[8:11], v[140:143], v[188:191], v[8:11]
	v_mfma_f32_16x16x32_bf16 v[52:55], v[144:147], v[160:163], 0
	v_mfma_f32_16x16x32_bf16 v[48:51], v[152:155], v[160:163], 0
	v_mfma_f32_16x16x32_bf16 v[36:39], v[144:147], v[168:171], 0
	v_mfma_f32_16x16x32_bf16 v[32:35], v[152:155], v[168:171], 0
	v_mfma_f32_16x16x32_bf16 v[20:23], v[144:147], v[176:179], 0
	v_mfma_f32_16x16x32_bf16 v[16:19], v[152:155], v[176:179], 0
	v_mfma_f32_16x16x32_bf16 v[4:7], v[144:147], v[184:187], 0
	v_mfma_f32_16x16x32_bf16 v[0:3], v[152:155], v[184:187], 0
	v_mfma_f32_16x16x32_bf16 v[52:55], v[148:151], v[164:167], v[52:55]
	v_mfma_f32_16x16x32_bf16 v[48:51], v[156:159], v[164:167], v[48:51]
	v_mfma_f32_16x16x32_bf16 v[36:39], v[148:151], v[172:175], v[36:39]
	v_mfma_f32_16x16x32_bf16 v[32:35], v[156:159], v[172:175], v[32:35]
	v_mfma_f32_16x16x32_bf16 v[20:23], v[148:151], v[180:183], v[20:23]
	v_mfma_f32_16x16x32_bf16 v[16:19], v[156:159], v[180:183], v[16:19]
	v_mfma_f32_16x16x32_bf16 v[4:7], v[148:151], v[188:191], v[4:7]
	v_mfma_f32_16x16x32_bf16 v[0:3], v[156:159], v[188:191], v[0:3]
	s_barrier
; #define PG8_STAGE(bufoff, gbase, voff) do { _Pragma("unroll") for (int _i = 0; _i < 2; ++_i) \
;         __builtin_amdgcn_global_load_lds((const unsigned*)((const char*)(gbase) + (voff)[_i]), (PG8_LAS unsigned*)(lds + (bufoff) + ldsw + _i * 8192), 16, 0, 0); } while (0)
; #define PG8_LDA(dst, b, h) do { _Pragma("unroll") for (int m = 0; m < 4; ++m) _Pragma("unroll") for (int k = 0; k < 2; ++k) dst[m][k] = *(const PG8_LAS bf16x8*)(lds + PG8_SA(b, h) + aoff + m * 2048 + k * 1024); } while (0)
; #define PG8_LDB(dst, b, h) do { _Pragma("unroll") for (int n = 0; n < 2; ++n) _Pragma("unroll") for (int k = 0; k < 2; ++k) dst[n][k] = *(const PG8_LAS bf16x8*)(lds + PG8_SB(b, h) + boff + n * 2048 + k * 1024); } while (0)
; #define PG8_MMA(ai, bj, At, Bt) do { __builtin_amdgcn_s_setprio(1); _Pragma("unroll") for (int m = 0; m < 4; ++m) _Pragma("unroll") for (int n = 0; n < 2; ++n) _Pragma("unroll") for (int k = 0; k < 2; ++k) \
;         acc[ai][bj][m][n] = __builtin_amdgcn_mfma_f32_16x16x32_bf16(Bt[n][k], At[m][k], acc[ai][bj][m][n], 0, 0, 0); __builtin_amdgcn_s_setprio(0); } while (0)
; #define PG8_WAIT_V(n) asm volatile("s_waitcnt vmcnt(" #n ")" ::: "memory")
; #define PG8_WAIT_L(n) asm volatile("s_waitcnt lgkmcnt(" #n ")" ::: "memory")
; #define PG8_BAR __builtin_amdgcn_s_barrier()
; #define PG8_SCHED __builtin_amdgcn_sched_barrier(0)
; template <class Epi, class Sched, bool ALIGN_EPI = false, bool SP2 = false>
; __device__ __forceinline__ void gemm_phase(PG8_LAS unsigned char* lds, const Gemm g, const Sched& S, const Epi& E) {
;     ...
;             PG8_LDB(B0, 1, 0); PG8_LDB(B1, 1, 1); PG8_SCHED; PG8_LDA(At, 1, 0); PG8_STAGE(PG8_SA(0, 1), a2 + hstep, voffA);
;             PG8_WAIT_V(8); PG8_WAIT_L(0); PG8_BAR; PG8_MMA(0, 0, At, B0); PG8_MMA(0, 1, At, B1); PG8_BAR; PG8_SCHED;
;             PG8_LDA(At, 1, 1); PG8_STAGE(PG8_SB(1, 0), b3, voffB); PG8_STAGE(PG8_SB(1, 1), b3 + hstep, voffB); PG8_STAGE(PG8_SA(1, 0), a3, voffA);
;             PG8_WAIT_V(8); PG8_WAIT_L(0); PG8_BAR; PG8_MMA(1, 0, At, B0); PG8_MMA(1, 1, At, B1); PG8_BAR; PG8_SCHED;
	s_setprio 0
	s_add_i32 s58, 0, 0x18000
	s_add_i32 s59, 0, 0x1c000
	v_add_u32_e32 v140, s58, v243
	v_add_u32_e32 v156, s59, v243
	ds_read_b128 v[120:123], v140
	ds_read_b128 v[128:131], v140 offset:1024
	ds_read_b128 v[136:139], v140 offset:2048
	ds_read_b128 v[140:143], v140 offset:3072
	ds_read_b128 v[144:147], v156
	ds_read_b128 v[148:151], v156 offset:1024
	ds_read_b128 v[152:155], v156 offset:2048
	ds_read_b128 v[156:159], v156 offset:3072
	s_add_u32 s36, s36, 0x40000
	s_addc_u32 s37, s37, 0
	s_mov_b32 m0, s43
	ds_read_b128 v[160:163], v247 offset:32768
	ds_read_b128 v[164:167], v247 offset:33792
	ds_read_b128 v[168:171], v247 offset:34816
	ds_read_b128 v[172:175], v247 offset:35840
	ds_read_b128 v[176:179], v247 offset:36864
	ds_read_b128 v[180:183], v247 offset:37888
	ds_read_b128 v[184:187], v247 offset:38912
	ds_read_b128 v[188:191], v247 offset:39936
	global_load_lds_dwordx4 v192, s[36:37]
	s_mov_b32 m0, s44
	s_nop 0
	global_load_lds_dwordx4 v196, s[36:37]
	s_waitcnt vmcnt(8)
	s_waitcnt lgkmcnt(0)
	s_setprio 1
	s_barrier
	v_mfma_f32_16x16x32_bf16 v[132:135], v[120:123], v[160:163], v[132:135]
	v_mfma_f32_16x16x32_bf16 v[124:127], v[136:139], v[160:163], v[124:127]
	v_mfma_f32_16x16x32_bf16 v[108:111], v[120:123], v[168:171], v[108:111]
	v_mfma_f32_16x16x32_bf16 v[104:107], v[136:139], v[168:171], v[104:107]
	v_mfma_f32_16x16x32_bf16 v[92:95], v[120:123], v[176:179], v[92:95]
	v_mfma_f32_16x16x32_bf16 v[88:91], v[136:139], v[176:179], v[88:91]
	v_mfma_f32_16x16x32_bf16 v[76:79], v[120:123], v[184:187], v[76:79]
	v_mfma_f32_16x16x32_bf16 v[72:75], v[136:139], v[184:187], v[72:75]
	v_mfma_f32_16x16x32_bf16 v[132:135], v[128:131], v[164:167], v[132:135]
	v_mfma_f32_16x16x32_bf16 v[124:127], v[140:143], v[164:167], v[124:127]
	v_mfma_f32_16x16x32_bf16 v[108:111], v[128:131], v[172:175], v[108:111]
	v_mfma_f32_16x16x32_bf16 v[104:107], v[140:143], v[172:175], v[104:107]
	v_mfma_f32_16x16x32_bf16 v[92:95], v[128:131], v[180:183], v[92:95]
	v_mfma_f32_16x16x32_bf16 v[88:91], v[140:143], v[180:183], v[88:91]
	v_mfma_f32_16x16x32_bf16 v[76:79], v[128:131], v[188:191], v[76:79]
	v_mfma_f32_16x16x32_bf16 v[72:75], v[140:143], v[188:191], v[72:75]
	v_mfma_f32_16x16x32_bf16 v[116:119], v[144:147], v[160:163], v[116:119]
	v_mfma_f32_16x16x32_bf16 v[112:115], v[152:155], v[160:163], v[112:115]
	v_mfma_f32_16x16x32_bf16 v[100:103], v[144:147], v[168:171], v[100:103]
	v_mfma_f32_16x16x32_bf16 v[96:99], v[152:155], v[168:171], v[96:99]
	v_mfma_f32_16x16x32_bf16 v[84:87], v[144:147], v[176:179], v[84:87]
	v_mfma_f32_16x16x32_bf16 v[80:83], v[152:155], v[176:179], v[80:83]
	v_mfma_f32_16x16x32_bf16 v[68:71], v[144:147], v[184:187], v[68:71]
	v_mfma_f32_16x16x32_bf16 v[64:67], v[152:155], v[184:187], v[64:67]
	v_mfma_f32_16x16x32_bf16 v[116:119], v[148:151], v[164:167], v[116:119]
	v_mfma_f32_16x16x32_bf16 v[112:115], v[156:159], v[164:167], v[112:115]
	v_mfma_f32_16x16x32_bf16 v[100:103], v[148:151], v[172:175], v[100:103]
	v_mfma_f32_16x16x32_bf16 v[96:99], v[156:159], v[172:175], v[96:99]
	v_mfma_f32_16x16x32_bf16 v[84:87], v[148:151], v[180:183], v[84:87]
	v_mfma_f32_16x16x32_bf16 v[80:83], v[156:159], v[180:183], v[80:83]
	v_mfma_f32_16x16x32_bf16 v[68:71], v[148:151], v[188:191], v[68:71]
	v_mfma_f32_16x16x32_bf16 v[64:67], v[156:159], v[188:191], v[64:67]
	s_barrier
	s_setprio 0
	s_add_i32 s36, s58, s40
	v_lshl_add_u64 v[204:205], v[204:205], 0, s[16:17]
	s_mov_b32 m0, s36
	s_nop 0
	global_load_lds_dwordx4 v[204:205], off
	s_add_i32 m0, s36, 0x2000
	s_add_u32 s34, s34, 0x40080
	v_lshl_add_u64 v[204:205], v[206:207], 0, s[16:17]
	s_addc_u32 s35, s35, 0
	s_add_i32 s36, s59, s40
	global_load_lds_dwordx4 v[204:205], off
	s_mov_b32 m0, s36
	s_nop 0
	global_load_lds_dwordx4 v194, s[34:35]
	s_add_i32 m0, s36, 0x2000
	s_nop 0
	global_load_lds_dwordx4 v198, s[34:35]
	v_lshl_add_u64 v[204:205], v[208:209], 0, s[16:17]
	s_mov_b32 m0, s46
	s_nop 0
	global_load_lds_dwordx4 v[204:205], off
	v_lshl_add_u64 v[204:205], v[210:211], 0, s[16:17]
	s_mov_b32 m0, s47
	s_nop 0
	global_load_lds_dwordx4 v[204:205], off
	ds_read_b128 v[160:163], v247 offset:49152
	ds_read_b128 v[164:167], v247 offset:50176
	ds_read_b128 v[168:171], v247 offset:51200
	ds_read_b128 v[172:175], v247 offset:52224
	ds_read_b128 v[176:179], v247 offset:53248
	ds_read_b128 v[180:183], v247 offset:54272
	ds_read_b128 v[184:187], v247 offset:55296
	ds_read_b128 v[188:191], v247 offset:56320
	s_waitcnt vmcnt(8)
	s_waitcnt lgkmcnt(0)
	s_setprio 1
	s_barrier
	v_mfma_f32_16x16x32_bf16 v[60:63], v[120:123], v[160:163], v[60:63]
	v_mfma_f32_16x16x32_bf16 v[56:59], v[136:139], v[160:163], v[56:59]
	v_mfma_f32_16x16x32_bf16 v[44:47], v[120:123], v[168:171], v[44:47]
	v_mfma_f32_16x16x32_bf16 v[40:43], v[136:139], v[168:171], v[40:43]
	v_mfma_f32_16x16x32_bf16 v[28:31], v[120:123], v[176:179], v[28:31]
	v_mfma_f32_16x16x32_bf16 v[24:27], v[136:139], v[176:179], v[24:27]
	v_mfma_f32_16x16x32_bf16 v[12:15], v[120:123], v[184:187], v[12:15]
	v_mfma_f32_16x16x32_bf16 v[8:11], v[136:139], v[184:187], v[8:11]
	v_mfma_f32_16x16x32_bf16 v[60:63], v[128:131], v[164:167], v[60:63]
	v_mfma_f32_16x16x32_bf16 v[56:59], v[140:143], v[164:167], v[56:59]
	v_mfma_f32_16x16x32_bf16 v[44:47], v[128:131], v[172:175], v[44:47]
	v_mfma_f32_16x16x32_bf16 v[40:43], v[140:143], v[172:175], v[40:43]
	v_mfma_f32_16x16x32_bf16 v[28:31], v[128:131], v[180:183], v[28:31]
	v_mfma_f32_16x16x32_bf16 v[24:27], v[140:143], v[180:183], v[24:27]
	v_mfma_f32_16x16x32_bf16 v[12:15], v[128:131], v[188:191], v[12:15]
	v_mfma_f32_16x16x32_bf16 v[8:11], v[140:143], v[188:191], v[8:11]
	v_mfma_f32_16x16x32_bf16 v[52:55], v[144:147], v[160:163], v[52:55]
	v_mfma_f32_16x16x32_bf16 v[48:51], v[152:155], v[160:163], v[48:51]
	v_mfma_f32_16x16x32_bf16 v[36:39], v[144:147], v[168:171], v[36:39]
	v_mfma_f32_16x16x32_bf16 v[32:35], v[152:155], v[168:171], v[32:35]
	v_mfma_f32_16x16x32_bf16 v[20:23], v[144:147], v[176:179], v[20:23]
	v_mfma_f32_16x16x32_bf16 v[16:19], v[152:155], v[176:179], v[16:19]
	v_mfma_f32_16x16x32_bf16 v[4:7], v[144:147], v[184:187], v[4:7]
	v_mfma_f32_16x16x32_bf16 v[0:3], v[152:155], v[184:187], v[0:3]
	v_mfma_f32_16x16x32_bf16 v[52:55], v[148:151], v[164:167], v[52:55]
	v_mfma_f32_16x16x32_bf16 v[48:51], v[156:159], v[164:167], v[48:51]
	v_mfma_f32_16x16x32_bf16 v[36:39], v[148:151], v[172:175], v[36:39]
	v_mfma_f32_16x16x32_bf16 v[32:35], v[156:159], v[172:175], v[32:35]
	v_mfma_f32_16x16x32_bf16 v[20:23], v[148:151], v[180:183], v[20:23]
	v_mfma_f32_16x16x32_bf16 v[16:19], v[156:159], v[180:183], v[16:19]
	v_mfma_f32_16x16x32_bf16 v[4:7], v[148:151], v[188:191], v[4:7]
	v_mfma_f32_16x16x32_bf16 v[0:3], v[156:159], v[188:191], v[0:3]
	s_barrier
	s_setprio 0
	s_add_i32 s57, s57, 2
	s_add_u32 s30, s30, 0x100
	s_addc_u32 s31, s31, 0
	s_add_u32 s55, s55, 0x100
	s_addc_u32 s56, s56, 0
	s_cmp_gt_u32 s57, 13
; #define PG8_STAGE(bufoff, gbase, voff) do { _Pragma("unroll") for (int _i = 0; _i < 2; ++_i) \
;         __builtin_amdgcn_global_load_lds((const unsigned*)((const char*)(gbase) + (voff)[_i]), (PG8_LAS unsigned*)(lds + (bufoff) + ldsw + _i * 8192), 16, 0, 0); } while (0)
; #define PG8_LDA(dst, b, h) do { _Pragma("unroll") for (int m = 0; m < 4; ++m) _Pragma("unroll") for (int k = 0; k < 2; ++k) dst[m][k] = *(const PG8_LAS bf16x8*)(lds + PG8_SA(b, h) + aoff + m * 2048 + k * 1024); } while (0)
; #define PG8_LDB(dst, b, h) do { _Pragma("unroll") for (int n = 0; n < 2; ++n) _Pragma("unroll") for (int k = 0; k < 2; ++k) dst[n][k] = *(const PG8_LAS bf16x8*)(lds + PG8_SB(b, h) + boff + n * 2048 + k * 1024); } while (0)
; #define PG8_MMA(ai, bj, At, Bt) do { __builtin_amdgcn_s_setprio(1); _Pragma("unroll") for (int m = 0; m < 4; ++m) _Pragma("unroll") for (int n = 0; n < 2; ++n) _Pragma("unroll") for (int k = 0; k < 2; ++k) \
;         acc[ai][bj][m][n] = __builtin_amdgcn_mfma_f32_16x16x32_bf16(Bt[n][k], At[m][k], acc[ai][bj][m][n], 0, 0, 0); __builtin_amdgcn_s_setprio(0); } while (0)
; #define PG8_WAIT_V(n) asm volatile("s_waitcnt vmcnt(" #n ")" ::: "memory")
; #define PG8_WAIT_L(n) asm volatile("s_waitcnt lgkmcnt(" #n ")" ::: "memory")
; template <class Epi, class Sched, bool ALIGN_EPI = false, bool SP2 = false>
; __device__ __forceinline__ void gemm_phase(PG8_LAS unsigned char* lds, const Gemm g, const Sched& S, const Epi& E) {
;     ...
;             const bool last = (t == nt - 2);
;             const char* a1 = cA + (size_t)(t + 1) * kstep;
;             const char* a2 = last ? nA : cA + (size_t)(t + 2) * kstep; const char* b2 = last ? nB : cB + (size_t)(t + 2) * kstep;
;             const char* a3 = a2 + kstep; const char* b3 = b2 + kstep;
;             if (last && has_next) S.a_ready(nxt, ui + 1);
;             if constexpr (SP2) {
;             PG8_LDB(B0, 0, 0); PG8_LDB(B1, 0, 1); PG8_SCHED; PG8_LDA(At, 0, 0); PG8_STAGE(PG8_SA(1, 1), a1 + hstep, voffA);
;             PG8_WAIT_V(8); PG8_WAIT_L(0); PG8_BAR; PG8_MMA(0, 0, At, B0); PG8_MMA(0, 1, At, B1); PG8_BAR; PG8_SCHED;
;             PG8_LDA(At, 0, 1); PG8_STAGE(PG8_SB(0, 0), b2, voffB); PG8_STAGE(PG8_SB(0, 1), b2 + hstep, voffB); PG8_STAGE(PG8_SA(0, 0), a2, voffA);
;             PG8_WAIT_V(8); PG8_WAIT_L(0); PG8_BAR; PG8_MMA(1, 0, At, B0); PG8_MMA(1, 1, At, B1); PG8_BAR; PG8_SCHED;
.LBB0_960:
	s_add_u32 s34, s30, 0xfffc0080
	s_addc_u32 s35, s31, -1
	s_cmp_eq_u32 s57, 12
	s_cselect_b32 s37, s23, s35
	s_cselect_b32 s36, s29, s34
	s_cselect_b32 s35, s21, s56
	s_cselect_b32 s34, s54, s55
	s_add_i32 m0, s41, 0xc000
	s_nop 0
	global_load_lds_dwordx4 v200, s[30:31]
	s_add_i32 m0, s41, 0xe000
	s_nop 0
	global_load_lds_dwordx4 v202, s[30:31]
	ds_read_b128 v[120:123], v245
	ds_read_b128 v[128:131], v245 offset:1024
	ds_read_b128 v[136:139], v245 offset:2048
	ds_read_b128 v[140:143], v245 offset:3072
	ds_read_b128 v[144:147], v246
	ds_read_b128 v[148:151], v246 offset:1024
	ds_read_b128 v[152:155], v246 offset:2048
	ds_read_b128 v[156:159], v246 offset:3072
	ds_read_b128 v[160:163], v247
	ds_read_b128 v[164:167], v247 offset:1024
	ds_read_b128 v[168:171], v247 offset:2048
	ds_read_b128 v[172:175], v247 offset:3072
	ds_read_b128 v[176:179], v247 offset:4096
	ds_read_b128 v[180:183], v247 offset:5120
	ds_read_b128 v[184:187], v247 offset:6144
	ds_read_b128 v[188:191], v247 offset:7168
	s_waitcnt vmcnt(8)
	s_waitcnt lgkmcnt(0)
	s_setprio 1
	s_barrier
	v_mfma_f32_16x16x32_bf16 v[132:135], v[120:123], v[160:163], v[132:135]
	v_mfma_f32_16x16x32_bf16 v[124:127], v[136:139], v[160:163], v[124:127]
	v_mfma_f32_16x16x32_bf16 v[108:111], v[120:123], v[168:171], v[108:111]
	v_mfma_f32_16x16x32_bf16 v[104:107], v[136:139], v[168:171], v[104:107]
	v_mfma_f32_16x16x32_bf16 v[92:95], v[120:123], v[176:179], v[92:95]
	v_mfma_f32_16x16x32_bf16 v[88:91], v[136:139], v[176:179], v[88:91]
	v_mfma_f32_16x16x32_bf16 v[76:79], v[120:123], v[184:187], v[76:79]
	v_mfma_f32_16x16x32_bf16 v[72:75], v[136:139], v[184:187], v[72:75]
	v_mfma_f32_16x16x32_bf16 v[132:135], v[128:131], v[164:167], v[132:135]
	v_mfma_f32_16x16x32_bf16 v[124:127], v[140:143], v[164:167], v[124:127]
	v_mfma_f32_16x16x32_bf16 v[108:111], v[128:131], v[172:175], v[108:111]
	v_mfma_f32_16x16x32_bf16 v[104:107], v[140:143], v[172:175], v[104:107]
	v_mfma_f32_16x16x32_bf16 v[92:95], v[128:131], v[180:183], v[92:95]
	v_mfma_f32_16x16x32_bf16 v[88:91], v[140:143], v[180:183], v[88:91]
	v_mfma_f32_16x16x32_bf16 v[76:79], v[128:131], v[188:191], v[76:79]
	v_mfma_f32_16x16x32_bf16 v[72:75], v[140:143], v[188:191], v[72:75]
	v_mfma_f32_16x16x32_bf16 v[116:119], v[144:147], v[160:163], v[116:119]
	v_mfma_f32_16x16x32_bf16 v[112:115], v[152:155], v[160:163], v[112:115]
	v_mfma_f32_16x16x32_bf16 v[100:103], v[144:147], v[168:171], v[100:103]
	v_mfma_f32_16x16x32_bf16 v[96:99], v[152:155], v[168:171], v[96:99]
	v_mfma_f32_16x16x32_bf16 v[84:87], v[144:147], v[176:179], v[84:87]
	v_mfma_f32_16x16x32_bf16 v[80:83], v[152:155], v[176:179], v[80:83]
	v_mfma_f32_16x16x32_bf16 v[68:71], v[144:147], v[184:187], v[68:71]
	v_mfma_f32_16x16x32_bf16 v[64:67], v[152:155], v[184:187], v[64:67]
	v_mfma_f32_16x16x32_bf16 v[116:119], v[148:151], v[164:167], v[116:119]
	v_mfma_f32_16x16x32_bf16 v[112:115], v[156:159], v[164:167], v[112:115]
	v_mfma_f32_16x16x32_bf16 v[100:103], v[148:151], v[172:175], v[100:103]
	v_mfma_f32_16x16x32_bf16 v[96:99], v[156:159], v[172:175], v[96:99]
	v_mfma_f32_16x16x32_bf16 v[84:87], v[148:151], v[180:183], v[84:87]
	v_mfma_f32_16x16x32_bf16 v[80:83], v[156:159], v[180:183], v[80:83]
	v_mfma_f32_16x16x32_bf16 v[68:71], v[148:151], v[188:191], v[68:71]
	v_mfma_f32_16x16x32_bf16 v[64:67], v[156:159], v[188:191], v[64:67]
	s_barrier
	s_setprio 0
	s_add_i32 s58, s51, s40
	v_lshl_add_u64 v[204:205], s[34:35], 0, v[194:195]
	s_mov_b32 m0, s58
	s_nop 0
	global_load_lds_dwordx4 v[204:205], off
	s_add_i32 m0, s58, 0x2000
	s_add_u32 s58, s34, 0x40000
	v_lshl_add_u64 v[206:207], s[34:35], 0, v[198:199]
	s_addc_u32 s59, s35, 0
	s_add_i32 s60, s52, s40
	global_load_lds_dwordx4 v[206:207], off
	s_mov_b32 m0, s60
	v_lshl_add_u64 v[210:211], s[36:37], 0, v[196:197]
	global_load_lds_dwordx4 v194, s[58:59]
	s_add_i32 m0, s60, 0x2000
	s_nop 0
	global_load_lds_dwordx4 v198, s[58:59]
	v_lshl_add_u64 v[208:209], s[36:37], 0, v[192:193]
	s_mov_b32 m0, s41
	s_nop 0
	global_load_lds_dwordx4 v[208:209], off
	s_mov_b32 m0, s42
	s_nop 0
	global_load_lds_dwordx4 v[210:211], off
	ds_read_b128 v[160:163], v247 offset:16384
	ds_read_b128 v[164:167], v247 offset:17408
	ds_read_b128 v[168:171], v247 offset:18432
	ds_read_b128 v[172:175], v247 offset:19456
	ds_read_b128 v[176:179], v247 offset:20480
	ds_read_b128 v[180:183], v247 offset:21504
	ds_read_b128 v[184:187], v247 offset:22528
	ds_read_b128 v[188:191], v247 offset:23552
	s_waitcnt vmcnt(8)
	s_waitcnt lgkmcnt(0)
	s_setprio 1
	s_barrier
	v_mfma_f32_16x16x32_bf16 v[60:63], v[120:123], v[160:163], v[60:63]
	v_mfma_f32_16x16x32_bf16 v[56:59], v[136:139], v[160:163], v[56:59]
	v_mfma_f32_16x16x32_bf16 v[44:47], v[120:123], v[168:171], v[44:47]
	v_mfma_f32_16x16x32_bf16 v[40:43], v[136:139], v[168:171], v[40:43]
	v_mfma_f32_16x16x32_bf16 v[28:31], v[120:123], v[176:179], v[28:31]
	v_mfma_f32_16x16x32_bf16 v[24:27], v[136:139], v[176:179], v[24:27]
	v_mfma_f32_16x16x32_bf16 v[12:15], v[120:123], v[184:187], v[12:15]
	v_mfma_f32_16x16x32_bf16 v[8:11], v[136:139], v[184:187], v[8:11]
	v_mfma_f32_16x16x32_bf16 v[60:63], v[128:131], v[164:167], v[60:63]
	v_mfma_f32_16x16x32_bf16 v[56:59], v[140:143], v[164:167], v[56:59]
	v_mfma_f32_16x16x32_bf16 v[44:47], v[128:131], v[172:175], v[44:47]
	v_mfma_f32_16x16x32_bf16 v[40:43], v[140:143], v[172:175], v[40:43]
	v_mfma_f32_16x16x32_bf16 v[28:31], v[128:131], v[180:183], v[28:31]
	v_mfma_f32_16x16x32_bf16 v[24:27], v[140:143], v[180:183], v[24:27]
	v_mfma_f32_16x16x32_bf16 v[12:15], v[128:131], v[188:191], v[12:15]
	v_mfma_f32_16x16x32_bf16 v[8:11], v[140:143], v[188:191], v[8:11]
	v_mfma_f32_16x16x32_bf16 v[52:55], v[144:147], v[160:163], v[52:55]
	v_mfma_f32_16x16x32_bf16 v[48:51], v[152:155], v[160:163], v[48:51]
	v_mfma_f32_16x16x32_bf16 v[36:39], v[144:147], v[168:171], v[36:39]
	v_mfma_f32_16x16x32_bf16 v[32:35], v[152:155], v[168:171], v[32:35]
	v_mfma_f32_16x16x32_bf16 v[20:23], v[144:147], v[176:179], v[20:23]
	v_mfma_f32_16x16x32_bf16 v[16:19], v[152:155], v[176:179], v[16:19]
	v_mfma_f32_16x16x32_bf16 v[4:7], v[144:147], v[184:187], v[4:7]
	v_mfma_f32_16x16x32_bf16 v[0:3], v[152:155], v[184:187], v[0:3]
	v_mfma_f32_16x16x32_bf16 v[52:55], v[148:151], v[164:167], v[52:55]
	v_mfma_f32_16x16x32_bf16 v[48:51], v[156:159], v[164:167], v[48:51]
	v_mfma_f32_16x16x32_bf16 v[36:39], v[148:151], v[172:175], v[36:39]
	v_mfma_f32_16x16x32_bf16 v[32:35], v[156:159], v[172:175], v[32:35]
	v_mfma_f32_16x16x32_bf16 v[20:23], v[148:151], v[180:183], v[20:23]
	v_mfma_f32_16x16x32_bf16 v[16:19], v[156:159], v[180:183], v[16:19]
	v_mfma_f32_16x16x32_bf16 v[4:7], v[148:151], v[188:191], v[4:7]
	v_mfma_f32_16x16x32_bf16 v[0:3], v[156:159], v[188:191], v[0:3]
	s_barrier
; #define PG8_STAGE(bufoff, gbase, voff) do { _Pragma("unroll") for (int _i = 0; _i < 2; ++_i) \
;         __builtin_amdgcn_global_load_lds((const unsigned*)((const char*)(gbase) + (voff)[_i]), (PG8_LAS unsigned*)(lds + (bufoff) + ldsw + _i * 8192), 16, 0, 0); } while (0)
; #define PG8_LDA(dst, b, h) do { _Pragma("unroll") for (int m = 0; m < 4; ++m) _Pragma("unroll") for (int k = 0; k < 2; ++k) dst[m][k] = *(const PG8_LAS bf16x8*)(lds + PG8_SA(b, h) + aoff + m * 2048 + k * 1024); } while (0)
; #define PG8_LDB(dst, b, h) do { _Pragma("unroll") for (int n = 0; n < 2; ++n) _Pragma("unroll") for (int k = 0; k < 2; ++k) dst[n][k] = *(const PG8_LAS bf16x8*)(lds + PG8_SB(b, h) + boff + n * 2048 + k * 1024); } while (0)
; #define PG8_MMA(ai, bj, At, Bt) do { __builtin_amdgcn_s_setprio(1); _Pragma("unroll") for (int m = 0; m < 4; ++m) _Pragma("unroll") for (int n = 0; n < 2; ++n) _Pragma("unroll") for (int k = 0; k < 2; ++k) \
;         acc[ai][bj][m][n] = __builtin_amdgcn_mfma_f32_16x16x32_bf16(Bt[n][k], At[m][k], acc[ai][bj][m][n], 0, 0, 0); __builtin_amdgcn_s_setprio(0); } while (0)
; #define PG8_WAIT_V(n) asm volatile("s_waitcnt vmcnt(" #n ")" ::: "memory")
; #define PG8_WAIT_L(n) asm volatile("s_waitcnt lgkmcnt(" #n ")" ::: "memory")
; #define PG8_BAR __builtin_amdgcn_s_barrier()
; #define PG8_SCHED __builtin_amdgcn_sched_barrier(0)
; template <class Epi, class Sched, bool ALIGN_EPI = false, bool SP2 = false>
; __device__ __forceinline__ void gemm_phase(PG8_LAS unsigned char* lds, const Gemm g, const Sched& S, const Epi& E) {
;     ...
;             PG8_LDB(B0, 1, 0); PG8_LDB(B1, 1, 1); PG8_SCHED; PG8_LDA(At, 1, 0); PG8_STAGE(PG8_SA(0, 1), a2 + hstep, voffA);
;             PG8_WAIT_V(8); PG8_WAIT_L(0); PG8_BAR; PG8_MMA(0, 0, At, B0); PG8_MMA(0, 1, At, B1); PG8_BAR; PG8_SCHED;
;             PG8_LDA(At, 1, 1); PG8_STAGE(PG8_SB(1, 0), b3, voffB); PG8_STAGE(PG8_SB(1, 1), b3 + hstep, voffB); PG8_STAGE(PG8_SA(1, 0), a3, voffA);
;             PG8_WAIT_V(8); PG8_WAIT_L(0); PG8_BAR; PG8_MMA(1, 0, At, B0); PG8_MMA(1, 1, At, B1); PG8_BAR; PG8_SCHED;
;     ...
;         if constexpr (ALIGN_EPI) { if (wr == 0) PG8_BAR; }
	s_setprio 0
	s_add_i32 s58, 0, 0x18000
	s_add_i32 s59, 0, 0x1c000
	v_add_u32_e32 v140, s58, v243
	v_add_u32_e32 v156, s59, v243
	ds_read_b128 v[120:123], v140
	ds_read_b128 v[128:131], v140 offset:1024
	ds_read_b128 v[136:139], v140 offset:2048
	ds_read_b128 v[140:143], v140 offset:3072
	ds_read_b128 v[144:147], v156
	ds_read_b128 v[148:151], v156 offset:1024
	ds_read_b128 v[152:155], v156 offset:2048
	ds_read_b128 v[156:159], v156 offset:3072
	s_add_u32 s36, s36, 0x40000
	s_addc_u32 s37, s37, 0
	s_mov_b32 m0, s43
	ds_read_b128 v[160:163], v247 offset:32768
	ds_read_b128 v[164:167], v247 offset:33792
	ds_read_b128 v[168:171], v247 offset:34816
	ds_read_b128 v[172:175], v247 offset:35840
	ds_read_b128 v[176:179], v247 offset:36864
	ds_read_b128 v[180:183], v247 offset:37888
	ds_read_b128 v[184:187], v247 offset:38912
	ds_read_b128 v[188:191], v247 offset:39936
	global_load_lds_dwordx4 v192, s[36:37]
	v_lshl_add_u64 v[212:213], s[36:37], 0, v[196:197]
	s_mov_b32 m0, s44
	s_nop 0
	global_load_lds_dwordx4 v[212:213], off
	s_waitcnt vmcnt(8)
	s_waitcnt lgkmcnt(0)
	s_setprio 1
	s_barrier
	v_mfma_f32_16x16x32_bf16 v[132:135], v[120:123], v[160:163], v[132:135]
	v_mfma_f32_16x16x32_bf16 v[124:127], v[136:139], v[160:163], v[124:127]
	v_mfma_f32_16x16x32_bf16 v[108:111], v[120:123], v[168:171], v[108:111]
	v_mfma_f32_16x16x32_bf16 v[104:107], v[136:139], v[168:171], v[104:107]
	v_mfma_f32_16x16x32_bf16 v[92:95], v[120:123], v[176:179], v[92:95]
	v_mfma_f32_16x16x32_bf16 v[88:91], v[136:139], v[176:179], v[88:91]
	v_mfma_f32_16x16x32_bf16 v[76:79], v[120:123], v[184:187], v[76:79]
	v_mfma_f32_16x16x32_bf16 v[72:75], v[136:139], v[184:187], v[72:75]
	v_mfma_f32_16x16x32_bf16 v[132:135], v[128:131], v[164:167], v[132:135]
	v_mfma_f32_16x16x32_bf16 v[124:127], v[140:143], v[164:167], v[124:127]
	v_mfma_f32_16x16x32_bf16 v[108:111], v[128:131], v[172:175], v[108:111]
	v_mfma_f32_16x16x32_bf16 v[104:107], v[140:143], v[172:175], v[104:107]
	v_mfma_f32_16x16x32_bf16 v[92:95], v[128:131], v[180:183], v[92:95]
	v_mfma_f32_16x16x32_bf16 v[88:91], v[140:143], v[180:183], v[88:91]
	v_mfma_f32_16x16x32_bf16 v[76:79], v[128:131], v[188:191], v[76:79]
	v_mfma_f32_16x16x32_bf16 v[72:75], v[140:143], v[188:191], v[72:75]
	v_mfma_f32_16x16x32_bf16 v[116:119], v[144:147], v[160:163], v[116:119]
	v_mfma_f32_16x16x32_bf16 v[112:115], v[152:155], v[160:163], v[112:115]
	v_mfma_f32_16x16x32_bf16 v[100:103], v[144:147], v[168:171], v[100:103]
	v_mfma_f32_16x16x32_bf16 v[96:99], v[152:155], v[168:171], v[96:99]
	v_mfma_f32_16x16x32_bf16 v[84:87], v[144:147], v[176:179], v[84:87]
	v_mfma_f32_16x16x32_bf16 v[80:83], v[152:155], v[176:179], v[80:83]
	v_mfma_f32_16x16x32_bf16 v[68:71], v[144:147], v[184:187], v[68:71]
	v_mfma_f32_16x16x32_bf16 v[64:67], v[152:155], v[184:187], v[64:67]
	v_mfma_f32_16x16x32_bf16 v[116:119], v[148:151], v[164:167], v[116:119]
	v_mfma_f32_16x16x32_bf16 v[112:115], v[156:159], v[164:167], v[112:115]
	v_mfma_f32_16x16x32_bf16 v[100:103], v[148:151], v[172:175], v[100:103]
	v_mfma_f32_16x16x32_bf16 v[96:99], v[156:159], v[172:175], v[96:99]
	v_mfma_f32_16x16x32_bf16 v[84:87], v[148:151], v[180:183], v[84:87]
	v_mfma_f32_16x16x32_bf16 v[80:83], v[156:159], v[180:183], v[80:83]
	v_mfma_f32_16x16x32_bf16 v[68:71], v[148:151], v[188:191], v[68:71]
	v_mfma_f32_16x16x32_bf16 v[64:67], v[156:159], v[188:191], v[64:67]
	s_barrier
	s_setprio 0
	s_add_i32 s36, s58, s40
	v_lshl_add_u64 v[204:205], v[204:205], 0, s[16:17]
	s_mov_b32 m0, s36
	s_nop 0
	global_load_lds_dwordx4 v[204:205], off
	s_add_i32 m0, s36, 0x2000
	s_add_u32 s34, s34, 0x40080
	v_lshl_add_u64 v[204:205], v[206:207], 0, s[16:17]
	s_addc_u32 s35, s35, 0
	s_add_i32 s36, s59, s40
	global_load_lds_dwordx4 v[204:205], off
	s_mov_b32 m0, s36
	s_nop 0
	global_load_lds_dwordx4 v194, s[34:35]
	s_add_i32 m0, s36, 0x2000
	s_nop 0
	global_load_lds_dwordx4 v198, s[34:35]
	v_lshl_add_u64 v[204:205], v[208:209], 0, s[16:17]
	s_mov_b32 m0, s46
	s_nop 0
	global_load_lds_dwordx4 v[204:205], off
	v_lshl_add_u64 v[204:205], v[210:211], 0, s[16:17]
	s_mov_b32 m0, s47
	s_nop 0
	global_load_lds_dwordx4 v[204:205], off
	ds_read_b128 v[160:163], v247 offset:49152
	ds_read_b128 v[164:167], v247 offset:50176
	ds_read_b128 v[168:171], v247 offset:51200
	ds_read_b128 v[172:175], v247 offset:52224
	ds_read_b128 v[176:179], v247 offset:53248
	ds_read_b128 v[180:183], v247 offset:54272
	ds_read_b128 v[184:187], v247 offset:55296
	ds_read_b128 v[188:191], v247 offset:56320
	s_waitcnt vmcnt(8)
	s_waitcnt lgkmcnt(0)
	s_setprio 1
	s_barrier
	v_mfma_f32_16x16x32_bf16 v[60:63], v[120:123], v[160:163], v[60:63]
	v_mfma_f32_16x16x32_bf16 v[56:59], v[136:139], v[160:163], v[56:59]
	v_mfma_f32_16x16x32_bf16 v[44:47], v[120:123], v[168:171], v[44:47]
	v_mfma_f32_16x16x32_bf16 v[40:43], v[136:139], v[168:171], v[40:43]
	v_mfma_f32_16x16x32_bf16 v[28:31], v[120:123], v[176:179], v[28:31]
	v_mfma_f32_16x16x32_bf16 v[24:27], v[136:139], v[176:179], v[24:27]
	v_mfma_f32_16x16x32_bf16 v[12:15], v[120:123], v[184:187], v[12:15]
	v_mfma_f32_16x16x32_bf16 v[8:11], v[136:139], v[184:187], v[8:11]
	v_mfma_f32_16x16x32_bf16 v[60:63], v[128:131], v[164:167], v[60:63]
	v_mfma_f32_16x16x32_bf16 v[56:59], v[140:143], v[164:167], v[56:59]
	v_mfma_f32_16x16x32_bf16 v[44:47], v[128:131], v[172:175], v[44:47]
	v_mfma_f32_16x16x32_bf16 v[40:43], v[140:143], v[172:175], v[40:43]
	v_mfma_f32_16x16x32_bf16 v[28:31], v[128:131], v[180:183], v[28:31]
	v_mfma_f32_16x16x32_bf16 v[24:27], v[140:143], v[180:183], v[24:27]
	v_mfma_f32_16x16x32_bf16 v[12:15], v[128:131], v[188:191], v[12:15]
	v_mfma_f32_16x16x32_bf16 v[8:11], v[140:143], v[188:191], v[8:11]
	v_mfma_f32_16x16x32_bf16 v[52:55], v[144:147], v[160:163], v[52:55]
	v_mfma_f32_16x16x32_bf16 v[48:51], v[152:155], v[160:163], v[48:51]
	v_mfma_f32_16x16x32_bf16 v[36:39], v[144:147], v[168:171], v[36:39]
	v_mfma_f32_16x16x32_bf16 v[32:35], v[152:155], v[168:171], v[32:35]
	v_mfma_f32_16x16x32_bf16 v[20:23], v[144:147], v[176:179], v[20:23]
	v_mfma_f32_16x16x32_bf16 v[16:19], v[152:155], v[176:179], v[16:19]
	v_mfma_f32_16x16x32_bf16 v[4:7], v[144:147], v[184:187], v[4:7]
	v_mfma_f32_16x16x32_bf16 v[0:3], v[152:155], v[184:187], v[0:3]
	v_mfma_f32_16x16x32_bf16 v[52:55], v[148:151], v[164:167], v[52:55]
	v_mfma_f32_16x16x32_bf16 v[48:51], v[156:159], v[164:167], v[48:51]
	v_mfma_f32_16x16x32_bf16 v[36:39], v[148:151], v[172:175], v[36:39]
	v_mfma_f32_16x16x32_bf16 v[32:35], v[156:159], v[172:175], v[32:35]
	v_mfma_f32_16x16x32_bf16 v[20:23], v[148:151], v[180:183], v[20:23]
	v_mfma_f32_16x16x32_bf16 v[16:19], v[156:159], v[180:183], v[16:19]
	v_mfma_f32_16x16x32_bf16 v[4:7], v[148:151], v[188:191], v[4:7]
	v_mfma_f32_16x16x32_bf16 v[0:3], v[156:159], v[188:191], v[0:3]
	s_barrier
	s_setprio 0
	s_add_i32 s57, s57, 2
	s_add_u32 s30, s30, 0x100
	s_addc_u32 s31, s31, 0
	s_add_u32 s55, s55, 0x100
	s_addc_u32 s56, s56, 0
	s_cmp_gt_u32 s57, 13
	s_cbranch_scc0 .LBB0_960
	s_and_b64 vcc, exec, s[18:19]
	s_cbranch_vccz .LBB0_963
	s_barrier

; #define PG8_STAGE(bufoff, gbase, voff) do { _Pragma("unroll") for (int _i = 0; _i < 2; ++_i) \
;         __builtin_amdgcn_global_load_lds((const unsigned*)((const char*)(gbase) + (voff)[_i]), (PG8_LAS unsigned*)(lds + (bufoff) + ldsw + _i * 8192), 16, 0, 0); } while (0)
; #define PG8_LDA(dst, b, h) do { _Pragma("unroll") for (int m = 0; m < 4; ++m) _Pragma("unroll") for (int k = 0; k < 2; ++k) dst[m][k] = *(const PG8_LAS bf16x8*)(lds + PG8_SA(b, h) + aoff + m * 2048 + k * 1024); } while (0)
; #define PG8_LDB(dst, b, h) do { _Pragma("unroll") for (int n = 0; n < 2; ++n) _Pragma("unroll") for (int k = 0; k < 2; ++k) dst[n][k] = *(const PG8_LAS bf16x8*)(lds + PG8_SB(b, h) + boff + n * 2048 + k * 1024); } while (0)
; #define PG8_WAIT_V(n) asm volatile("s_waitcnt vmcnt(" #n ")" ::: "memory")
; #define PG8_WAIT_L(n) asm volatile("s_waitcnt lgkmcnt(" #n ")" ::: "memory")
; #define PG8_BAR __builtin_amdgcn_s_barrier()
; #define PG8_SCHED __builtin_amdgcn_sched_barrier(0)
; template <class Epi, class Sched, bool ALIGN_EPI = false, bool SP2 = false>
; __device__ __forceinline__ void gemm_phase(PG8_LAS unsigned char* lds, const Gemm g, const Sched& S, const Epi& E) {
;     ...
;         const char* nA = has_next ? (const char*)g.A + (size_t)nxt.pm * tstep : cA; const char* nB = has_next ? (const char*)g.Bt + (size_t)nxt.pn * tstep : cB;
;         for (int t = 0; t < nt; t += 2) {
;             const bool last = (t == nt - 2);
;             const char* a1 = cA + (size_t)(t + 1) * kstep;
;             const char* a2 = last ? nA : cA + (size_t)(t + 2) * kstep; const char* b2 = last ? nB : cB + (size_t)(t + 2) * kstep;
;             const char* a3 = a2 + kstep; const char* b3 = b2 + kstep;
;             if (last && has_next) S.a_ready(nxt, ui + 1);
;             if constexpr (SP2) {
;             PG8_LDB(B0, 0, 0); PG8_LDB(B1, 0, 1); PG8_SCHED; PG8_LDA(At, 0, 0); PG8_STAGE(PG8_SA(1, 1), a1 + hstep, voffA);
;             PG8_WAIT_V(8); PG8_WAIT_L(0); PG8_BAR; PG8_MMA(0, 0, At, B0); PG8_MMA(0, 1, At, B1); PG8_BAR; PG8_SCHED;
;             PG8_LDA(At, 0, 1); PG8_STAGE(PG8_SB(0, 0), b2, voffB); PG8_STAGE(PG8_SB(0, 1), b2 + hstep, voffB); PG8_STAGE(PG8_SA(0, 0), a2, voffA);
;             PG8_WAIT_V(8); PG8_WAIT_L(0); PG8_BAR; PG8_MMA(1, 0, At, B0); PG8_MMA(1, 1, At, B1); PG8_BAR; PG8_SCHED;
.LBB0_1048:
	s_ashr_i32 s17, s16, 31
	s_lshl_b64 s[18:19], s[16:17], 19
	s_add_u32 s18, s34, s18
	s_addc_u32 s19, s35, s19
	s_and_b64 s[20:21], s[0:1], exec
	s_cselect_b32 s17, s19, s25
	s_cselect_b32 s50, s18, s24
	s_ashr_i32 s15, s14, 31
	s_lshl_b64 s[20:21], s[14:15], 19
	s_add_u32 s20, s36, s20
	s_addc_u32 s21, s37, s21
	s_and_b64 s[28:29], s[0:1], exec
	s_cselect_b32 s15, s21, s27
	s_cselect_b32 s51, s20, s26
	s_add_u32 s24, s24, 0x40080
	s_addc_u32 s25, s25, 0
	s_add_u32 s52, s26, 0x100
	s_addc_u32 s53, s27, 0
	s_mov_b32 s54, -2
	s_add_u32 s26, s24, 0xfffc0080
	s_addc_u32 s27, s25, -1
	s_cmp_eq_u32 s54, 12
	s_cselect_b32 s29, s17, s27
	s_cselect_b32 s28, s50, s26
	s_cselect_b32 s27, s15, s53
	s_cselect_b32 s26, s51, s52
	s_add_i32 m0, s23, 0xc000
	s_nop 0
	global_load_lds_dwordx4 v136, s[24:25]
	s_add_i32 m0, s23, 0xe000
	s_nop 0
	global_load_lds_dwordx4 v138, s[24:25]
	s_waitcnt vmcnt(8)
	s_waitcnt lgkmcnt(0)
	s_setprio 1
	s_barrier
	v_mfma_f32_16x16x32_bf16 v[124:127], v[152:155], v[184:187], 0
	v_mfma_f32_16x16x32_bf16 v[120:123], v[160:163], v[184:187], 0
	v_mfma_f32_16x16x32_bf16 v[108:111], v[152:155], v[192:195], 0
	v_mfma_f32_16x16x32_bf16 v[104:107], v[160:163], v[192:195], 0
	v_mfma_f32_16x16x32_bf16 v[92:95], v[152:155], v[200:203], 0
	v_mfma_f32_16x16x32_bf16 v[88:91], v[160:163], v[200:203], 0
	v_mfma_f32_16x16x32_bf16 v[76:79], v[152:155], v[208:211], 0
	v_mfma_f32_16x16x32_bf16 v[72:75], v[160:163], v[208:211], 0
	v_mfma_f32_16x16x32_bf16 v[124:127], v[156:159], v[188:191], v[124:127]
	v_mfma_f32_16x16x32_bf16 v[120:123], v[164:167], v[188:191], v[120:123]
	v_mfma_f32_16x16x32_bf16 v[108:111], v[156:159], v[196:199], v[108:111]
	v_mfma_f32_16x16x32_bf16 v[104:107], v[164:167], v[196:199], v[104:107]
	v_mfma_f32_16x16x32_bf16 v[92:95], v[156:159], v[204:207], v[92:95]
	v_mfma_f32_16x16x32_bf16 v[88:91], v[164:167], v[204:207], v[88:91]
	v_mfma_f32_16x16x32_bf16 v[76:79], v[156:159], v[212:215], v[76:79]
	v_mfma_f32_16x16x32_bf16 v[72:75], v[164:167], v[212:215], v[72:75]
	v_mfma_f32_16x16x32_bf16 v[116:119], v[168:171], v[184:187], 0
	v_mfma_f32_16x16x32_bf16 v[112:115], v[176:179], v[184:187], 0
	v_mfma_f32_16x16x32_bf16 v[100:103], v[168:171], v[192:195], 0
	v_mfma_f32_16x16x32_bf16 v[96:99], v[176:179], v[192:195], 0
	v_mfma_f32_16x16x32_bf16 v[84:87], v[168:171], v[200:203], 0
	v_mfma_f32_16x16x32_bf16 v[80:83], v[176:179], v[200:203], 0
	v_mfma_f32_16x16x32_bf16 v[68:71], v[168:171], v[208:211], 0
	v_mfma_f32_16x16x32_bf16 v[64:67], v[176:179], v[208:211], 0
	v_mfma_f32_16x16x32_bf16 v[116:119], v[172:175], v[188:191], v[116:119]
	v_mfma_f32_16x16x32_bf16 v[112:115], v[180:183], v[188:191], v[112:115]
	v_mfma_f32_16x16x32_bf16 v[100:103], v[172:175], v[196:199], v[100:103]
	v_mfma_f32_16x16x32_bf16 v[96:99], v[180:183], v[196:199], v[96:99]
	v_mfma_f32_16x16x32_bf16 v[84:87], v[172:175], v[204:207], v[84:87]
	v_mfma_f32_16x16x32_bf16 v[80:83], v[180:183], v[204:207], v[80:83]
	v_mfma_f32_16x16x32_bf16 v[68:71], v[172:175], v[212:215], v[68:71]
	v_mfma_f32_16x16x32_bf16 v[64:67], v[180:183], v[212:215], v[64:67]
	s_barrier
	s_setprio 0
	s_add_i32 s55, s44, s33
	v_lshl_add_u64 v[216:217], s[26:27], 0, v[132:133]
	s_mov_b32 m0, s55
	s_nop 0
	global_load_lds_dwordx4 v[216:217], off
	s_add_i32 m0, s55, 0x2000
	s_add_u32 s56, s26, 0x40000
	v_lshl_add_u64 v[218:219], s[26:27], 0, v[128:129]
	s_addc_u32 s57, s27, 0
	s_add_i32 s55, s45, s33
	global_load_lds_dwordx4 v[218:219], off
	s_mov_b32 m0, s55
	v_lshl_add_u64 v[222:223], s[28:29], 0, v[130:131]
	global_load_lds_dwordx4 v132, s[56:57]
	s_add_i32 m0, s55, 0x2000
	s_nop 0
	global_load_lds_dwordx4 v128, s[56:57]
	v_lshl_add_u64 v[220:221], s[28:29], 0, v[134:135]
	s_mov_b32 m0, s23
	s_nop 0
	global_load_lds_dwordx4 v[220:221], off
	s_mov_b32 m0, s39
	s_nop 0
	global_load_lds_dwordx4 v[222:223], off
	ds_read_b128 v[184:187], v150 offset:16384
	ds_read_b128 v[188:191], v150 offset:17408
	ds_read_b128 v[192:195], v150 offset:18432
	ds_read_b128 v[196:199], v150 offset:19456
	ds_read_b128 v[200:203], v150 offset:20480
	ds_read_b128 v[204:207], v150 offset:21504
	ds_read_b128 v[208:211], v150 offset:22528
	ds_read_b128 v[212:215], v150 offset:23552
	s_waitcnt vmcnt(8)
	s_waitcnt lgkmcnt(0)
	s_setprio 1
	s_barrier
	v_mfma_f32_16x16x32_bf16 v[60:63], v[152:155], v[184:187], 0
	v_mfma_f32_16x16x32_bf16 v[56:59], v[160:163], v[184:187], 0
	v_mfma_f32_16x16x32_bf16 v[44:47], v[152:155], v[192:195], 0
	v_mfma_f32_16x16x32_bf16 v[40:43], v[160:163], v[192:195], 0
	v_mfma_f32_16x16x32_bf16 v[28:31], v[152:155], v[200:203], 0
	v_mfma_f32_16x16x32_bf16 v[24:27], v[160:163], v[200:203], 0
	v_mfma_f32_16x16x32_bf16 v[12:15], v[152:155], v[208:211], 0
	v_mfma_f32_16x16x32_bf16 v[8:11], v[160:163], v[208:211], 0
	v_mfma_f32_16x16x32_bf16 v[60:63], v[156:159], v[188:191], v[60:63]
	v_mfma_f32_16x16x32_bf16 v[56:59], v[164:167], v[188:191], v[56:59]
	v_mfma_f32_16x16x32_bf16 v[44:47], v[156:159], v[196:199], v[44:47]
	v_mfma_f32_16x16x32_bf16 v[40:43], v[164:167], v[196:199], v[40:43]
	v_mfma_f32_16x16x32_bf16 v[28:31], v[156:159], v[204:207], v[28:31]
	v_mfma_f32_16x16x32_bf16 v[24:27], v[164:167], v[204:207], v[24:27]
	v_mfma_f32_16x16x32_bf16 v[12:15], v[156:159], v[212:215], v[12:15]
	v_mfma_f32_16x16x32_bf16 v[8:11], v[164:167], v[212:215], v[8:11]
	v_mfma_f32_16x16x32_bf16 v[52:55], v[168:171], v[184:187], 0
	v_mfma_f32_16x16x32_bf16 v[48:51], v[176:179], v[184:187], 0
	v_mfma_f32_16x16x32_bf16 v[36:39], v[168:171], v[192:195], 0
	v_mfma_f32_16x16x32_bf16 v[32:35], v[176:179], v[192:195], 0
	v_mfma_f32_16x16x32_bf16 v[20:23], v[168:171], v[200:203], 0
	v_mfma_f32_16x16x32_bf16 v[16:19], v[176:179], v[200:203], 0
	v_mfma_f32_16x16x32_bf16 v[4:7], v[168:171], v[208:211], 0
	v_mfma_f32_16x16x32_bf16 v[0:3], v[176:179], v[208:211], 0
	v_mfma_f32_16x16x32_bf16 v[52:55], v[172:175], v[188:191], v[52:55]
	v_mfma_f32_16x16x32_bf16 v[48:51], v[180:183], v[188:191], v[48:51]
	v_mfma_f32_16x16x32_bf16 v[36:39], v[172:175], v[196:199], v[36:39]
	v_mfma_f32_16x16x32_bf16 v[32:35], v[180:183], v[196:199], v[32:35]
	v_mfma_f32_16x16x32_bf16 v[20:23], v[172:175], v[204:207], v[20:23]
	v_mfma_f32_16x16x32_bf16 v[16:19], v[180:183], v[204:207], v[16:19]
	v_mfma_f32_16x16x32_bf16 v[4:7], v[172:175], v[212:215], v[4:7]
	v_mfma_f32_16x16x32_bf16 v[0:3], v[180:183], v[212:215], v[0:3]
	s_barrier
; #define PG8_STAGE(bufoff, gbase, voff) do { _Pragma("unroll") for (int _i = 0; _i < 2; ++_i) \
;         __builtin_amdgcn_global_load_lds((const unsigned*)((const char*)(gbase) + (voff)[_i]), (PG8_LAS unsigned*)(lds + (bufoff) + ldsw + _i * 8192), 16, 0, 0); } while (0)
; #define PG8_LDA(dst, b, h) do { _Pragma("unroll") for (int m = 0; m < 4; ++m) _Pragma("unroll") for (int k = 0; k < 2; ++k) dst[m][k] = *(const PG8_LAS bf16x8*)(lds + PG8_SA(b, h) + aoff + m * 2048 + k * 1024); } while (0)
; #define PG8_LDB(dst, b, h) do { _Pragma("unroll") for (int n = 0; n < 2; ++n) _Pragma("unroll") for (int k = 0; k < 2; ++k) dst[n][k] = *(const PG8_LAS bf16x8*)(lds + PG8_SB(b, h) + boff + n * 2048 + k * 1024); } while (0)
; #define PG8_MMA(ai, bj, At, Bt) do { __builtin_amdgcn_s_setprio(1); _Pragma("unroll") for (int m = 0; m < 4; ++m) _Pragma("unroll") for (int n = 0; n < 2; ++n) _Pragma("unroll") for (int k = 0; k < 2; ++k) \
;         acc[ai][bj][m][n] = __builtin_amdgcn_mfma_f32_16x16x32_bf16(Bt[n][k], At[m][k], acc[ai][bj][m][n], 0, 0, 0); __builtin_amdgcn_s_setprio(0); } while (0)
; #define PG8_WAIT_V(n) asm volatile("s_waitcnt vmcnt(" #n ")" ::: "memory")
; #define PG8_WAIT_L(n) asm volatile("s_waitcnt lgkmcnt(" #n ")" ::: "memory")
; #define PG8_BAR __builtin_amdgcn_s_barrier()
; #define PG8_SCHED __builtin_amdgcn_sched_barrier(0)
; template <class Epi, class Sched, bool ALIGN_EPI = false, bool SP2 = false>
; __device__ __forceinline__ void gemm_phase(PG8_LAS unsigned char* lds, const Gemm g, const Sched& S, const Epi& E) {
;     ...
;             PG8_LDB(B0, 1, 0); PG8_LDB(B1, 1, 1); PG8_SCHED; PG8_LDA(At, 1, 0); PG8_STAGE(PG8_SA(0, 1), a2 + hstep, voffA);
;             PG8_WAIT_V(8); PG8_WAIT_L(0); PG8_BAR; PG8_MMA(0, 0, At, B0); PG8_MMA(0, 1, At, B1); PG8_BAR; PG8_SCHED;
;             PG8_LDA(At, 1, 1); PG8_STAGE(PG8_SB(1, 0), b3, voffB); PG8_STAGE(PG8_SB(1, 1), b3 + hstep, voffB); PG8_STAGE(PG8_SA(1, 0), a3, voffA);
;             PG8_WAIT_V(8); PG8_WAIT_L(0); PG8_BAR; PG8_MMA(1, 0, At, B0); PG8_MMA(1, 1, At, B1); PG8_BAR; PG8_SCHED;
	s_setprio 0
	s_add_i32 s55, 0, 0x18000
	v_add_u32_e32 v151, s55, v145
	s_add_i32 s56, 0, 0x1c000
	ds_read_b128 v[152:155], v151
	ds_read_b128 v[156:159], v151 offset:1024
	ds_read_b128 v[160:163], v151 offset:2048
	ds_read_b128 v[164:167], v151 offset:3072
	v_add_u32_e32 v151, s56, v145
	ds_read_b128 v[168:171], v151
	ds_read_b128 v[172:175], v151 offset:1024
	ds_read_b128 v[176:179], v151 offset:2048
	ds_read_b128 v[180:183], v151 offset:3072
	s_add_u32 s28, s28, 0x40000
	s_addc_u32 s29, s29, 0
	s_mov_b32 m0, s40
	ds_read_b128 v[184:187], v150 offset:32768
	ds_read_b128 v[188:191], v150 offset:33792
	ds_read_b128 v[192:195], v150 offset:34816
	ds_read_b128 v[196:199], v150 offset:35840
	ds_read_b128 v[200:203], v150 offset:36864
	ds_read_b128 v[204:207], v150 offset:37888
	ds_read_b128 v[208:211], v150 offset:38912
	ds_read_b128 v[212:215], v150 offset:39936
	global_load_lds_dwordx4 v134, s[28:29]
	s_mov_b32 m0, s41
	s_nop 0
	global_load_lds_dwordx4 v130, s[28:29]
	s_waitcnt vmcnt(8)
	s_waitcnt lgkmcnt(0)
	s_setprio 1
	s_barrier
	v_mfma_f32_16x16x32_bf16 v[124:127], v[152:155], v[184:187], v[124:127]
	v_mfma_f32_16x16x32_bf16 v[120:123], v[160:163], v[184:187], v[120:123]
	v_mfma_f32_16x16x32_bf16 v[108:111], v[152:155], v[192:195], v[108:111]
	v_mfma_f32_16x16x32_bf16 v[104:107], v[160:163], v[192:195], v[104:107]
	v_mfma_f32_16x16x32_bf16 v[92:95], v[152:155], v[200:203], v[92:95]
	v_mfma_f32_16x16x32_bf16 v[88:91], v[160:163], v[200:203], v[88:91]
	v_mfma_f32_16x16x32_bf16 v[76:79], v[152:155], v[208:211], v[76:79]
	v_mfma_f32_16x16x32_bf16 v[72:75], v[160:163], v[208:211], v[72:75]
	v_mfma_f32_16x16x32_bf16 v[124:127], v[156:159], v[188:191], v[124:127]
	v_mfma_f32_16x16x32_bf16 v[120:123], v[164:167], v[188:191], v[120:123]
	v_mfma_f32_16x16x32_bf16 v[108:111], v[156:159], v[196:199], v[108:111]
	v_mfma_f32_16x16x32_bf16 v[104:107], v[164:167], v[196:199], v[104:107]
	v_mfma_f32_16x16x32_bf16 v[92:95], v[156:159], v[204:207], v[92:95]
	v_mfma_f32_16x16x32_bf16 v[88:91], v[164:167], v[204:207], v[88:91]
	v_mfma_f32_16x16x32_bf16 v[76:79], v[156:159], v[212:215], v[76:79]
	v_mfma_f32_16x16x32_bf16 v[72:75], v[164:167], v[212:215], v[72:75]
	v_mfma_f32_16x16x32_bf16 v[116:119], v[168:171], v[184:187], v[116:119]
	v_mfma_f32_16x16x32_bf16 v[112:115], v[176:179], v[184:187], v[112:115]
	v_mfma_f32_16x16x32_bf16 v[100:103], v[168:171], v[192:195], v[100:103]
	v_mfma_f32_16x16x32_bf16 v[96:99], v[176:179], v[192:195], v[96:99]
	v_mfma_f32_16x16x32_bf16 v[84:87], v[168:171], v[200:203], v[84:87]
	v_mfma_f32_16x16x32_bf16 v[80:83], v[176:179], v[200:203], v[80:83]
	v_mfma_f32_16x16x32_bf16 v[68:71], v[168:171], v[208:211], v[68:71]
	v_mfma_f32_16x16x32_bf16 v[64:67], v[176:179], v[208:211], v[64:67]
	v_mfma_f32_16x16x32_bf16 v[116:119], v[172:175], v[188:191], v[116:119]
	v_mfma_f32_16x16x32_bf16 v[112:115], v[180:183], v[188:191], v[112:115]
	v_mfma_f32_16x16x32_bf16 v[100:103], v[172:175], v[196:199], v[100:103]
	v_mfma_f32_16x16x32_bf16 v[96:99], v[180:183], v[196:199], v[96:99]
	v_mfma_f32_16x16x32_bf16 v[84:87], v[172:175], v[204:207], v[84:87]
	v_mfma_f32_16x16x32_bf16 v[80:83], v[180:183], v[204:207], v[80:83]
	v_mfma_f32_16x16x32_bf16 v[68:71], v[172:175], v[212:215], v[68:71]
	v_mfma_f32_16x16x32_bf16 v[64:67], v[180:183], v[212:215], v[64:67]
	s_barrier
	s_setprio 0
	s_add_i32 s28, s55, s33
	v_lshl_add_u64 v[216:217], v[216:217], 0, s[8:9]
	s_mov_b32 m0, s28
	s_nop 0
	global_load_lds_dwordx4 v[216:217], off
	s_add_i32 m0, s28, 0x2000
	s_add_u32 s26, s26, 0x40080
	v_lshl_add_u64 v[216:217], v[218:219], 0, s[8:9]
	s_addc_u32 s27, s27, 0
	s_add_i32 s28, s56, s33
	global_load_lds_dwordx4 v[216:217], off
	s_mov_b32 m0, s28
	s_nop 0
	global_load_lds_dwordx4 v132, s[26:27]
	s_add_i32 m0, s28, 0x2000
	s_nop 0
	global_load_lds_dwordx4 v128, s[26:27]
	v_lshl_add_u64 v[216:217], v[220:221], 0, s[8:9]
	s_mov_b32 m0, s42
	s_nop 0
	global_load_lds_dwordx4 v[216:217], off
	v_lshl_add_u64 v[216:217], v[222:223], 0, s[8:9]
	s_mov_b32 m0, s43
	s_nop 0
	global_load_lds_dwordx4 v[216:217], off
	ds_read_b128 v[184:187], v150 offset:49152
	ds_read_b128 v[188:191], v150 offset:50176
	ds_read_b128 v[192:195], v150 offset:51200
	ds_read_b128 v[196:199], v150 offset:52224
	ds_read_b128 v[200:203], v150 offset:53248
	ds_read_b128 v[204:207], v150 offset:54272
	ds_read_b128 v[208:211], v150 offset:55296
	ds_read_b128 v[212:215], v150 offset:56320
	s_waitcnt vmcnt(8)
	s_waitcnt lgkmcnt(0)
	s_setprio 1
	s_barrier
	v_mfma_f32_16x16x32_bf16 v[60:63], v[152:155], v[184:187], v[60:63]
	v_mfma_f32_16x16x32_bf16 v[56:59], v[160:163], v[184:187], v[56:59]
	v_mfma_f32_16x16x32_bf16 v[44:47], v[152:155], v[192:195], v[44:47]
	v_mfma_f32_16x16x32_bf16 v[40:43], v[160:163], v[192:195], v[40:43]
	v_mfma_f32_16x16x32_bf16 v[28:31], v[152:155], v[200:203], v[28:31]
	v_mfma_f32_16x16x32_bf16 v[24:27], v[160:163], v[200:203], v[24:27]
	v_mfma_f32_16x16x32_bf16 v[12:15], v[152:155], v[208:211], v[12:15]
	v_mfma_f32_16x16x32_bf16 v[8:11], v[160:163], v[208:211], v[8:11]
	v_mfma_f32_16x16x32_bf16 v[60:63], v[156:159], v[188:191], v[60:63]
	v_mfma_f32_16x16x32_bf16 v[56:59], v[164:167], v[188:191], v[56:59]
	v_mfma_f32_16x16x32_bf16 v[44:47], v[156:159], v[196:199], v[44:47]
	v_mfma_f32_16x16x32_bf16 v[40:43], v[164:167], v[196:199], v[40:43]
	v_mfma_f32_16x16x32_bf16 v[28:31], v[156:159], v[204:207], v[28:31]
	v_mfma_f32_16x16x32_bf16 v[24:27], v[164:167], v[204:207], v[24:27]
	v_mfma_f32_16x16x32_bf16 v[12:15], v[156:159], v[212:215], v[12:15]
	v_mfma_f32_16x16x32_bf16 v[8:11], v[164:167], v[212:215], v[8:11]
	v_mfma_f32_16x16x32_bf16 v[52:55], v[168:171], v[184:187], v[52:55]
	v_mfma_f32_16x16x32_bf16 v[48:51], v[176:179], v[184:187], v[48:51]
	v_mfma_f32_16x16x32_bf16 v[36:39], v[168:171], v[192:195], v[36:39]
	v_mfma_f32_16x16x32_bf16 v[32:35], v[176:179], v[192:195], v[32:35]
	v_mfma_f32_16x16x32_bf16 v[20:23], v[168:171], v[200:203], v[20:23]
	v_mfma_f32_16x16x32_bf16 v[16:19], v[176:179], v[200:203], v[16:19]
	v_mfma_f32_16x16x32_bf16 v[4:7], v[168:171], v[208:211], v[4:7]
	v_mfma_f32_16x16x32_bf16 v[0:3], v[176:179], v[208:211], v[0:3]
	v_mfma_f32_16x16x32_bf16 v[52:55], v[172:175], v[188:191], v[52:55]
	v_mfma_f32_16x16x32_bf16 v[48:51], v[180:183], v[188:191], v[48:51]
	v_mfma_f32_16x16x32_bf16 v[36:39], v[172:175], v[196:199], v[36:39]
	v_mfma_f32_16x16x32_bf16 v[32:35], v[180:183], v[196:199], v[32:35]
	v_mfma_f32_16x16x32_bf16 v[20:23], v[172:175], v[204:207], v[20:23]
	v_mfma_f32_16x16x32_bf16 v[16:19], v[180:183], v[204:207], v[16:19]
	v_mfma_f32_16x16x32_bf16 v[4:7], v[172:175], v[212:215], v[4:7]
	v_mfma_f32_16x16x32_bf16 v[0:3], v[180:183], v[212:215], v[0:3]
	s_barrier
	s_setprio 0
	s_add_i32 s54, s54, 2
	s_add_u32 s24, s24, 0x100
	s_addc_u32 s25, s25, 0
	s_add_u32 s52, s52, 0x100
	s_addc_u32 s53, s53, 0
	s_cmp_gt_u32 s54, 13

; #define PG8_STAGE(bufoff, gbase, voff) do { _Pragma("unroll") for (int _i = 0; _i < 2; ++_i) \
;         __builtin_amdgcn_global_load_lds((const unsigned*)((const char*)(gbase) + (voff)[_i]), (PG8_LAS unsigned*)(lds + (bufoff) + ldsw + _i * 8192), 16, 0, 0); } while (0)
; #define PG8_LDA(dst, b, h) do { _Pragma("unroll") for (int m = 0; m < 4; ++m) _Pragma("unroll") for (int k = 0; k < 2; ++k) dst[m][k] = *(const PG8_LAS bf16x8*)(lds + PG8_SA(b, h) + aoff + m * 2048 + k * 1024); } while (0)
; #define PG8_LDB(dst, b, h) do { _Pragma("unroll") for (int n = 0; n < 2; ++n) _Pragma("unroll") for (int k = 0; k < 2; ++k) dst[n][k] = *(const PG8_LAS bf16x8*)(lds + PG8_SB(b, h) + boff + n * 2048 + k * 1024); } while (0)
; #define PG8_MMA(ai, bj, At, Bt) do { __builtin_amdgcn_s_setprio(1); _Pragma("unroll") for (int m = 0; m < 4; ++m) _Pragma("unroll") for (int n = 0; n < 2; ++n) _Pragma("unroll") for (int k = 0; k < 2; ++k) \
;         acc[ai][bj][m][n] = __builtin_amdgcn_mfma_f32_16x16x32_bf16(Bt[n][k], At[m][k], acc[ai][bj][m][n], 0, 0, 0); __builtin_amdgcn_s_setprio(0); } while (0)
; #define PG8_WAIT_V(n) asm volatile("s_waitcnt vmcnt(" #n ")" ::: "memory")
; #define PG8_BAR __builtin_amdgcn_s_barrier()
; template <class Epi, class Sched, bool ALIGN_EPI = false, bool SP2 = false>
; __device__ __forceinline__ void gemm_phase(PG8_LAS unsigned char* lds, const Gemm g, const Sched& S, const Epi& E) {
;     ...
;         for (int t = 0; t < nt; t += 2) {
;             const bool last = (t == nt - 2);
;             const char* a1 = cA + (size_t)(t + 1) * kstep;
;             const char* a2 = last ? nA : cA + (size_t)(t + 2) * kstep; const char* b2 = last ? nB : cB + (size_t)(t + 2) * kstep;
;             const char* a3 = a2 + kstep; const char* b3 = b2 + kstep;
;             if (last && has_next) S.a_ready(nxt, ui + 1);
;             if constexpr (SP2) {
;             PG8_LDB(B0, 0, 0); PG8_LDB(B1, 0, 1); PG8_SCHED; PG8_LDA(At, 0, 0); PG8_STAGE(PG8_SA(1, 1), a1 + hstep, voffA);
;             PG8_WAIT_V(8); PG8_WAIT_L(0); PG8_BAR; PG8_MMA(0, 0, At, B0); PG8_MMA(0, 1, At, B1); PG8_BAR; PG8_SCHED;
;             PG8_LDA(At, 0, 1); PG8_STAGE(PG8_SB(0, 0), b2, voffB); PG8_STAGE(PG8_SB(0, 1), b2 + hstep, voffB); PG8_STAGE(PG8_SA(0, 0), a2, voffA);
;             PG8_WAIT_V(8); PG8_WAIT_L(0); PG8_BAR; PG8_MMA(1, 0, At, B0); PG8_MMA(1, 1, At, B1); PG8_BAR; PG8_SCHED;
.LBB0_1129:
	s_add_u32 s24, s24, 0xb0080
	s_addc_u32 s25, s25, 0
	s_add_u32 s51, s26, 0x100
	s_addc_u32 s52, s27, 0
	s_mov_b32 s53, -2
	s_add_u32 s26, s24, 0xfff50080
	s_addc_u32 s27, s25, -1
	s_cmp_eq_u32 s53, 40
	s_cselect_b32 s29, s7, s27
	s_cselect_b32 s28, s6, s26
	s_cselect_b32 s27, s23, s52
	s_cselect_b32 s26, s22, s51
	s_add_i32 m0, s35, 0xc000
	s_nop 0
	global_load_lds_dwordx4 v200, s[24:25]
	s_add_i32 m0, s35, 0xe000
	s_nop 0
	global_load_lds_dwordx4 v202, s[24:25]
	s_waitcnt vmcnt(8)
	s_waitcnt lgkmcnt(0)
	s_setprio 1
	s_barrier
	v_mfma_f32_16x16x32_bf16 v[132:135], v[120:123], v[160:163], 0
	v_mfma_f32_16x16x32_bf16 v[124:127], v[136:139], v[160:163], 0
	v_mfma_f32_16x16x32_bf16 v[108:111], v[120:123], v[168:171], 0
	v_mfma_f32_16x16x32_bf16 v[104:107], v[136:139], v[168:171], 0
	v_mfma_f32_16x16x32_bf16 v[92:95], v[120:123], v[176:179], 0
	v_mfma_f32_16x16x32_bf16 v[88:91], v[136:139], v[176:179], 0
	v_mfma_f32_16x16x32_bf16 v[76:79], v[120:123], v[184:187], 0
	v_mfma_f32_16x16x32_bf16 v[72:75], v[136:139], v[184:187], 0
	v_mfma_f32_16x16x32_bf16 v[132:135], v[128:131], v[164:167], v[132:135]
	v_mfma_f32_16x16x32_bf16 v[124:127], v[140:143], v[164:167], v[124:127]
	v_mfma_f32_16x16x32_bf16 v[108:111], v[128:131], v[172:175], v[108:111]
	v_mfma_f32_16x16x32_bf16 v[104:107], v[140:143], v[172:175], v[104:107]
	v_mfma_f32_16x16x32_bf16 v[92:95], v[128:131], v[180:183], v[92:95]
	v_mfma_f32_16x16x32_bf16 v[88:91], v[140:143], v[180:183], v[88:91]
	v_mfma_f32_16x16x32_bf16 v[76:79], v[128:131], v[188:191], v[76:79]
	v_mfma_f32_16x16x32_bf16 v[72:75], v[140:143], v[188:191], v[72:75]
	v_mfma_f32_16x16x32_bf16 v[116:119], v[144:147], v[160:163], 0
	v_mfma_f32_16x16x32_bf16 v[112:115], v[152:155], v[160:163], 0
	v_mfma_f32_16x16x32_bf16 v[100:103], v[144:147], v[168:171], 0
	v_mfma_f32_16x16x32_bf16 v[96:99], v[152:155], v[168:171], 0
	v_mfma_f32_16x16x32_bf16 v[84:87], v[144:147], v[176:179], 0
	v_mfma_f32_16x16x32_bf16 v[80:83], v[152:155], v[176:179], 0
	v_mfma_f32_16x16x32_bf16 v[68:71], v[144:147], v[184:187], 0
	v_mfma_f32_16x16x32_bf16 v[64:67], v[152:155], v[184:187], 0
	v_mfma_f32_16x16x32_bf16 v[116:119], v[148:151], v[164:167], v[116:119]
	v_mfma_f32_16x16x32_bf16 v[112:115], v[156:159], v[164:167], v[112:115]
	v_mfma_f32_16x16x32_bf16 v[100:103], v[148:151], v[172:175], v[100:103]
	v_mfma_f32_16x16x32_bf16 v[96:99], v[156:159], v[172:175], v[96:99]
	v_mfma_f32_16x16x32_bf16 v[84:87], v[148:151], v[180:183], v[84:87]
	v_mfma_f32_16x16x32_bf16 v[80:83], v[156:159], v[180:183], v[80:83]
	v_mfma_f32_16x16x32_bf16 v[68:71], v[148:151], v[188:191], v[68:71]
	v_mfma_f32_16x16x32_bf16 v[64:67], v[156:159], v[188:191], v[64:67]
	s_barrier
	s_setprio 0
	s_add_i32 s54, s45, s34
	v_lshl_add_u64 v[204:205], s[26:27], 0, v[194:195]
	s_mov_b32 m0, s54
	s_nop 0
	global_load_lds_dwordx4 v[204:205], off
	s_add_i32 m0, s54, 0x2000
	s_add_u32 s54, s26, 0xb0000
	v_lshl_add_u64 v[206:207], s[26:27], 0, v[198:199]
	s_addc_u32 s55, s27, 0
	s_add_i32 s56, s46, s34
	global_load_lds_dwordx4 v[206:207], off
	s_mov_b32 m0, s56
	v_lshl_add_u64 v[210:211], s[28:29], 0, v[196:197]
	global_load_lds_dwordx4 v194, s[54:55]
	s_add_i32 m0, s56, 0x2000
	s_nop 0
	global_load_lds_dwordx4 v198, s[54:55]
	v_lshl_add_u64 v[208:209], s[28:29], 0, v[192:193]
	s_mov_b32 m0, s35
	s_nop 0
	global_load_lds_dwordx4 v[208:209], off
	s_mov_b32 m0, s36
	s_nop 0
	global_load_lds_dwordx4 v[210:211], off
	ds_read_b128 v[160:163], v247 offset:16384
	ds_read_b128 v[164:167], v247 offset:17408
	ds_read_b128 v[168:171], v247 offset:18432
	ds_read_b128 v[172:175], v247 offset:19456
	ds_read_b128 v[176:179], v247 offset:20480
	ds_read_b128 v[180:183], v247 offset:21504
	ds_read_b128 v[184:187], v247 offset:22528
	ds_read_b128 v[188:191], v247 offset:23552
	s_waitcnt vmcnt(8)
	s_waitcnt lgkmcnt(0)
	s_setprio 1
	s_barrier
	v_mfma_f32_16x16x32_bf16 v[60:63], v[120:123], v[160:163], 0
	v_mfma_f32_16x16x32_bf16 v[56:59], v[136:139], v[160:163], 0
	v_mfma_f32_16x16x32_bf16 v[44:47], v[120:123], v[168:171], 0
	v_mfma_f32_16x16x32_bf16 v[40:43], v[136:139], v[168:171], 0
	v_mfma_f32_16x16x32_bf16 v[28:31], v[120:123], v[176:179], 0
	v_mfma_f32_16x16x32_bf16 v[24:27], v[136:139], v[176:179], 0
	v_mfma_f32_16x16x32_bf16 v[12:15], v[120:123], v[184:187], 0
	v_mfma_f32_16x16x32_bf16 v[8:11], v[136:139], v[184:187], 0
	v_mfma_f32_16x16x32_bf16 v[60:63], v[128:131], v[164:167], v[60:63]
	v_mfma_f32_16x16x32_bf16 v[56:59], v[140:143], v[164:167], v[56:59]
	v_mfma_f32_16x16x32_bf16 v[44:47], v[128:131], v[172:175], v[44:47]
	v_mfma_f32_16x16x32_bf16 v[40:43], v[140:143], v[172:175], v[40:43]
	v_mfma_f32_16x16x32_bf16 v[28:31], v[128:131], v[180:183], v[28:31]
	v_mfma_f32_16x16x32_bf16 v[24:27], v[140:143], v[180:183], v[24:27]
	v_mfma_f32_16x16x32_bf16 v[12:15], v[128:131], v[188:191], v[12:15]
	v_mfma_f32_16x16x32_bf16 v[8:11], v[140:143], v[188:191], v[8:11]
	v_mfma_f32_16x16x32_bf16 v[52:55], v[144:147], v[160:163], 0
	v_mfma_f32_16x16x32_bf16 v[48:51], v[152:155], v[160:163], 0
	v_mfma_f32_16x16x32_bf16 v[36:39], v[144:147], v[168:171], 0
	v_mfma_f32_16x16x32_bf16 v[32:35], v[152:155], v[168:171], 0
	v_mfma_f32_16x16x32_bf16 v[20:23], v[144:147], v[176:179], 0
	v_mfma_f32_16x16x32_bf16 v[16:19], v[152:155], v[176:179], 0
	v_mfma_f32_16x16x32_bf16 v[4:7], v[144:147], v[184:187], 0
	v_mfma_f32_16x16x32_bf16 v[0:3], v[152:155], v[184:187], 0
	v_mfma_f32_16x16x32_bf16 v[52:55], v[148:151], v[164:167], v[52:55]
	v_mfma_f32_16x16x32_bf16 v[48:51], v[156:159], v[164:167], v[48:51]
	v_mfma_f32_16x16x32_bf16 v[36:39], v[148:151], v[172:175], v[36:39]
	v_mfma_f32_16x16x32_bf16 v[32:35], v[156:159], v[172:175], v[32:35]
	v_mfma_f32_16x16x32_bf16 v[20:23], v[148:151], v[180:183], v[20:23]
	v_mfma_f32_16x16x32_bf16 v[16:19], v[156:159], v[180:183], v[16:19]
	v_mfma_f32_16x16x32_bf16 v[4:7], v[148:151], v[188:191], v[4:7]
	v_mfma_f32_16x16x32_bf16 v[0:3], v[156:159], v[188:191], v[0:3]
	s_barrier
; #define PG8_STAGE(bufoff, gbase, voff) do { _Pragma("unroll") for (int _i = 0; _i < 2; ++_i) \
;         __builtin_amdgcn_global_load_lds((const unsigned*)((const char*)(gbase) + (voff)[_i]), (PG8_LAS unsigned*)(lds + (bufoff) + ldsw + _i * 8192), 16, 0, 0); } while (0)
; #define PG8_LDA(dst, b, h) do { _Pragma("unroll") for (int m = 0; m < 4; ++m) _Pragma("unroll") for (int k = 0; k < 2; ++k) dst[m][k] = *(const PG8_LAS bf16x8*)(lds + PG8_SA(b, h) + aoff + m * 2048 + k * 1024); } while (0)
; #define PG8_LDB(dst, b, h) do { _Pragma("unroll") for (int n = 0; n < 2; ++n) _Pragma("unroll") for (int k = 0; k < 2; ++k) dst[n][k] = *(const PG8_LAS bf16x8*)(lds + PG8_SB(b, h) + boff + n * 2048 + k * 1024); } while (0)
; #define PG8_MMA(ai, bj, At, Bt) do { __builtin_amdgcn_s_setprio(1); _Pragma("unroll") for (int m = 0; m < 4; ++m) _Pragma("unroll") for (int n = 0; n < 2; ++n) _Pragma("unroll") for (int k = 0; k < 2; ++k) \
;         acc[ai][bj][m][n] = __builtin_amdgcn_mfma_f32_16x16x32_bf16(Bt[n][k], At[m][k], acc[ai][bj][m][n], 0, 0, 0); __builtin_amdgcn_s_setprio(0); } while (0)
; #define PG8_WAIT_V(n) asm volatile("s_waitcnt vmcnt(" #n ")" ::: "memory")
; #define PG8_WAIT_L(n) asm volatile("s_waitcnt lgkmcnt(" #n ")" ::: "memory")
; #define PG8_BAR __builtin_amdgcn_s_barrier()
; #define PG8_SCHED __builtin_amdgcn_sched_barrier(0)
; template <class Epi, class Sched, bool ALIGN_EPI = false, bool SP2 = false>
; __device__ __forceinline__ void gemm_phase(PG8_LAS unsigned char* lds, const Gemm g, const Sched& S, const Epi& E) {
;     ...
;             PG8_LDB(B0, 1, 0); PG8_LDB(B1, 1, 1); PG8_SCHED; PG8_LDA(At, 1, 0); PG8_STAGE(PG8_SA(0, 1), a2 + hstep, voffA);
;             PG8_WAIT_V(8); PG8_WAIT_L(0); PG8_BAR; PG8_MMA(0, 0, At, B0); PG8_MMA(0, 1, At, B1); PG8_BAR; PG8_SCHED;
;             PG8_LDA(At, 1, 1); PG8_STAGE(PG8_SB(1, 0), b3, voffB); PG8_STAGE(PG8_SB(1, 1), b3 + hstep, voffB); PG8_STAGE(PG8_SA(1, 0), a3, voffA);
;             PG8_WAIT_V(8); PG8_WAIT_L(0); PG8_BAR; PG8_MMA(1, 0, At, B0); PG8_MMA(1, 1, At, B1); PG8_BAR; PG8_SCHED;
	s_setprio 0
	s_add_i32 s54, 0, 0x18000
	s_add_i32 s55, 0, 0x1c000
	v_add_u32_e32 v140, s54, v243
	v_add_u32_e32 v156, s55, v243
	ds_read_b128 v[120:123], v140
	ds_read_b128 v[128:131], v140 offset:1024
	ds_read_b128 v[136:139], v140 offset:2048
	ds_read_b128 v[140:143], v140 offset:3072
	ds_read_b128 v[144:147], v156
	ds_read_b128 v[148:151], v156 offset:1024
	ds_read_b128 v[152:155], v156 offset:2048
	ds_read_b128 v[156:159], v156 offset:3072
	s_add_u32 s28, s28, 0xb0000
	s_addc_u32 s29, s29, 0
	s_mov_b32 m0, s37
	ds_read_b128 v[160:163], v247 offset:32768
	ds_read_b128 v[164:167], v247 offset:33792
	ds_read_b128 v[168:171], v247 offset:34816
	ds_read_b128 v[172:175], v247 offset:35840
	ds_read_b128 v[176:179], v247 offset:36864
	ds_read_b128 v[180:183], v247 offset:37888
	ds_read_b128 v[184:187], v247 offset:38912
	ds_read_b128 v[188:191], v247 offset:39936
	global_load_lds_dwordx4 v192, s[28:29]
	s_mov_b32 m0, s38
	s_nop 0
	global_load_lds_dwordx4 v196, s[28:29]
	s_waitcnt vmcnt(8)
	s_waitcnt lgkmcnt(0)
	s_setprio 1
	s_barrier
	v_mfma_f32_16x16x32_bf16 v[132:135], v[120:123], v[160:163], v[132:135]
	v_mfma_f32_16x16x32_bf16 v[124:127], v[136:139], v[160:163], v[124:127]
	v_mfma_f32_16x16x32_bf16 v[108:111], v[120:123], v[168:171], v[108:111]
	v_mfma_f32_16x16x32_bf16 v[104:107], v[136:139], v[168:171], v[104:107]
	v_mfma_f32_16x16x32_bf16 v[92:95], v[120:123], v[176:179], v[92:95]
	v_mfma_f32_16x16x32_bf16 v[88:91], v[136:139], v[176:179], v[88:91]
	v_mfma_f32_16x16x32_bf16 v[76:79], v[120:123], v[184:187], v[76:79]
	v_mfma_f32_16x16x32_bf16 v[72:75], v[136:139], v[184:187], v[72:75]
	v_mfma_f32_16x16x32_bf16 v[132:135], v[128:131], v[164:167], v[132:135]
	v_mfma_f32_16x16x32_bf16 v[124:127], v[140:143], v[164:167], v[124:127]
	v_mfma_f32_16x16x32_bf16 v[108:111], v[128:131], v[172:175], v[108:111]
	v_mfma_f32_16x16x32_bf16 v[104:107], v[140:143], v[172:175], v[104:107]
	v_mfma_f32_16x16x32_bf16 v[92:95], v[128:131], v[180:183], v[92:95]
	v_mfma_f32_16x16x32_bf16 v[88:91], v[140:143], v[180:183], v[88:91]
	v_mfma_f32_16x16x32_bf16 v[76:79], v[128:131], v[188:191], v[76:79]
	v_mfma_f32_16x16x32_bf16 v[72:75], v[140:143], v[188:191], v[72:75]
	v_mfma_f32_16x16x32_bf16 v[116:119], v[144:147], v[160:163], v[116:119]
	v_mfma_f32_16x16x32_bf16 v[112:115], v[152:155], v[160:163], v[112:115]
	v_mfma_f32_16x16x32_bf16 v[100:103], v[144:147], v[168:171], v[100:103]
	v_mfma_f32_16x16x32_bf16 v[96:99], v[152:155], v[168:171], v[96:99]
	v_mfma_f32_16x16x32_bf16 v[84:87], v[144:147], v[176:179], v[84:87]
	v_mfma_f32_16x16x32_bf16 v[80:83], v[152:155], v[176:179], v[80:83]
	v_mfma_f32_16x16x32_bf16 v[68:71], v[144:147], v[184:187], v[68:71]
	v_mfma_f32_16x16x32_bf16 v[64:67], v[152:155], v[184:187], v[64:67]
	v_mfma_f32_16x16x32_bf16 v[116:119], v[148:151], v[164:167], v[116:119]
	v_mfma_f32_16x16x32_bf16 v[112:115], v[156:159], v[164:167], v[112:115]
	v_mfma_f32_16x16x32_bf16 v[100:103], v[148:151], v[172:175], v[100:103]
	v_mfma_f32_16x16x32_bf16 v[96:99], v[156:159], v[172:175], v[96:99]
	v_mfma_f32_16x16x32_bf16 v[84:87], v[148:151], v[180:183], v[84:87]
	v_mfma_f32_16x16x32_bf16 v[80:83], v[156:159], v[180:183], v[80:83]
	v_mfma_f32_16x16x32_bf16 v[68:71], v[148:151], v[188:191], v[68:71]
	v_mfma_f32_16x16x32_bf16 v[64:67], v[156:159], v[188:191], v[64:67]
	s_barrier
	s_setprio 0
	s_add_i32 s28, s54, s34
	v_lshl_add_u64 v[204:205], v[204:205], 0, s[18:19]
	s_mov_b32 m0, s28
	s_nop 0
	global_load_lds_dwordx4 v[204:205], off
	s_add_i32 m0, s28, 0x2000
	s_add_u32 s26, s26, 0xb0080
	v_lshl_add_u64 v[204:205], v[206:207], 0, s[18:19]
	s_addc_u32 s27, s27, 0
	s_add_i32 s28, s55, s34
	global_load_lds_dwordx4 v[204:205], off
	s_mov_b32 m0, s28
	s_nop 0
	global_load_lds_dwordx4 v194, s[26:27]
	s_add_i32 m0, s28, 0x2000
	s_nop 0
	global_load_lds_dwordx4 v198, s[26:27]
	v_lshl_add_u64 v[204:205], v[208:209], 0, s[18:19]
	s_mov_b32 m0, s40
	s_nop 0
	global_load_lds_dwordx4 v[204:205], off
	v_lshl_add_u64 v[204:205], v[210:211], 0, s[18:19]
	s_mov_b32 m0, s41
	s_nop 0
	global_load_lds_dwordx4 v[204:205], off
	ds_read_b128 v[160:163], v247 offset:49152
	ds_read_b128 v[164:167], v247 offset:50176
	ds_read_b128 v[168:171], v247 offset:51200
	ds_read_b128 v[172:175], v247 offset:52224
	ds_read_b128 v[176:179], v247 offset:53248
	ds_read_b128 v[180:183], v247 offset:54272
	ds_read_b128 v[184:187], v247 offset:55296
	ds_read_b128 v[188:191], v247 offset:56320
	s_waitcnt vmcnt(8)
	s_waitcnt lgkmcnt(0)
	s_setprio 1
	s_barrier
	v_mfma_f32_16x16x32_bf16 v[60:63], v[120:123], v[160:163], v[60:63]
	v_mfma_f32_16x16x32_bf16 v[56:59], v[136:139], v[160:163], v[56:59]
	v_mfma_f32_16x16x32_bf16 v[44:47], v[120:123], v[168:171], v[44:47]
	v_mfma_f32_16x16x32_bf16 v[40:43], v[136:139], v[168:171], v[40:43]
	v_mfma_f32_16x16x32_bf16 v[28:31], v[120:123], v[176:179], v[28:31]
	v_mfma_f32_16x16x32_bf16 v[24:27], v[136:139], v[176:179], v[24:27]
	v_mfma_f32_16x16x32_bf16 v[12:15], v[120:123], v[184:187], v[12:15]
	v_mfma_f32_16x16x32_bf16 v[8:11], v[136:139], v[184:187], v[8:11]
	v_mfma_f32_16x16x32_bf16 v[60:63], v[128:131], v[164:167], v[60:63]
	v_mfma_f32_16x16x32_bf16 v[56:59], v[140:143], v[164:167], v[56:59]
	v_mfma_f32_16x16x32_bf16 v[44:47], v[128:131], v[172:175], v[44:47]
	v_mfma_f32_16x16x32_bf16 v[40:43], v[140:143], v[172:175], v[40:43]
	v_mfma_f32_16x16x32_bf16 v[28:31], v[128:131], v[180:183], v[28:31]
	v_mfma_f32_16x16x32_bf16 v[24:27], v[140:143], v[180:183], v[24:27]
	v_mfma_f32_16x16x32_bf16 v[12:15], v[128:131], v[188:191], v[12:15]
	v_mfma_f32_16x16x32_bf16 v[8:11], v[140:143], v[188:191], v[8:11]
	v_mfma_f32_16x16x32_bf16 v[52:55], v[144:147], v[160:163], v[52:55]
	v_mfma_f32_16x16x32_bf16 v[48:51], v[152:155], v[160:163], v[48:51]
	v_mfma_f32_16x16x32_bf16 v[36:39], v[144:147], v[168:171], v[36:39]
	v_mfma_f32_16x16x32_bf16 v[32:35], v[152:155], v[168:171], v[32:35]
	v_mfma_f32_16x16x32_bf16 v[20:23], v[144:147], v[176:179], v[20:23]
	v_mfma_f32_16x16x32_bf16 v[16:19], v[152:155], v[176:179], v[16:19]
	v_mfma_f32_16x16x32_bf16 v[4:7], v[144:147], v[184:187], v[4:7]
	v_mfma_f32_16x16x32_bf16 v[0:3], v[152:155], v[184:187], v[0:3]
	v_mfma_f32_16x16x32_bf16 v[52:55], v[148:151], v[164:167], v[52:55]
	v_mfma_f32_16x16x32_bf16 v[48:51], v[156:159], v[164:167], v[48:51]
	v_mfma_f32_16x16x32_bf16 v[36:39], v[148:151], v[172:175], v[36:39]
	v_mfma_f32_16x16x32_bf16 v[32:35], v[156:159], v[172:175], v[32:35]
	v_mfma_f32_16x16x32_bf16 v[20:23], v[148:151], v[180:183], v[20:23]
	v_mfma_f32_16x16x32_bf16 v[16:19], v[156:159], v[180:183], v[16:19]
	v_mfma_f32_16x16x32_bf16 v[4:7], v[148:151], v[188:191], v[4:7]
	v_mfma_f32_16x16x32_bf16 v[0:3], v[156:159], v[188:191], v[0:3]
	s_barrier
	s_setprio 0
	s_add_i32 s53, s53, 2
	s_add_u32 s24, s24, 0x100
	s_addc_u32 s25, s25, 0
	s_add_u32 s51, s51, 0x100
	s_addc_u32 s52, s52, 0
	s_cmp_gt_u32 s53, 41

; #define PG8_STAGE(bufoff, gbase, voff) do { _Pragma("unroll") for (int _i = 0; _i < 2; ++_i) \
;         __builtin_amdgcn_global_load_lds((const unsigned*)((const char*)(gbase) + (voff)[_i]), (PG8_LAS unsigned*)(lds + (bufoff) + ldsw + _i * 8192), 16, 0, 0); } while (0)
; #define PG8_LDA(dst, b, h) do { _Pragma("unroll") for (int m = 0; m < 4; ++m) _Pragma("unroll") for (int k = 0; k < 2; ++k) dst[m][k] = *(const PG8_LAS bf16x8*)(lds + PG8_SA(b, h) + aoff + m * 2048 + k * 1024); } while (0)
; #define PG8_LDB(dst, b, h) do { _Pragma("unroll") for (int n = 0; n < 2; ++n) _Pragma("unroll") for (int k = 0; k < 2; ++k) dst[n][k] = *(const PG8_LAS bf16x8*)(lds + PG8_SB(b, h) + boff + n * 2048 + k * 1024); } while (0)
; #define PG8_WAIT_V(n) asm volatile("s_waitcnt vmcnt(" #n ")" ::: "memory")
; #define PG8_WAIT_L(n) asm volatile("s_waitcnt lgkmcnt(" #n ")" ::: "memory")
; #define PG8_BAR __builtin_amdgcn_s_barrier()
; #define PG8_SCHED __builtin_amdgcn_sched_barrier(0)
; template <class Epi, class Sched, bool ALIGN_EPI = false, bool SP2 = false>
; __device__ __forceinline__ void gemm_phase(PG8_LAS unsigned char* lds, const Gemm g, const Sched& S, const Epi& E) {
;     ...
;         const char* nA = has_next ? (const char*)g.A + (size_t)nxt.pm * tstep : cA; const char* nB = has_next ? (const char*)g.Bt + (size_t)nxt.pn * tstep : cB;
;         for (int t = 0; t < nt; t += 2) {
;             const bool last = (t == nt - 2);
;             const char* a1 = cA + (size_t)(t + 1) * kstep;
;             const char* a2 = last ? nA : cA + (size_t)(t + 2) * kstep; const char* b2 = last ? nB : cB + (size_t)(t + 2) * kstep;
;             const char* a3 = a2 + kstep; const char* b3 = b2 + kstep;
;             if (last && has_next) S.a_ready(nxt, ui + 1);
;             if constexpr (SP2) {
;             PG8_LDB(B0, 0, 0); PG8_LDB(B1, 0, 1); PG8_SCHED; PG8_LDA(At, 0, 0); PG8_STAGE(PG8_SA(1, 1), a1 + hstep, voffA);
;             PG8_WAIT_V(8); PG8_WAIT_L(0); PG8_BAR; PG8_MMA(0, 0, At, B0); PG8_MMA(0, 1, At, B1); PG8_BAR; PG8_SCHED;
;             PG8_LDA(At, 0, 1); PG8_STAGE(PG8_SB(0, 0), b2, voffB); PG8_STAGE(PG8_SB(0, 1), b2 + hstep, voffB); PG8_STAGE(PG8_SA(0, 0), a2, voffA);
;             PG8_WAIT_V(8); PG8_WAIT_L(0); PG8_BAR; PG8_MMA(1, 0, At, B0); PG8_MMA(1, 1, At, B1); PG8_BAR; PG8_SCHED;
.LBB0_1218:
	s_ashr_i32 s17, s16, 31
	s_lshl_b64 s[18:19], s[16:17], 19
	s_add_u32 s18, s36, s18
	s_addc_u32 s19, s37, s19
	s_and_b64 s[20:21], s[0:1], exec
	s_cselect_b32 s17, s19, s25
	s_cselect_b32 s50, s18, s24
	s_ashr_i32 s15, s14, 31
	s_lshl_b64 s[20:21], s[14:15], 19
	s_add_u32 s20, s34, s20
	s_addc_u32 s21, s35, s21
	s_and_b64 s[28:29], s[0:1], exec
	s_cselect_b32 s15, s21, s27
	s_cselect_b32 s51, s20, s26
	s_add_u32 s24, s24, 0x40080
	s_addc_u32 s25, s25, 0
	s_add_u32 s52, s26, 0x100
	s_addc_u32 s53, s27, 0
	s_mov_b32 s54, -2
	s_add_u32 s26, s24, 0xfffc0080
	s_addc_u32 s27, s25, -1
	s_cmp_eq_u32 s54, 12
	s_cselect_b32 s29, s17, s27
	s_cselect_b32 s28, s50, s26
	s_cselect_b32 s27, s15, s53
	s_cselect_b32 s26, s51, s52
	s_add_i32 m0, s23, 0xc000
	s_nop 0
	global_load_lds_dwordx4 v136, s[24:25]
	s_add_i32 m0, s23, 0xe000
	s_nop 0
	global_load_lds_dwordx4 v138, s[24:25]
	s_waitcnt vmcnt(8)
	s_waitcnt lgkmcnt(0)
	s_setprio 1
	s_barrier
	v_mfma_f32_16x16x32_bf16 v[124:127], v[152:155], v[184:187], 0
	v_mfma_f32_16x16x32_bf16 v[120:123], v[160:163], v[184:187], 0
	v_mfma_f32_16x16x32_bf16 v[108:111], v[152:155], v[192:195], 0
	v_mfma_f32_16x16x32_bf16 v[104:107], v[160:163], v[192:195], 0
	v_mfma_f32_16x16x32_bf16 v[92:95], v[152:155], v[200:203], 0
	v_mfma_f32_16x16x32_bf16 v[88:91], v[160:163], v[200:203], 0
	v_mfma_f32_16x16x32_bf16 v[76:79], v[152:155], v[208:211], 0
	v_mfma_f32_16x16x32_bf16 v[72:75], v[160:163], v[208:211], 0
	v_mfma_f32_16x16x32_bf16 v[124:127], v[156:159], v[188:191], v[124:127]
	v_mfma_f32_16x16x32_bf16 v[120:123], v[164:167], v[188:191], v[120:123]
	v_mfma_f32_16x16x32_bf16 v[108:111], v[156:159], v[196:199], v[108:111]
	v_mfma_f32_16x16x32_bf16 v[104:107], v[164:167], v[196:199], v[104:107]
	v_mfma_f32_16x16x32_bf16 v[92:95], v[156:159], v[204:207], v[92:95]
	v_mfma_f32_16x16x32_bf16 v[88:91], v[164:167], v[204:207], v[88:91]
	v_mfma_f32_16x16x32_bf16 v[76:79], v[156:159], v[212:215], v[76:79]
	v_mfma_f32_16x16x32_bf16 v[72:75], v[164:167], v[212:215], v[72:75]
	v_mfma_f32_16x16x32_bf16 v[116:119], v[168:171], v[184:187], 0
	v_mfma_f32_16x16x32_bf16 v[112:115], v[176:179], v[184:187], 0
	v_mfma_f32_16x16x32_bf16 v[100:103], v[168:171], v[192:195], 0
	v_mfma_f32_16x16x32_bf16 v[96:99], v[176:179], v[192:195], 0
	v_mfma_f32_16x16x32_bf16 v[84:87], v[168:171], v[200:203], 0
	v_mfma_f32_16x16x32_bf16 v[80:83], v[176:179], v[200:203], 0
	v_mfma_f32_16x16x32_bf16 v[68:71], v[168:171], v[208:211], 0
	v_mfma_f32_16x16x32_bf16 v[64:67], v[176:179], v[208:211], 0
	v_mfma_f32_16x16x32_bf16 v[116:119], v[172:175], v[188:191], v[116:119]
	v_mfma_f32_16x16x32_bf16 v[112:115], v[180:183], v[188:191], v[112:115]
	v_mfma_f32_16x16x32_bf16 v[100:103], v[172:175], v[196:199], v[100:103]
	v_mfma_f32_16x16x32_bf16 v[96:99], v[180:183], v[196:199], v[96:99]
	v_mfma_f32_16x16x32_bf16 v[84:87], v[172:175], v[204:207], v[84:87]
	v_mfma_f32_16x16x32_bf16 v[80:83], v[180:183], v[204:207], v[80:83]
	v_mfma_f32_16x16x32_bf16 v[68:71], v[172:175], v[212:215], v[68:71]
	v_mfma_f32_16x16x32_bf16 v[64:67], v[180:183], v[212:215], v[64:67]
	s_barrier
	s_setprio 0
	s_add_i32 s55, s44, s33
	v_lshl_add_u64 v[216:217], s[26:27], 0, v[132:133]
	s_mov_b32 m0, s55
	s_nop 0
	global_load_lds_dwordx4 v[216:217], off
	s_add_i32 m0, s55, 0x2000
	s_add_u32 s56, s26, 0x40000
	v_lshl_add_u64 v[218:219], s[26:27], 0, v[128:129]
	s_addc_u32 s57, s27, 0
	s_add_i32 s55, s45, s33
	global_load_lds_dwordx4 v[218:219], off
	s_mov_b32 m0, s55
	v_lshl_add_u64 v[222:223], s[28:29], 0, v[130:131]
	global_load_lds_dwordx4 v132, s[56:57]
	s_add_i32 m0, s55, 0x2000
	s_nop 0
	global_load_lds_dwordx4 v128, s[56:57]
	v_lshl_add_u64 v[220:221], s[28:29], 0, v[134:135]
	s_mov_b32 m0, s23
	s_nop 0
	global_load_lds_dwordx4 v[220:221], off
	s_mov_b32 m0, s39
	s_nop 0
	global_load_lds_dwordx4 v[222:223], off
	ds_read_b128 v[184:187], v150 offset:16384
	ds_read_b128 v[188:191], v150 offset:17408
	ds_read_b128 v[192:195], v150 offset:18432
	ds_read_b128 v[196:199], v150 offset:19456
	ds_read_b128 v[200:203], v150 offset:20480
	ds_read_b128 v[204:207], v150 offset:21504
	ds_read_b128 v[208:211], v150 offset:22528
	ds_read_b128 v[212:215], v150 offset:23552
	s_waitcnt vmcnt(8)
	s_waitcnt lgkmcnt(0)
	s_setprio 1
	s_barrier
	v_mfma_f32_16x16x32_bf16 v[60:63], v[152:155], v[184:187], 0
	v_mfma_f32_16x16x32_bf16 v[56:59], v[160:163], v[184:187], 0
	v_mfma_f32_16x16x32_bf16 v[44:47], v[152:155], v[192:195], 0
	v_mfma_f32_16x16x32_bf16 v[40:43], v[160:163], v[192:195], 0
	v_mfma_f32_16x16x32_bf16 v[28:31], v[152:155], v[200:203], 0
	v_mfma_f32_16x16x32_bf16 v[24:27], v[160:163], v[200:203], 0
	v_mfma_f32_16x16x32_bf16 v[12:15], v[152:155], v[208:211], 0
	v_mfma_f32_16x16x32_bf16 v[8:11], v[160:163], v[208:211], 0
	v_mfma_f32_16x16x32_bf16 v[60:63], v[156:159], v[188:191], v[60:63]
	v_mfma_f32_16x16x32_bf16 v[56:59], v[164:167], v[188:191], v[56:59]
	v_mfma_f32_16x16x32_bf16 v[44:47], v[156:159], v[196:199], v[44:47]
	v_mfma_f32_16x16x32_bf16 v[40:43], v[164:167], v[196:199], v[40:43]
	v_mfma_f32_16x16x32_bf16 v[28:31], v[156:159], v[204:207], v[28:31]
	v_mfma_f32_16x16x32_bf16 v[24:27], v[164:167], v[204:207], v[24:27]
	v_mfma_f32_16x16x32_bf16 v[12:15], v[156:159], v[212:215], v[12:15]
	v_mfma_f32_16x16x32_bf16 v[8:11], v[164:167], v[212:215], v[8:11]
	v_mfma_f32_16x16x32_bf16 v[52:55], v[168:171], v[184:187], 0
	v_mfma_f32_16x16x32_bf16 v[48:51], v[176:179], v[184:187], 0
	v_mfma_f32_16x16x32_bf16 v[36:39], v[168:171], v[192:195], 0
	v_mfma_f32_16x16x32_bf16 v[32:35], v[176:179], v[192:195], 0
	v_mfma_f32_16x16x32_bf16 v[20:23], v[168:171], v[200:203], 0
	v_mfma_f32_16x16x32_bf16 v[16:19], v[176:179], v[200:203], 0
	v_mfma_f32_16x16x32_bf16 v[4:7], v[168:171], v[208:211], 0
	v_mfma_f32_16x16x32_bf16 v[0:3], v[176:179], v[208:211], 0
	v_mfma_f32_16x16x32_bf16 v[52:55], v[172:175], v[188:191], v[52:55]
	v_mfma_f32_16x16x32_bf16 v[48:51], v[180:183], v[188:191], v[48:51]
	v_mfma_f32_16x16x32_bf16 v[36:39], v[172:175], v[196:199], v[36:39]
	v_mfma_f32_16x16x32_bf16 v[32:35], v[180:183], v[196:199], v[32:35]
	v_mfma_f32_16x16x32_bf16 v[20:23], v[172:175], v[204:207], v[20:23]
	v_mfma_f32_16x16x32_bf16 v[16:19], v[180:183], v[204:207], v[16:19]
	v_mfma_f32_16x16x32_bf16 v[4:7], v[172:175], v[212:215], v[4:7]
	v_mfma_f32_16x16x32_bf16 v[0:3], v[180:183], v[212:215], v[0:3]
	s_barrier
; #define PG8_STAGE(bufoff, gbase, voff) do { _Pragma("unroll") for (int _i = 0; _i < 2; ++_i) \
;         __builtin_amdgcn_global_load_lds((const unsigned*)((const char*)(gbase) + (voff)[_i]), (PG8_LAS unsigned*)(lds + (bufoff) + ldsw + _i * 8192), 16, 0, 0); } while (0)
; #define PG8_LDA(dst, b, h) do { _Pragma("unroll") for (int m = 0; m < 4; ++m) _Pragma("unroll") for (int k = 0; k < 2; ++k) dst[m][k] = *(const PG8_LAS bf16x8*)(lds + PG8_SA(b, h) + aoff + m * 2048 + k * 1024); } while (0)
; #define PG8_LDB(dst, b, h) do { _Pragma("unroll") for (int n = 0; n < 2; ++n) _Pragma("unroll") for (int k = 0; k < 2; ++k) dst[n][k] = *(const PG8_LAS bf16x8*)(lds + PG8_SB(b, h) + boff + n * 2048 + k * 1024); } while (0)
; #define PG8_MMA(ai, bj, At, Bt) do { __builtin_amdgcn_s_setprio(1); _Pragma("unroll") for (int m = 0; m < 4; ++m) _Pragma("unroll") for (int n = 0; n < 2; ++n) _Pragma("unroll") for (int k = 0; k < 2; ++k) \
;         acc[ai][bj][m][n] = __builtin_amdgcn_mfma_f32_16x16x32_bf16(Bt[n][k], At[m][k], acc[ai][bj][m][n], 0, 0, 0); __builtin_amdgcn_s_setprio(0); } while (0)
; #define PG8_WAIT_V(n) asm volatile("s_waitcnt vmcnt(" #n ")" ::: "memory")
; #define PG8_WAIT_L(n) asm volatile("s_waitcnt lgkmcnt(" #n ")" ::: "memory")
; #define PG8_BAR __builtin_amdgcn_s_barrier()
; #define PG8_SCHED __builtin_amdgcn_sched_barrier(0)
; template <class Epi, class Sched, bool ALIGN_EPI = false, bool SP2 = false>
; __device__ __forceinline__ void gemm_phase(PG8_LAS unsigned char* lds, const Gemm g, const Sched& S, const Epi& E) {
;     ...
;             PG8_LDB(B0, 1, 0); PG8_LDB(B1, 1, 1); PG8_SCHED; PG8_LDA(At, 1, 0); PG8_STAGE(PG8_SA(0, 1), a2 + hstep, voffA);
;             PG8_WAIT_V(8); PG8_WAIT_L(0); PG8_BAR; PG8_MMA(0, 0, At, B0); PG8_MMA(0, 1, At, B1); PG8_BAR; PG8_SCHED;
;             PG8_LDA(At, 1, 1); PG8_STAGE(PG8_SB(1, 0), b3, voffB); PG8_STAGE(PG8_SB(1, 1), b3 + hstep, voffB); PG8_STAGE(PG8_SA(1, 0), a3, voffA);
;             PG8_WAIT_V(8); PG8_WAIT_L(0); PG8_BAR; PG8_MMA(1, 0, At, B0); PG8_MMA(1, 1, At, B1); PG8_BAR; PG8_SCHED;
	s_setprio 0
	s_add_i32 s55, 0, 0x18000
	v_add_u32_e32 v151, s55, v145
	s_add_i32 s56, 0, 0x1c000
	ds_read_b128 v[152:155], v151
	ds_read_b128 v[156:159], v151 offset:1024
	ds_read_b128 v[160:163], v151 offset:2048
	ds_read_b128 v[164:167], v151 offset:3072
	v_add_u32_e32 v151, s56, v145
	ds_read_b128 v[168:171], v151
	ds_read_b128 v[172:175], v151 offset:1024
	ds_read_b128 v[176:179], v151 offset:2048
	ds_read_b128 v[180:183], v151 offset:3072
	s_add_u32 s28, s28, 0x40000
	s_addc_u32 s29, s29, 0
	s_mov_b32 m0, s40
	ds_read_b128 v[184:187], v150 offset:32768
	ds_read_b128 v[188:191], v150 offset:33792
	ds_read_b128 v[192:195], v150 offset:34816
	ds_read_b128 v[196:199], v150 offset:35840
	ds_read_b128 v[200:203], v150 offset:36864
	ds_read_b128 v[204:207], v150 offset:37888
	ds_read_b128 v[208:211], v150 offset:38912
	ds_read_b128 v[212:215], v150 offset:39936
	global_load_lds_dwordx4 v134, s[28:29]
	s_mov_b32 m0, s41
	s_nop 0
	global_load_lds_dwordx4 v130, s[28:29]
	s_waitcnt vmcnt(8)
	s_waitcnt lgkmcnt(0)
	s_setprio 1
	s_barrier
	v_mfma_f32_16x16x32_bf16 v[124:127], v[152:155], v[184:187], v[124:127]
	v_mfma_f32_16x16x32_bf16 v[120:123], v[160:163], v[184:187], v[120:123]
	v_mfma_f32_16x16x32_bf16 v[108:111], v[152:155], v[192:195], v[108:111]
	v_mfma_f32_16x16x32_bf16 v[104:107], v[160:163], v[192:195], v[104:107]
	v_mfma_f32_16x16x32_bf16 v[92:95], v[152:155], v[200:203], v[92:95]
	v_mfma_f32_16x16x32_bf16 v[88:91], v[160:163], v[200:203], v[88:91]
	v_mfma_f32_16x16x32_bf16 v[76:79], v[152:155], v[208:211], v[76:79]
	v_mfma_f32_16x16x32_bf16 v[72:75], v[160:163], v[208:211], v[72:75]
	v_mfma_f32_16x16x32_bf16 v[124:127], v[156:159], v[188:191], v[124:127]
	v_mfma_f32_16x16x32_bf16 v[120:123], v[164:167], v[188:191], v[120:123]
	v_mfma_f32_16x16x32_bf16 v[108:111], v[156:159], v[196:199], v[108:111]
	v_mfma_f32_16x16x32_bf16 v[104:107], v[164:167], v[196:199], v[104:107]
	v_mfma_f32_16x16x32_bf16 v[92:95], v[156:159], v[204:207], v[92:95]
	v_mfma_f32_16x16x32_bf16 v[88:91], v[164:167], v[204:207], v[88:91]
	v_mfma_f32_16x16x32_bf16 v[76:79], v[156:159], v[212:215], v[76:79]
	v_mfma_f32_16x16x32_bf16 v[72:75], v[164:167], v[212:215], v[72:75]
	v_mfma_f32_16x16x32_bf16 v[116:119], v[168:171], v[184:187], v[116:119]
	v_mfma_f32_16x16x32_bf16 v[112:115], v[176:179], v[184:187], v[112:115]
	v_mfma_f32_16x16x32_bf16 v[100:103], v[168:171], v[192:195], v[100:103]
	v_mfma_f32_16x16x32_bf16 v[96:99], v[176:179], v[192:195], v[96:99]
	v_mfma_f32_16x16x32_bf16 v[84:87], v[168:171], v[200:203], v[84:87]
	v_mfma_f32_16x16x32_bf16 v[80:83], v[176:179], v[200:203], v[80:83]
	v_mfma_f32_16x16x32_bf16 v[68:71], v[168:171], v[208:211], v[68:71]
	v_mfma_f32_16x16x32_bf16 v[64:67], v[176:179], v[208:211], v[64:67]
	v_mfma_f32_16x16x32_bf16 v[116:119], v[172:175], v[188:191], v[116:119]
	v_mfma_f32_16x16x32_bf16 v[112:115], v[180:183], v[188:191], v[112:115]
	v_mfma_f32_16x16x32_bf16 v[100:103], v[172:175], v[196:199], v[100:103]
	v_mfma_f32_16x16x32_bf16 v[96:99], v[180:183], v[196:199], v[96:99]
	v_mfma_f32_16x16x32_bf16 v[84:87], v[172:175], v[204:207], v[84:87]
	v_mfma_f32_16x16x32_bf16 v[80:83], v[180:183], v[204:207], v[80:83]
	v_mfma_f32_16x16x32_bf16 v[68:71], v[172:175], v[212:215], v[68:71]
	v_mfma_f32_16x16x32_bf16 v[64:67], v[180:183], v[212:215], v[64:67]
	s_barrier
	s_setprio 0
	s_add_i32 s28, s55, s33
	v_lshl_add_u64 v[216:217], v[216:217], 0, s[10:11]
	s_mov_b32 m0, s28
	s_nop 0
	global_load_lds_dwordx4 v[216:217], off
	s_add_i32 m0, s28, 0x2000
	s_add_u32 s26, s26, 0x40080
	v_lshl_add_u64 v[216:217], v[218:219], 0, s[10:11]
	s_addc_u32 s27, s27, 0
	s_add_i32 s28, s56, s33
	global_load_lds_dwordx4 v[216:217], off
	s_mov_b32 m0, s28
	s_nop 0
	global_load_lds_dwordx4 v132, s[26:27]
	s_add_i32 m0, s28, 0x2000
	s_nop 0
	global_load_lds_dwordx4 v128, s[26:27]
	v_lshl_add_u64 v[216:217], v[220:221], 0, s[10:11]
	s_mov_b32 m0, s42
	s_nop 0
	global_load_lds_dwordx4 v[216:217], off
	v_lshl_add_u64 v[216:217], v[222:223], 0, s[10:11]
	s_mov_b32 m0, s43
	s_nop 0
	global_load_lds_dwordx4 v[216:217], off
	ds_read_b128 v[184:187], v150 offset:49152
	ds_read_b128 v[188:191], v150 offset:50176
	ds_read_b128 v[192:195], v150 offset:51200
	ds_read_b128 v[196:199], v150 offset:52224
	ds_read_b128 v[200:203], v150 offset:53248
	ds_read_b128 v[204:207], v150 offset:54272
	ds_read_b128 v[208:211], v150 offset:55296
	ds_read_b128 v[212:215], v150 offset:56320
	s_waitcnt vmcnt(8)
	s_waitcnt lgkmcnt(0)
	s_setprio 1
	s_barrier
	v_mfma_f32_16x16x32_bf16 v[60:63], v[152:155], v[184:187], v[60:63]
	v_mfma_f32_16x16x32_bf16 v[56:59], v[160:163], v[184:187], v[56:59]
	v_mfma_f32_16x16x32_bf16 v[44:47], v[152:155], v[192:195], v[44:47]
	v_mfma_f32_16x16x32_bf16 v[40:43], v[160:163], v[192:195], v[40:43]
	v_mfma_f32_16x16x32_bf16 v[28:31], v[152:155], v[200:203], v[28:31]
	v_mfma_f32_16x16x32_bf16 v[24:27], v[160:163], v[200:203], v[24:27]
	v_mfma_f32_16x16x32_bf16 v[12:15], v[152:155], v[208:211], v[12:15]
	v_mfma_f32_16x16x32_bf16 v[8:11], v[160:163], v[208:211], v[8:11]
	v_mfma_f32_16x16x32_bf16 v[60:63], v[156:159], v[188:191], v[60:63]
	v_mfma_f32_16x16x32_bf16 v[56:59], v[164:167], v[188:191], v[56:59]
	v_mfma_f32_16x16x32_bf16 v[44:47], v[156:159], v[196:199], v[44:47]
	v_mfma_f32_16x16x32_bf16 v[40:43], v[164:167], v[196:199], v[40:43]
	v_mfma_f32_16x16x32_bf16 v[28:31], v[156:159], v[204:207], v[28:31]
	v_mfma_f32_16x16x32_bf16 v[24:27], v[164:167], v[204:207], v[24:27]
	v_mfma_f32_16x16x32_bf16 v[12:15], v[156:159], v[212:215], v[12:15]
	v_mfma_f32_16x16x32_bf16 v[8:11], v[164:167], v[212:215], v[8:11]
	v_mfma_f32_16x16x32_bf16 v[52:55], v[168:171], v[184:187], v[52:55]
	v_mfma_f32_16x16x32_bf16 v[48:51], v[176:179], v[184:187], v[48:51]
	v_mfma_f32_16x16x32_bf16 v[36:39], v[168:171], v[192:195], v[36:39]
	v_mfma_f32_16x16x32_bf16 v[32:35], v[176:179], v[192:195], v[32:35]
	v_mfma_f32_16x16x32_bf16 v[20:23], v[168:171], v[200:203], v[20:23]
	v_mfma_f32_16x16x32_bf16 v[16:19], v[176:179], v[200:203], v[16:19]
	v_mfma_f32_16x16x32_bf16 v[4:7], v[168:171], v[208:211], v[4:7]
	v_mfma_f32_16x16x32_bf16 v[0:3], v[176:179], v[208:211], v[0:3]
	v_mfma_f32_16x16x32_bf16 v[52:55], v[172:175], v[188:191], v[52:55]
	v_mfma_f32_16x16x32_bf16 v[48:51], v[180:183], v[188:191], v[48:51]
	v_mfma_f32_16x16x32_bf16 v[36:39], v[172:175], v[196:199], v[36:39]
	v_mfma_f32_16x16x32_bf16 v[32:35], v[180:183], v[196:199], v[32:35]
	v_mfma_f32_16x16x32_bf16 v[20:23], v[172:175], v[204:207], v[20:23]
	v_mfma_f32_16x16x32_bf16 v[16:19], v[180:183], v[204:207], v[16:19]
	v_mfma_f32_16x16x32_bf16 v[4:7], v[172:175], v[212:215], v[4:7]
	v_mfma_f32_16x16x32_bf16 v[0:3], v[180:183], v[212:215], v[0:3]
	s_barrier
	s_setprio 0
	s_add_i32 s54, s54, 2
	s_add_u32 s24, s24, 0x100
	s_addc_u32 s25, s25, 0
	s_add_u32 s52, s52, 0x100
	s_addc_u32 s53, s53, 0
	s_cmp_gt_u32 s54, 13
; #define PG8_STAGE(bufoff, gbase, voff) do { _Pragma("unroll") for (int _i = 0; _i < 2; ++_i) \
;         __builtin_amdgcn_global_load_lds((const unsigned*)((const char*)(gbase) + (voff)[_i]), (PG8_LAS unsigned*)(lds + (bufoff) + ldsw + _i * 8192), 16, 0, 0); } while (0)
; #define PG8_LDA(dst, b, h) do { _Pragma("unroll") for (int m = 0; m < 4; ++m) _Pragma("unroll") for (int k = 0; k < 2; ++k) dst[m][k] = *(const PG8_LAS bf16x8*)(lds + PG8_SA(b, h) + aoff + m * 2048 + k * 1024); } while (0)
; #define PG8_LDB(dst, b, h) do { _Pragma("unroll") for (int n = 0; n < 2; ++n) _Pragma("unroll") for (int k = 0; k < 2; ++k) dst[n][k] = *(const PG8_LAS bf16x8*)(lds + PG8_SB(b, h) + boff + n * 2048 + k * 1024); } while (0)
; #define PG8_MMA(ai, bj, At, Bt) do { __builtin_amdgcn_s_setprio(1); _Pragma("unroll") for (int m = 0; m < 4; ++m) _Pragma("unroll") for (int n = 0; n < 2; ++n) _Pragma("unroll") for (int k = 0; k < 2; ++k) \
;         acc[ai][bj][m][n] = __builtin_amdgcn_mfma_f32_16x16x32_bf16(Bt[n][k], At[m][k], acc[ai][bj][m][n], 0, 0, 0); __builtin_amdgcn_s_setprio(0); } while (0)
; #define PG8_WAIT_V(n) asm volatile("s_waitcnt vmcnt(" #n ")" ::: "memory")
; #define PG8_WAIT_L(n) asm volatile("s_waitcnt lgkmcnt(" #n ")" ::: "memory")
; template <class Epi, class Sched, bool ALIGN_EPI = false, bool SP2 = false>
; __device__ __forceinline__ void gemm_phase(PG8_LAS unsigned char* lds, const Gemm g, const Sched& S, const Epi& E) {
;     ...
;             const bool last = (t == nt - 2);
;             const char* a1 = cA + (size_t)(t + 1) * kstep;
;             const char* a2 = last ? nA : cA + (size_t)(t + 2) * kstep; const char* b2 = last ? nB : cB + (size_t)(t + 2) * kstep;
;             const char* a3 = a2 + kstep; const char* b3 = b2 + kstep;
;             if (last && has_next) S.a_ready(nxt, ui + 1);
;             if constexpr (SP2) {
;             PG8_LDB(B0, 0, 0); PG8_LDB(B1, 0, 1); PG8_SCHED; PG8_LDA(At, 0, 0); PG8_STAGE(PG8_SA(1, 1), a1 + hstep, voffA);
;             PG8_WAIT_V(8); PG8_WAIT_L(0); PG8_BAR; PG8_MMA(0, 0, At, B0); PG8_MMA(0, 1, At, B1); PG8_BAR; PG8_SCHED;
;             PG8_LDA(At, 0, 1); PG8_STAGE(PG8_SB(0, 0), b2, voffB); PG8_STAGE(PG8_SB(0, 1), b2 + hstep, voffB); PG8_STAGE(PG8_SA(0, 0), a2, voffA);
;             PG8_WAIT_V(8); PG8_WAIT_L(0); PG8_BAR; PG8_MMA(1, 0, At, B0); PG8_MMA(1, 1, At, B1); PG8_BAR; PG8_SCHED;
.LBB0_1219:
	s_add_u32 s26, s24, 0xfffc0080
	s_addc_u32 s27, s25, -1
	s_cmp_eq_u32 s54, 12
	s_cselect_b32 s29, s17, s27
	s_cselect_b32 s28, s50, s26
	s_cselect_b32 s27, s15, s53
	s_cselect_b32 s26, s51, s52
	s_add_i32 m0, s23, 0xc000
	s_nop 0
	global_load_lds_dwordx4 v136, s[24:25]
	s_add_i32 m0, s23, 0xe000
	s_nop 0
	global_load_lds_dwordx4 v138, s[24:25]
	ds_read_b128 v[152:155], v148
	ds_read_b128 v[156:159], v148 offset:1024
	ds_read_b128 v[160:163], v148 offset:2048
	ds_read_b128 v[164:167], v148 offset:3072
	ds_read_b128 v[168:171], v149
	ds_read_b128 v[172:175], v149 offset:1024
	ds_read_b128 v[176:179], v149 offset:2048
	ds_read_b128 v[180:183], v149 offset:3072
	ds_read_b128 v[184:187], v150
	ds_read_b128 v[188:191], v150 offset:1024
	ds_read_b128 v[192:195], v150 offset:2048
	ds_read_b128 v[196:199], v150 offset:3072
	ds_read_b128 v[200:203], v150 offset:4096
	ds_read_b128 v[204:207], v150 offset:5120
	ds_read_b128 v[208:211], v150 offset:6144
	ds_read_b128 v[212:215], v150 offset:7168
	s_waitcnt vmcnt(8)
	s_waitcnt lgkmcnt(0)
	s_setprio 1
	s_barrier
	v_mfma_f32_16x16x32_bf16 v[124:127], v[152:155], v[184:187], v[124:127]
	v_mfma_f32_16x16x32_bf16 v[120:123], v[160:163], v[184:187], v[120:123]
	v_mfma_f32_16x16x32_bf16 v[108:111], v[152:155], v[192:195], v[108:111]
	v_mfma_f32_16x16x32_bf16 v[104:107], v[160:163], v[192:195], v[104:107]
	v_mfma_f32_16x16x32_bf16 v[92:95], v[152:155], v[200:203], v[92:95]
	v_mfma_f32_16x16x32_bf16 v[88:91], v[160:163], v[200:203], v[88:91]
	v_mfma_f32_16x16x32_bf16 v[76:79], v[152:155], v[208:211], v[76:79]
	v_mfma_f32_16x16x32_bf16 v[72:75], v[160:163], v[208:211], v[72:75]
	v_mfma_f32_16x16x32_bf16 v[124:127], v[156:159], v[188:191], v[124:127]
	v_mfma_f32_16x16x32_bf16 v[120:123], v[164:167], v[188:191], v[120:123]
	v_mfma_f32_16x16x32_bf16 v[108:111], v[156:159], v[196:199], v[108:111]
	v_mfma_f32_16x16x32_bf16 v[104:107], v[164:167], v[196:199], v[104:107]
	v_mfma_f32_16x16x32_bf16 v[92:95], v[156:159], v[204:207], v[92:95]
	v_mfma_f32_16x16x32_bf16 v[88:91], v[164:167], v[204:207], v[88:91]
	v_mfma_f32_16x16x32_bf16 v[76:79], v[156:159], v[212:215], v[76:79]
	v_mfma_f32_16x16x32_bf16 v[72:75], v[164:167], v[212:215], v[72:75]
	v_mfma_f32_16x16x32_bf16 v[116:119], v[168:171], v[184:187], v[116:119]
	v_mfma_f32_16x16x32_bf16 v[112:115], v[176:179], v[184:187], v[112:115]
	v_mfma_f32_16x16x32_bf16 v[100:103], v[168:171], v[192:195], v[100:103]
	v_mfma_f32_16x16x32_bf16 v[96:99], v[176:179], v[192:195], v[96:99]
	v_mfma_f32_16x16x32_bf16 v[84:87], v[168:171], v[200:203], v[84:87]
	v_mfma_f32_16x16x32_bf16 v[80:83], v[176:179], v[200:203], v[80:83]
	v_mfma_f32_16x16x32_bf16 v[68:71], v[168:171], v[208:211], v[68:71]
	v_mfma_f32_16x16x32_bf16 v[64:67], v[176:179], v[208:211], v[64:67]
	v_mfma_f32_16x16x32_bf16 v[116:119], v[172:175], v[188:191], v[116:119]
	v_mfma_f32_16x16x32_bf16 v[112:115], v[180:183], v[188:191], v[112:115]
	v_mfma_f32_16x16x32_bf16 v[100:103], v[172:175], v[196:199], v[100:103]
	v_mfma_f32_16x16x32_bf16 v[96:99], v[180:183], v[196:199], v[96:99]
	v_mfma_f32_16x16x32_bf16 v[84:87], v[172:175], v[204:207], v[84:87]
	v_mfma_f32_16x16x32_bf16 v[80:83], v[180:183], v[204:207], v[80:83]
	v_mfma_f32_16x16x32_bf16 v[68:71], v[172:175], v[212:215], v[68:71]
	v_mfma_f32_16x16x32_bf16 v[64:67], v[180:183], v[212:215], v[64:67]
	s_barrier
	s_setprio 0
	s_add_i32 s55, s44, s33
	v_lshl_add_u64 v[216:217], s[26:27], 0, v[132:133]
	s_mov_b32 m0, s55
	s_nop 0
	global_load_lds_dwordx4 v[216:217], off
	s_add_i32 m0, s55, 0x2000
	s_add_u32 s56, s26, 0x40000
	v_lshl_add_u64 v[218:219], s[26:27], 0, v[128:129]
	s_addc_u32 s57, s27, 0
	s_add_i32 s55, s45, s33
	global_load_lds_dwordx4 v[218:219], off
	s_mov_b32 m0, s55
	v_lshl_add_u64 v[222:223], s[28:29], 0, v[130:131]
	global_load_lds_dwordx4 v132, s[56:57]
	s_add_i32 m0, s55, 0x2000
	s_nop 0
	global_load_lds_dwordx4 v128, s[56:57]
	v_lshl_add_u64 v[220:221], s[28:29], 0, v[134:135]
	s_mov_b32 m0, s23
	s_nop 0
	global_load_lds_dwordx4 v[220:221], off
	s_mov_b32 m0, s39
	s_nop 0
	global_load_lds_dwordx4 v[222:223], off
	ds_read_b128 v[184:187], v150 offset:16384
	ds_read_b128 v[188:191], v150 offset:17408
	ds_read_b128 v[192:195], v150 offset:18432
	ds_read_b128 v[196:199], v150 offset:19456
	ds_read_b128 v[200:203], v150 offset:20480
	ds_read_b128 v[204:207], v150 offset:21504
	ds_read_b128 v[208:211], v150 offset:22528
	ds_read_b128 v[212:215], v150 offset:23552
	s_waitcnt vmcnt(8)
	s_waitcnt lgkmcnt(0)
	s_setprio 1
	s_barrier
	v_mfma_f32_16x16x32_bf16 v[60:63], v[152:155], v[184:187], v[60:63]
	v_mfma_f32_16x16x32_bf16 v[56:59], v[160:163], v[184:187], v[56:59]
	v_mfma_f32_16x16x32_bf16 v[44:47], v[152:155], v[192:195], v[44:47]
	v_mfma_f32_16x16x32_bf16 v[40:43], v[160:163], v[192:195], v[40:43]
	v_mfma_f32_16x16x32_bf16 v[28:31], v[152:155], v[200:203], v[28:31]
	v_mfma_f32_16x16x32_bf16 v[24:27], v[160:163], v[200:203], v[24:27]
	v_mfma_f32_16x16x32_bf16 v[12:15], v[152:155], v[208:211], v[12:15]
	v_mfma_f32_16x16x32_bf16 v[8:11], v[160:163], v[208:211], v[8:11]
	v_mfma_f32_16x16x32_bf16 v[60:63], v[156:159], v[188:191], v[60:63]
	v_mfma_f32_16x16x32_bf16 v[56:59], v[164:167], v[188:191], v[56:59]
	v_mfma_f32_16x16x32_bf16 v[44:47], v[156:159], v[196:199], v[44:47]
	v_mfma_f32_16x16x32_bf16 v[40:43], v[164:167], v[196:199], v[40:43]
	v_mfma_f32_16x16x32_bf16 v[28:31], v[156:159], v[204:207], v[28:31]
	v_mfma_f32_16x16x32_bf16 v[24:27], v[164:167], v[204:207], v[24:27]
	v_mfma_f32_16x16x32_bf16 v[12:15], v[156:159], v[212:215], v[12:15]
	v_mfma_f32_16x16x32_bf16 v[8:11], v[164:167], v[212:215], v[8:11]
	v_mfma_f32_16x16x32_bf16 v[52:55], v[168:171], v[184:187], v[52:55]
	v_mfma_f32_16x16x32_bf16 v[48:51], v[176:179], v[184:187], v[48:51]
	v_mfma_f32_16x16x32_bf16 v[36:39], v[168:171], v[192:195], v[36:39]
	v_mfma_f32_16x16x32_bf16 v[32:35], v[176:179], v[192:195], v[32:35]
	v_mfma_f32_16x16x32_bf16 v[20:23], v[168:171], v[200:203], v[20:23]
	v_mfma_f32_16x16x32_bf16 v[16:19], v[176:179], v[200:203], v[16:19]
	v_mfma_f32_16x16x32_bf16 v[4:7], v[168:171], v[208:211], v[4:7]
	v_mfma_f32_16x16x32_bf16 v[0:3], v[176:179], v[208:211], v[0:3]
	v_mfma_f32_16x16x32_bf16 v[52:55], v[172:175], v[188:191], v[52:55]
	v_mfma_f32_16x16x32_bf16 v[48:51], v[180:183], v[188:191], v[48:51]
	v_mfma_f32_16x16x32_bf16 v[36:39], v[172:175], v[196:199], v[36:39]
	v_mfma_f32_16x16x32_bf16 v[32:35], v[180:183], v[196:199], v[32:35]
	v_mfma_f32_16x16x32_bf16 v[20:23], v[172:175], v[204:207], v[20:23]
	v_mfma_f32_16x16x32_bf16 v[16:19], v[180:183], v[204:207], v[16:19]
	v_mfma_f32_16x16x32_bf16 v[4:7], v[172:175], v[212:215], v[4:7]
	v_mfma_f32_16x16x32_bf16 v[0:3], v[180:183], v[212:215], v[0:3]
	s_barrier
; #define PG8_STAGE(bufoff, gbase, voff) do { _Pragma("unroll") for (int _i = 0; _i < 2; ++_i) \
;         __builtin_amdgcn_global_load_lds((const unsigned*)((const char*)(gbase) + (voff)[_i]), (PG8_LAS unsigned*)(lds + (bufoff) + ldsw + _i * 8192), 16, 0, 0); } while (0)
; #define PG8_LDA(dst, b, h) do { _Pragma("unroll") for (int m = 0; m < 4; ++m) _Pragma("unroll") for (int k = 0; k < 2; ++k) dst[m][k] = *(const PG8_LAS bf16x8*)(lds + PG8_SA(b, h) + aoff + m * 2048 + k * 1024); } while (0)
; #define PG8_LDB(dst, b, h) do { _Pragma("unroll") for (int n = 0; n < 2; ++n) _Pragma("unroll") for (int k = 0; k < 2; ++k) dst[n][k] = *(const PG8_LAS bf16x8*)(lds + PG8_SB(b, h) + boff + n * 2048 + k * 1024); } while (0)
; #define PG8_MMA(ai, bj, At, Bt) do { __builtin_amdgcn_s_setprio(1); _Pragma("unroll") for (int m = 0; m < 4; ++m) _Pragma("unroll") for (int n = 0; n < 2; ++n) _Pragma("unroll") for (int k = 0; k < 2; ++k) \
;         acc[ai][bj][m][n] = __builtin_amdgcn_mfma_f32_16x16x32_bf16(Bt[n][k], At[m][k], acc[ai][bj][m][n], 0, 0, 0); __builtin_amdgcn_s_setprio(0); } while (0)
; #define PG8_WAIT_V(n) asm volatile("s_waitcnt vmcnt(" #n ")" ::: "memory")
; #define PG8_WAIT_L(n) asm volatile("s_waitcnt lgkmcnt(" #n ")" ::: "memory")
; #define PG8_BAR __builtin_amdgcn_s_barrier()
; #define PG8_SCHED __builtin_amdgcn_sched_barrier(0)
; template <class Epi, class Sched, bool ALIGN_EPI = false, bool SP2 = false>
; __device__ __forceinline__ void gemm_phase(PG8_LAS unsigned char* lds, const Gemm g, const Sched& S, const Epi& E) {
;     ...
;             PG8_LDB(B0, 1, 0); PG8_LDB(B1, 1, 1); PG8_SCHED; PG8_LDA(At, 1, 0); PG8_STAGE(PG8_SA(0, 1), a2 + hstep, voffA);
;             PG8_WAIT_V(8); PG8_WAIT_L(0); PG8_BAR; PG8_MMA(0, 0, At, B0); PG8_MMA(0, 1, At, B1); PG8_BAR; PG8_SCHED;
;             PG8_LDA(At, 1, 1); PG8_STAGE(PG8_SB(1, 0), b3, voffB); PG8_STAGE(PG8_SB(1, 1), b3 + hstep, voffB); PG8_STAGE(PG8_SA(1, 0), a3, voffA);
;             PG8_WAIT_V(8); PG8_WAIT_L(0); PG8_BAR; PG8_MMA(1, 0, At, B0); PG8_MMA(1, 1, At, B1); PG8_BAR; PG8_SCHED;
;     ...
;         if constexpr (ALIGN_EPI) { if (wr == 0) PG8_BAR; }
	s_setprio 0
	s_add_i32 s55, 0, 0x18000
	v_add_u32_e32 v151, s55, v145
	s_add_i32 s56, 0, 0x1c000
	ds_read_b128 v[152:155], v151
	ds_read_b128 v[156:159], v151 offset:1024
	ds_read_b128 v[160:163], v151 offset:2048
	ds_read_b128 v[164:167], v151 offset:3072
	v_add_u32_e32 v151, s56, v145
	ds_read_b128 v[168:171], v151
	ds_read_b128 v[172:175], v151 offset:1024
	ds_read_b128 v[176:179], v151 offset:2048
	ds_read_b128 v[180:183], v151 offset:3072
	s_add_u32 s28, s28, 0x40000
	s_addc_u32 s29, s29, 0
	s_mov_b32 m0, s40
	ds_read_b128 v[184:187], v150 offset:32768
	ds_read_b128 v[188:191], v150 offset:33792
	ds_read_b128 v[192:195], v150 offset:34816
	ds_read_b128 v[196:199], v150 offset:35840
	ds_read_b128 v[200:203], v150 offset:36864
	ds_read_b128 v[204:207], v150 offset:37888
	ds_read_b128 v[208:211], v150 offset:38912
	ds_read_b128 v[212:215], v150 offset:39936
	global_load_lds_dwordx4 v134, s[28:29]
	s_mov_b32 m0, s41
	s_nop 0
	global_load_lds_dwordx4 v130, s[28:29]
	s_waitcnt vmcnt(8)
	s_waitcnt lgkmcnt(0)
	s_setprio 1
	s_barrier
	v_mfma_f32_16x16x32_bf16 v[124:127], v[152:155], v[184:187], v[124:127]
	v_mfma_f32_16x16x32_bf16 v[120:123], v[160:163], v[184:187], v[120:123]
	v_mfma_f32_16x16x32_bf16 v[108:111], v[152:155], v[192:195], v[108:111]
	v_mfma_f32_16x16x32_bf16 v[104:107], v[160:163], v[192:195], v[104:107]
	v_mfma_f32_16x16x32_bf16 v[92:95], v[152:155], v[200:203], v[92:95]
	v_mfma_f32_16x16x32_bf16 v[88:91], v[160:163], v[200:203], v[88:91]
	v_mfma_f32_16x16x32_bf16 v[76:79], v[152:155], v[208:211], v[76:79]
	v_mfma_f32_16x16x32_bf16 v[72:75], v[160:163], v[208:211], v[72:75]
	v_mfma_f32_16x16x32_bf16 v[124:127], v[156:159], v[188:191], v[124:127]
	v_mfma_f32_16x16x32_bf16 v[120:123], v[164:167], v[188:191], v[120:123]
	v_mfma_f32_16x16x32_bf16 v[108:111], v[156:159], v[196:199], v[108:111]
	v_mfma_f32_16x16x32_bf16 v[104:107], v[164:167], v[196:199], v[104:107]
	v_mfma_f32_16x16x32_bf16 v[92:95], v[156:159], v[204:207], v[92:95]
	v_mfma_f32_16x16x32_bf16 v[88:91], v[164:167], v[204:207], v[88:91]
	v_mfma_f32_16x16x32_bf16 v[76:79], v[156:159], v[212:215], v[76:79]
	v_mfma_f32_16x16x32_bf16 v[72:75], v[164:167], v[212:215], v[72:75]
	v_mfma_f32_16x16x32_bf16 v[116:119], v[168:171], v[184:187], v[116:119]
	v_mfma_f32_16x16x32_bf16 v[112:115], v[176:179], v[184:187], v[112:115]
	v_mfma_f32_16x16x32_bf16 v[100:103], v[168:171], v[192:195], v[100:103]
	v_mfma_f32_16x16x32_bf16 v[96:99], v[176:179], v[192:195], v[96:99]
	v_mfma_f32_16x16x32_bf16 v[84:87], v[168:171], v[200:203], v[84:87]
	v_mfma_f32_16x16x32_bf16 v[80:83], v[176:179], v[200:203], v[80:83]
	v_mfma_f32_16x16x32_bf16 v[68:71], v[168:171], v[208:211], v[68:71]
	v_mfma_f32_16x16x32_bf16 v[64:67], v[176:179], v[208:211], v[64:67]
	v_mfma_f32_16x16x32_bf16 v[116:119], v[172:175], v[188:191], v[116:119]
	v_mfma_f32_16x16x32_bf16 v[112:115], v[180:183], v[188:191], v[112:115]
	v_mfma_f32_16x16x32_bf16 v[100:103], v[172:175], v[196:199], v[100:103]
	v_mfma_f32_16x16x32_bf16 v[96:99], v[180:183], v[196:199], v[96:99]
	v_mfma_f32_16x16x32_bf16 v[84:87], v[172:175], v[204:207], v[84:87]
	v_mfma_f32_16x16x32_bf16 v[80:83], v[180:183], v[204:207], v[80:83]
	v_mfma_f32_16x16x32_bf16 v[68:71], v[172:175], v[212:215], v[68:71]
	v_mfma_f32_16x16x32_bf16 v[64:67], v[180:183], v[212:215], v[64:67]
	s_barrier
	s_setprio 0
	s_add_i32 s28, s55, s33
	v_lshl_add_u64 v[216:217], v[216:217], 0, s[10:11]
	s_mov_b32 m0, s28
	s_nop 0
	global_load_lds_dwordx4 v[216:217], off
	s_add_i32 m0, s28, 0x2000
	s_add_u32 s26, s26, 0x40080
	v_lshl_add_u64 v[216:217], v[218:219], 0, s[10:11]
	s_addc_u32 s27, s27, 0
	s_add_i32 s28, s56, s33
	global_load_lds_dwordx4 v[216:217], off
	s_mov_b32 m0, s28
	s_nop 0
	global_load_lds_dwordx4 v132, s[26:27]
	s_add_i32 m0, s28, 0x2000
	s_nop 0
	global_load_lds_dwordx4 v128, s[26:27]
	v_lshl_add_u64 v[216:217], v[220:221], 0, s[10:11]
	s_mov_b32 m0, s42
	s_nop 0
	global_load_lds_dwordx4 v[216:217], off
	v_lshl_add_u64 v[216:217], v[222:223], 0, s[10:11]
	s_mov_b32 m0, s43
	s_nop 0
	global_load_lds_dwordx4 v[216:217], off
	ds_read_b128 v[184:187], v150 offset:49152
	ds_read_b128 v[188:191], v150 offset:50176
	ds_read_b128 v[192:195], v150 offset:51200
	ds_read_b128 v[196:199], v150 offset:52224
	ds_read_b128 v[200:203], v150 offset:53248
	ds_read_b128 v[204:207], v150 offset:54272
	ds_read_b128 v[208:211], v150 offset:55296
	ds_read_b128 v[212:215], v150 offset:56320
	s_waitcnt vmcnt(8)
	s_waitcnt lgkmcnt(0)
	s_setprio 1
	s_barrier
	v_mfma_f32_16x16x32_bf16 v[60:63], v[152:155], v[184:187], v[60:63]
	v_mfma_f32_16x16x32_bf16 v[56:59], v[160:163], v[184:187], v[56:59]
	v_mfma_f32_16x16x32_bf16 v[44:47], v[152:155], v[192:195], v[44:47]
	v_mfma_f32_16x16x32_bf16 v[40:43], v[160:163], v[192:195], v[40:43]
	v_mfma_f32_16x16x32_bf16 v[28:31], v[152:155], v[200:203], v[28:31]
	v_mfma_f32_16x16x32_bf16 v[24:27], v[160:163], v[200:203], v[24:27]
	v_mfma_f32_16x16x32_bf16 v[12:15], v[152:155], v[208:211], v[12:15]
	v_mfma_f32_16x16x32_bf16 v[8:11], v[160:163], v[208:211], v[8:11]
	v_mfma_f32_16x16x32_bf16 v[60:63], v[156:159], v[188:191], v[60:63]
	v_mfma_f32_16x16x32_bf16 v[56:59], v[164:167], v[188:191], v[56:59]
	v_mfma_f32_16x16x32_bf16 v[44:47], v[156:159], v[196:199], v[44:47]
	v_mfma_f32_16x16x32_bf16 v[40:43], v[164:167], v[196:199], v[40:43]
	v_mfma_f32_16x16x32_bf16 v[28:31], v[156:159], v[204:207], v[28:31]
	v_mfma_f32_16x16x32_bf16 v[24:27], v[164:167], v[204:207], v[24:27]
	v_mfma_f32_16x16x32_bf16 v[12:15], v[156:159], v[212:215], v[12:15]
	v_mfma_f32_16x16x32_bf16 v[8:11], v[164:167], v[212:215], v[8:11]
	v_mfma_f32_16x16x32_bf16 v[52:55], v[168:171], v[184:187], v[52:55]
	v_mfma_f32_16x16x32_bf16 v[48:51], v[176:179], v[184:187], v[48:51]
	v_mfma_f32_16x16x32_bf16 v[36:39], v[168:171], v[192:195], v[36:39]
	v_mfma_f32_16x16x32_bf16 v[32:35], v[176:179], v[192:195], v[32:35]
	v_mfma_f32_16x16x32_bf16 v[20:23], v[168:171], v[200:203], v[20:23]
	v_mfma_f32_16x16x32_bf16 v[16:19], v[176:179], v[200:203], v[16:19]
	v_mfma_f32_16x16x32_bf16 v[4:7], v[168:171], v[208:211], v[4:7]
	v_mfma_f32_16x16x32_bf16 v[0:3], v[176:179], v[208:211], v[0:3]
	v_mfma_f32_16x16x32_bf16 v[52:55], v[172:175], v[188:191], v[52:55]
	v_mfma_f32_16x16x32_bf16 v[48:51], v[180:183], v[188:191], v[48:51]
	v_mfma_f32_16x16x32_bf16 v[36:39], v[172:175], v[196:199], v[36:39]
	v_mfma_f32_16x16x32_bf16 v[32:35], v[180:183], v[196:199], v[32:35]
	v_mfma_f32_16x16x32_bf16 v[20:23], v[172:175], v[204:207], v[20:23]
	v_mfma_f32_16x16x32_bf16 v[16:19], v[180:183], v[204:207], v[16:19]
	v_mfma_f32_16x16x32_bf16 v[4:7], v[172:175], v[212:215], v[4:7]
	v_mfma_f32_16x16x32_bf16 v[0:3], v[180:183], v[212:215], v[0:3]
	s_barrier
	s_setprio 0
	s_add_i32 s54, s54, 2
	s_add_u32 s24, s24, 0x100
	s_addc_u32 s25, s25, 0
	s_add_u32 s52, s52, 0x100
	s_addc_u32 s53, s53, 0
	s_cmp_gt_u32 s54, 13
	s_cbranch_scc0 .LBB0_1219
	s_and_b64 vcc, exec, s[12:13]
	s_cbranch_vccz .LBB0_1222
	s_barrier
